# norm loops prefetch next row; gate sigmoid computed under the Y image loads; ffup conv weights loaded before the image barrier; cache_conv items kept off the XCD-7 workgroups too
# speedup vs baseline: 1.0688x; 1.0067x over previous
; DI int TID512() { int t = threadIdx.x; asm volatile("" : "+v"(t)); return t; }
; DI void norm_phase(const Params& p, int l, int mode, int B, int G, char* smem) {
;   const int tid = TID512(), lane = tid & 63, wid = tid >> 6;
;   const float* gamma = mode == 0 ? p.in[8] + (size_t)l * 1024 : (mode == 1 ? p.in[28] + (size_t)l * 1024 : p.in[34]);
;   float* wga = (float*)smem;
;   if (mode == 0) {
;     __syncthreads();
;     const float* src = p.in[9] + (size_t)l * 1024 * PW + 3072;
; #pragma unroll
;     for (int i = 0; i < 8; ++i) {
;       const int id = tid + i * 512, k = id >> 2, part = id & 3;
;       ((float4*)wga)[(((k >> 8) * 4 + (k & 3)) * 4 + part) * 64 + ((k >> 2) & 63)] = *(const float4*)(src + (size_t)k * PW + part * 4);
;     }
;     __syncthreads();
;   }
;   float4 g[4];
; #pragma unroll
;   for (int i = 0; i < 4; ++i) g[i] = *(const float4*)(gamma + i * 256 + lane * 4);
;   for (int row = B * 8 + wid; row < MT; row += G * 8) {
.LBB0_76:
	s_mov_b32 s7, s21
	s_lshl_b64 s[4:5], s[6:7], 12
	v_writelane_b32 v254, s4, 37
	v_mov_b32_e32 v1, v184
	s_waitcnt lgkmcnt(0)
	v_writelane_b32 v254, s5, 38
	s_mul_hi_u32 s5, s6, 0x1010000
	v_writelane_b32 v254, s6, 39
	s_mul_i32 s4, s6, 0x1010000
	s_add_u32 s4, s54, s4
	v_writelane_b32 v254, s7, 40
	v_and_b32_e32 v0, 3, v1
	v_writelane_b32 v254, s40, 41
	s_addc_u32 s5, s55, s5
	v_lshlrev_b32_e32 v172, 4, v0
	v_lshl_add_u64 v[4:5], s[4:5], 0, v[172:173]
	s_mov_b64 s[4:5], 0x3000
	v_add_u32_e32 v36, 0x200, v1
	v_add_u32_e32 v38, 0x400, v1
	v_add_u32_e32 v40, 0x600, v1
	v_lshl_add_u64 v[32:33], v[4:5], 0, s[4:5]
	v_ashrrev_i32_e32 v2, 2, v1
	s_movk_i32 s6, 0x4040
	v_ashrrev_i32_e32 v37, 2, v36
	v_ashrrev_i32_e32 v39, 2, v38
	v_ashrrev_i32_e32 v41, 2, v40
	v_mad_i64_i32 v[4:5], s[4:5], v2, s6, v[32:33]
	v_mad_i64_i32 v[8:9], s[4:5], v37, s6, v[32:33]
	v_mad_i64_i32 v[12:13], s[4:5], v39, s6, v[32:33]
	v_mad_i64_i32 v[16:17], s[4:5], v41, s6, v[32:33]
	s_barrier
	global_load_dwordx4 v[4:7], v[4:5], off
	s_nop 0
	global_load_dwordx4 v[8:11], v[8:9], off
	s_nop 0
	global_load_dwordx4 v[12:15], v[12:13], off
	s_nop 0
	global_load_dwordx4 v[16:19], v[16:17], off
	v_add_u32_e32 v42, 0x800, v1
	v_ashrrev_i32_e32 v43, 2, v42
	v_mad_i64_i32 v[20:21], s[4:5], v43, s6, v[32:33]
	global_load_dwordx4 v[20:23], v[20:21], off
	v_add_u32_e32 v44, 0xa00, v1
	v_ashrrev_i32_e32 v45, 2, v44
	v_mad_i64_i32 v[24:25], s[4:5], v45, s6, v[32:33]
	global_load_dwordx4 v[24:27], v[24:25], off
	v_add_u32_e32 v46, 0xc00, v1
	v_ashrrev_i32_e32 v47, 2, v46
	v_mad_i64_i32 v[28:29], s[4:5], v47, s6, v[32:33]
	global_load_dwordx4 v[28:31], v[28:29], off
	v_add_u32_e32 v48, 0xe00, v1
	v_ashrrev_i32_e32 v49, 2, v48
	v_mad_i64_i32 v[32:33], s[4:5], v49, s6, v[32:33]
	global_load_dwordx4 v[32:35], v[32:33], off
	v_and_b32_e32 v51, 0xffffc00, v1
	v_lshlrev_b32_e32 v2, 12, v2
	v_lshlrev_b32_e32 v51, 4, v51
	v_and_b32_e32 v53, 0xffffc00, v36
	v_and_b32_e32 v38, 0xffffc00, v38
	v_and_b32_e32 v54, 0xffffc00, v40
	v_and_b32_e32 v2, 0x3000, v2
	v_lshlrev_b32_e32 v37, 12, v37
	v_lshlrev_b32_e32 v39, 12, v39
	v_lshlrev_b32_e32 v41, 12, v41
	v_and_b32_e32 v52, 0x3f0, v1
	v_lshlrev_b32_e32 v0, 10, v0
	v_lshlrev_b32_e32 v53, 4, v53
	v_lshlrev_b32_e32 v38, 4, v38
	v_lshlrev_b32_e32 v54, 4, v54
	v_add3_u32 v2, 16, v51, v2
	v_and_b32_e32 v37, 0x3000, v37
	v_and_b32_e32 v39, 0x3000, v39
	v_and_b32_e32 v41, 0x3000, v41
	v_and_b32_e32 v36, 0x3f0, v36
	v_and_b32_e32 v40, 0x3f0, v40
	v_add3_u32 v2, v2, v0, v52
	v_add3_u32 v37, 16, v53, v37
	v_add3_u32 v38, 16, v38, v39
	v_add3_u32 v39, 16, v54, v41
	v_and_b32_e32 v42, 0xffffc00, v42
	v_add3_u32 v36, v37, v0, v36
	v_add3_u32 v37, v38, v0, v52
	v_add3_u32 v38, v39, v0, v40
	v_writelane_b32 v254, s41, 42
	v_writelane_b32 v254, s42, 43
	s_waitcnt vmcnt(7)
	ds_write_b128 v2, v[4:7]
	s_waitcnt vmcnt(6)
	ds_write_b128 v36, v[8:11]
	s_waitcnt vmcnt(5)
	ds_write_b128 v37, v[12:15]
	s_waitcnt vmcnt(4)
	ds_write_b128 v38, v[16:19]
	v_lshlrev_b32_e32 v4, 12, v43
	v_lshlrev_b32_e32 v2, 4, v42
	v_and_b32_e32 v4, 0x3000, v4
	v_add3_u32 v2, 16, v2, v4
	v_add3_u32 v2, v2, v0, v52
	s_waitcnt vmcnt(3)
	ds_write_b128 v2, v[20:23]
	v_and_b32_e32 v2, 0xffffc00, v44
	v_lshlrev_b32_e32 v4, 12, v45
	v_writelane_b32 v254, s43, 44
	v_lshlrev_b32_e32 v2, 4, v2
	v_and_b32_e32 v4, 0x3000, v4
	v_writelane_b32 v254, s44, 45
	v_add3_u32 v2, 16, v2, v4
	v_and_b32_e32 v4, 0x3f0, v44
	v_writelane_b32 v254, s45, 46
	v_add3_u32 v2, v2, v0, v4
	v_writelane_b32 v254, s46, 47
	s_waitcnt vmcnt(2)
	ds_write_b128 v2, v[24:27]
	v_and_b32_e32 v2, 0xffffc00, v46
	v_lshlrev_b32_e32 v4, 12, v47
	v_writelane_b32 v254, s47, 48
	v_lshlrev_b32_e32 v2, 4, v2
	v_and_b32_e32 v4, 0x3000, v4
	v_writelane_b32 v254, s48, 49
	v_add3_u32 v2, 16, v2, v4
	v_writelane_b32 v254, s49, 50
	v_add3_u32 v2, v2, v0, v52
	v_writelane_b32 v254, s50, 51
	s_waitcnt vmcnt(1)
	ds_write_b128 v2, v[28:31]
	v_and_b32_e32 v2, 0xffffc00, v48
	v_lshlrev_b32_e32 v4, 12, v49
	v_writelane_b32 v254, s51, 52
	v_lshlrev_b32_e32 v2, 4, v2
	v_and_b32_e32 v4, 0x3000, v4
	v_writelane_b32 v254, s52, 53
	v_add3_u32 v2, 16, v2, v4
	v_and_b32_e32 v4, 0x3f0, v48
	v_writelane_b32 v254, s53, 54
	v_ashrrev_i32_e32 v50, 6, v1
	v_add3_u32 v0, v2, v0, v4
	v_readlane_b32 s4, v253, 47
	v_writelane_b32 v254, s54, 55
	s_waitcnt vmcnt(0)
	ds_write_b128 v0, v[32:35]
	v_add_u32_e32 v0, s4, v50
	s_mov_b32 s4, 0x8200
	s_mov_b32 s24, 0x81ff
	v_writelane_b32 v254, s55, 56
	v_readlane_b32 s5, v253, 48
	v_cmp_gt_i32_e32 vcc, s4, v0
	s_waitcnt lgkmcnt(0)
	s_barrier
; DI void norm_phase(const Params& p, int l, int mode, int B, int G, char* smem) {
;     ...
;   float4 g[4];
; #pragma unroll
;   for (int i = 0; i < 4; ++i) g[i] = *(const float4*)(gamma + i * 256 + lane * 4);
;   for (int row = B * 8 + wid; row < MT; row += G * 8) {
;     float* X = p.out + (size_t)row * 1024;
;     const float* Xr = (mode == 0 && l == 0 && row < MP) ? p.in[0] + (size_t)row * 1024 : X;
;     float4 v[4];
;     float ss = 0.f;
; #pragma unroll
;     for (int i = 0; i < 4; ++i) { { const f32x4 t4 = __builtin_nontemporal_load((const f32x4*)(Xr + i * 256 + lane * 4)); v[i] = float4{t4[0], t4[1], t4[2], t4[3]}; } ss += v[i].x * v[i].x + v[i].y * v[i].y + v[i].z * v[i].z + v[i].w * v[i].w; }
	s_and_saveexec_b64 s[4:5], vcc
	s_cbranch_execz .LBB0_81
	v_readlane_b32 s36, v254, 41
	v_readlane_b32 s48, v254, 53
	v_readlane_b32 s6, v254, 37
	v_and_b32_e32 v20, 63, v1
	v_readlane_b32 s49, v254, 54
	v_readlane_b32 s7, v254, 38
	s_add_u32 s6, s48, s6
	s_addc_u32 s7, s49, s7
	v_lshlrev_b32_e32 v24, 4, v20
	s_nop 1
	global_load_dwordx4 v[4:7], v24, s[6:7]
	global_load_dwordx4 v[8:11], v24, s[6:7] offset:1024
	global_load_dwordx4 v[12:15], v24, s[6:7] offset:2048
	global_load_dwordx4 v[16:19], v24, s[6:7] offset:3072
	v_xor_b32_e32 v1, 32, v190
	v_cmp_lt_i32_e32 vcc, v1, v191
	v_readlane_b32 s38, v254, 43
	v_readlane_b32 s39, v254, 44
	v_cndmask_b32_e32 v1, v190, v1, vcc
	v_lshlrev_b32_e32 v2, 2, v1
	v_xor_b32_e32 v1, 16, v190
	v_cmp_lt_i32_e32 vcc, v1, v191
	v_readlane_b32 s40, v254, 45
	v_readlane_b32 s41, v254, 46
	v_cndmask_b32_e32 v1, v190, v1, vcc
	v_cmp_lt_i32_e32 vcc, v195, v191
	v_lshlrev_b32_e32 v40, 2, v1
	v_readlane_b32 s42, v254, 47
	v_cndmask_b32_e32 v1, v190, v195, vcc
	v_cmp_lt_i32_e32 vcc, v194, v191
	v_lshlrev_b32_e32 v41, 2, v1
	v_readlane_b32 s43, v254, 48
	v_cndmask_b32_e32 v1, v190, v194, vcc
	v_cmp_lt_i32_e32 vcc, v193, v191
	v_lshlrev_b32_e32 v42, 2, v1
	v_readlane_b32 s44, v254, 49
	v_cndmask_b32_e32 v1, v190, v193, vcc
	v_cmp_lt_i32_e32 vcc, v192, v191
	v_lshlrev_b32_e32 v43, 2, v1
	v_readlane_b32 s45, v254, 50
	v_cndmask_b32_e32 v1, v190, v192, vcc
	v_readlane_b32 s46, v254, 51
	v_readlane_b32 s47, v254, 52
	v_readlane_b32 s50, v254, 55
	v_readlane_b32 s51, v254, 56
	v_lshlrev_b32_e32 v44, 2, v1
	v_ashrrev_i32_e32 v1, 31, v0
	v_lshlrev_b32_e32 v172, 2, v20
	v_cmp_gt_u32_e32 vcc, 16, v20
	v_cmp_eq_u32_e64 s[38:39], 15, v20
	v_cmp_eq_u32_e64 s[40:41], 14, v20
	v_cmp_eq_u32_e64 s[42:43], 13, v20
	v_cmp_eq_u32_e64 s[44:45], 12, v20
	v_cmp_eq_u32_e64 s[46:47], 11, v20
	v_cmp_eq_u32_e64 s[48:49], 10, v20
	v_cmp_eq_u32_e64 s[50:51], 9, v20
	v_cmp_eq_u32_e64 s[52:53], 8, v20
	v_cmp_eq_u32_e64 s[54:55], 7, v20
	v_cmp_eq_u32_e64 s[56:57], 6, v20
	v_cmp_eq_u32_e64 s[58:59], 5, v20
	v_cmp_eq_u32_e64 s[60:61], 4, v20
	v_cmp_eq_u32_e64 s[62:63], 3, v20
	v_cmp_eq_u32_e64 s[64:65], 2, v20
	v_cmp_eq_u32_e64 s[66:67], 1, v20
	v_cmp_eq_u32_e64 s[68:69], 0, v20
	v_lshlrev_b32_e32 v20, 3, v20
	v_mov_b32_e32 v21, v173
	s_movk_i32 s8, 0x880
	v_lshlrev_b64 v[22:23], 12, v[0:1]
	v_readlane_b32 s6, v254, 39
	v_add_u32_e32 v45, 16, v24
	v_mad_i64_i32 v[20:21], s[8:9], v0, s8, v[20:21]
	v_or_b32_e32 v22, v22, v24
	v_lshlrev_b64 v[24:25], 6, v[0:1]
	v_readlane_b32 s7, v254, 40
	s_cmp_eq_u32 s6, 0
	v_lshl_add_u64 v[24:25], v[24:25], 0, v[172:173]
	s_mov_b64 s[8:9], 0x1ee54100
	s_cselect_b64 s[6:7], -1, 0
	v_lshl_add_u64 v[24:25], v[24:25], 0, s[8:9]
	s_mov_b64 s[8:9], 0
	v_readlane_b32 s37, v254, 42
	v_mov_b32_e32 v120, v0
	v_mov_b32_e32 v122, v22
	v_mov_b32_e32 v123, v23
	v_cmp_gt_i32_e64 s[72:73], s28, v120
	v_readlane_b32 s10, v253, 63
	v_readlane_b32 s11, v254, 0
	s_and_b64 s[72:73], s[6:7], s[72:73]
	v_mov_b32_e32 v121, s93
	v_mov_b32_e32 v124, s11
	v_cndmask_b32_e64 v125, v121, v124, s[72:73]
	v_mov_b32_e32 v121, s92
	v_mov_b32_e32 v124, s10
	v_cndmask_b32_e64 v124, v121, v124, s[72:73]
	v_lshl_add_u64 v[124:125], v[124:125], 0, v[122:123]
	global_load_dwordx4 v[104:107], v[124:125], off nt
	global_load_dwordx4 v[108:111], v[124:125], off offset:1024 nt
	global_load_dwordx4 v[112:115], v[124:125], off offset:2048 nt
	global_load_dwordx4 v[116:119], v[124:125], off offset:3072 nt
	s_branch .LBB0_79

; DI unsigned pack2(float a, float b) { f32v2_t v = {a, b}; bf16v2_t r = __builtin_convertvector(v, bf16v2_t); return __builtin_bit_cast(unsigned, r); }
; DI void norm_phase(const Params& p, int l, int mode, int B, int G, char* smem) {
;     ...
;   for (int row = B * 8 + wid; row < MT; row += G * 8) {
;     float* X = p.out + (size_t)row * 1024;
;     const float* Xr = (mode == 0 && l == 0 && row < MP) ? p.in[0] + (size_t)row * 1024 : X;
;     float4 v[4];
;     float ss = 0.f;
; #pragma unroll
;     for (int i = 0; i < 4; ++i) { { const f32x4 t4 = __builtin_nontemporal_load((const f32x4*)(Xr + i * 256 + lane * 4)); v[i] = float4{t4[0], t4[1], t4[2], t4[3]}; } ss += v[i].x * v[i].x + v[i].y * v[i].y + v[i].z * v[i].z + v[i].w * v[i].w; }
;     ss = wave_sum(ss);
;     const float rs = rsqrtf(ss * (1.f / 1024.f) + EPS);
;     u16* XN = (u16*)(p.ws + O_XN) + (size_t)row * LDK;
; #pragma unroll
;     for (int i = 0; i < 4; ++i) {
;       v[i] = float4{v[i].x * rs * g[i].x, v[i].y * rs * g[i].y, v[i].z * rs * g[i].z, v[i].w * rs * g[i].w};
;       if (mode == 2) *(float4*)(X + i * 256 + lane * 4) = v[i];
;       else *(uint2*)(XN + i * 256 + lane * 4) = uint2{pack2(v[i].x, v[i].y), pack2(v[i].z, v[i].w)};
.LBB0_79:
	s_waitcnt vmcnt(0)
	v_mov_b32_e32 v26, v104
	v_mov_b32_e32 v27, v105
	v_mov_b32_e32 v28, v106
	v_mov_b32_e32 v29, v107
	v_mov_b32_e32 v30, v108
	v_mov_b32_e32 v31, v109
	v_mov_b32_e32 v32, v110
	v_mov_b32_e32 v33, v111
	v_mov_b32_e32 v34, v112
	v_mov_b32_e32 v35, v113
	v_mov_b32_e32 v36, v114
	v_mov_b32_e32 v37, v115
	v_mov_b32_e32 v46, v116
	v_mov_b32_e32 v47, v117
	v_mov_b32_e32 v48, v118
	v_mov_b32_e32 v49, v119
	v_readlane_b32 s20, v254, 31
	v_readlane_b32 s10, v254, 33
	v_readlane_b32 s11, v254, 34
	v_add_u32_e32 v120, s20, v0
	s_nop 0
	v_lshl_add_u64 v[122:123], v[22:23], 0, s[10:11]
	v_cmp_ge_i32_e64 s[34:35], s24, v120
	s_nop 1
	v_cndmask_b32_e64 v120, v0, v120, s[34:35]
	v_cndmask_b32_e64 v122, v22, v122, s[34:35]
	v_cndmask_b32_e64 v123, v23, v123, s[34:35]
	v_cmp_gt_i32_e64 s[72:73], s28, v120
	v_readlane_b32 s10, v253, 63
	v_readlane_b32 s11, v254, 0
	s_and_b64 s[72:73], s[6:7], s[72:73]
	v_mov_b32_e32 v121, s93
	v_mov_b32_e32 v124, s11
	v_cndmask_b32_e64 v125, v121, v124, s[72:73]
	v_mov_b32_e32 v121, s92
	v_mov_b32_e32 v124, s10
	v_cndmask_b32_e64 v124, v121, v124, s[72:73]
	v_lshl_add_u64 v[124:125], v[124:125], 0, v[122:123]
	global_load_dwordx4 v[104:107], v[124:125], off nt
	global_load_dwordx4 v[108:111], v[124:125], off offset:1024 nt
	global_load_dwordx4 v[112:115], v[124:125], off offset:2048 nt
	global_load_dwordx4 v[116:119], v[124:125], off offset:3072 nt
	s_waitcnt lgkmcnt(2)
	s_mov_b32 s10, 0xa544000
	v_mov_b32_e32 v50, v27
	v_mov_b32_e32 v51, v31
	v_mov_b32_e32 v38, v26
	v_mov_b32_e32 v39, v30
	v_mov_b32_e32 v58, v35
	v_mov_b32_e32 v59, v47
	v_pk_mul_f32 v[50:51], v[50:51], v[50:51]
	v_mov_b32_e32 v52, v28
	v_mov_b32_e32 v53, v32
	v_mov_b32_e32 v56, v34
	v_mov_b32_e32 v57, v46
	v_pk_mul_f32 v[58:59], v[58:59], v[58:59]
	v_pk_fma_f32 v[38:39], v[38:39], v[38:39], v[50:51]
	v_mov_b32_e32 v54, v29
	v_mov_b32_e32 v55, v33
	s_waitcnt lgkmcnt(1)
	v_mov_b32_e32 v60, v36
	v_mov_b32_e32 v61, v48
	v_pk_fma_f32 v[50:51], v[56:57], v[56:57], v[58:59]
	v_pk_fma_f32 v[38:39], v[52:53], v[52:53], v[38:39]
	s_waitcnt lgkmcnt(0)
	v_mov_b32_e32 v62, v37
	v_mov_b32_e32 v63, v49
	v_pk_fma_f32 v[50:51], v[60:61], v[60:61], v[50:51]
	v_pk_fma_f32 v[38:39], v[54:55], v[54:55], v[38:39]
	v_pk_fma_f32 v[50:51], v[62:63], v[62:63], v[50:51]
	v_add_f32_e32 v1, v38, v39
	v_add_f32_e32 v1, v1, v50
	v_add_f32_e32 v1, v1, v51
	ds_bpermute_b32 v38, v2, v1
	s_waitcnt lgkmcnt(0)
	v_add_f32_e32 v1, v1, v38
	ds_bpermute_b32 v38, v40, v1
	s_waitcnt lgkmcnt(0)
	v_add_f32_e32 v1, v1, v38
	ds_bpermute_b32 v38, v41, v1
	s_waitcnt lgkmcnt(0)
	v_add_f32_e32 v1, v1, v38
	ds_bpermute_b32 v38, v42, v1
	s_waitcnt lgkmcnt(0)
	v_add_f32_e32 v1, v1, v38
	ds_bpermute_b32 v38, v43, v1
	s_waitcnt lgkmcnt(0)
	v_add_f32_e32 v1, v1, v38
	ds_bpermute_b32 v50, v44, v1
	v_lshl_add_u64 v[38:39], s[94:95], 0, v[20:21]
	s_waitcnt lgkmcnt(0)
	v_add_f32_e32 v1, v1, v50
	v_fmamk_f32 v1, v1, 0x3a800000, v186
	v_mul_f32_e32 v50, 0x4b800000, v1
	v_cmp_gt_f32_e64 s[72:73], s1, v1
	s_nop 1
	v_cndmask_b32_e64 v1, v1, v50, s[72:73]
	v_rsq_f32_e32 v1, v1
	v_add_co_u32_e64 v50, s[74:75], s10, v38
	v_mul_f32_e32 v38, 0x45800000, v1
	v_cndmask_b32_e64 v38, v1, v38, s[72:73]
	v_pk_mul_f32 v[26:27], v[26:27], v[38:39] op_sel_hi:[1,0]
	v_pk_mul_f32 v[28:29], v[28:29], v[38:39] op_sel_hi:[1,0]
	v_addc_co_u32_e64 v51, s[74:75], 0, v39, s[74:75]
	v_pk_mul_f32 v[30:31], v[30:31], v[38:39] op_sel_hi:[1,0]
	v_pk_mul_f32 v[32:33], v[32:33], v[38:39] op_sel_hi:[1,0]
	v_pk_mul_f32 v[52:53], v[34:35], v[38:39] op_sel_hi:[1,0]
	v_pk_mul_f32 v[54:55], v[36:37], v[38:39] op_sel_hi:[1,0]
	v_pk_mul_f32 v[46:47], v[46:47], v[38:39] op_sel_hi:[1,0]
	v_pk_mul_f32 v[48:49], v[48:49], v[38:39] op_sel_hi:[1,0]
	v_pk_mul_f32 v[102:103], v[4:5], v[26:27]
	v_pk_mul_f32 v[38:39], v[6:7], v[28:29]
	v_pk_mul_f32 v[36:37], v[8:9], v[30:31]
	v_pk_mul_f32 v[34:35], v[10:11], v[32:33]
	v_pk_mul_f32 v[32:33], v[12:13], v[52:53]
	v_pk_mul_f32 v[30:31], v[14:15], v[54:55]
	v_pk_mul_f32 v[28:29], v[16:17], v[46:47]
	v_pk_mul_f32 v[26:27], v[18:19], v[48:49]
	v_cvt_pk_bf16_f32 v46, v102, v103
	v_cvt_pk_bf16_f32 v47, v38, v39
	v_cvt_pk_bf16_f32 v48, v36, v37
	v_cvt_pk_bf16_f32 v49, v34, v35
	v_cvt_pk_bf16_f32 v52, v32, v33
	v_cvt_pk_bf16_f32 v53, v30, v31
	v_cvt_pk_bf16_f32 v54, v28, v29
	v_cvt_pk_bf16_f32 v55, v26, v27
	global_store_dwordx2 v[50:51], v[46:47], off offset:256
	global_store_dwordx2 v[50:51], v[48:49], off offset:768
	global_store_dwordx2 v[50:51], v[52:53], off offset:1280
	global_store_dwordx2 v[50:51], v[54:55], off offset:1792
	ds_read_b128 v[46:49], v45
	ds_read_b128 v[50:53], v45 offset:1024
	ds_read_b128 v[62:65], v45 offset:2048
	ds_read_b128 v[66:69], v45 offset:3072
	ds_read_b128 v[70:73], v45 offset:4096
	ds_read_b128 v[74:77], v45 offset:5120
	ds_read_b128 v[78:81], v45 offset:6144
	ds_read_b128 v[82:85], v45 offset:7168
	ds_read_b128 v[86:89], v45 offset:8192
	ds_read_b128 v[90:93], v45 offset:9216
	ds_read_b128 v[94:97], v45 offset:10240
	ds_read_b128 v[98:101], v45 offset:11264
	s_waitcnt lgkmcnt(11)
	v_fma_f32 v60, v46, v102, 0
	v_fma_f32 v59, v47, v102, 0
	v_fma_f32 v58, v48, v102, 0
	v_fma_f32 v57, v49, v102, 0
	s_waitcnt lgkmcnt(10)
	v_fma_f32 v56, v50, v102, 0
	v_fma_f32 v55, v51, v102, 0
	v_fma_f32 v54, v52, v102, 0
	s_waitcnt lgkmcnt(9)
	v_fma_f32 v52, v102, v62, 0
	v_fma_f32 v51, v102, v63, 0
	v_fma_f32 v50, v102, v64, 0
	v_fma_f32 v49, v102, v65, 0
	s_waitcnt lgkmcnt(8)
	v_fma_f32 v48, v102, v66, 0
	v_fma_f32 v47, v102, v67, 0
	v_fma_f32 v46, v102, v68, 0
	v_fma_f32 v1, v102, v69, 0
	ds_read_b128 v[62:65], v45 offset:12288
	ds_read_b128 v[66:69], v45 offset:13312
	v_fma_f32 v53, v53, v102, 0
	s_waitcnt lgkmcnt(9)
; DI void norm_phase(const Params& p, int l, int mode, int B, int G, char* smem) {
;     ...
;       for (int i = 0; i < 4; ++i) {
;         const float xv[4] = {v[i].x, v[i].y, v[i].z, v[i].w};
; #pragma unroll
;         for (int e = 0; e < 4; ++e) {
;           asm volatile("" ::: "memory");
; #pragma unroll
;           for (int q = 0; q < 4; ++q) {
;             const float4 w = ((const float4*)wga)[((i * 4 + e) * 4 + q) * 64 + lane];
;             ga[q * 4 + 0] += xv[e] * w.x; ga[q * 4 + 1] += xv[e] * w.y; ga[q * 4 + 2] += xv[e] * w.z; ga[q * 4 + 3] += xv[e] * w.w;
;           }
;         }
;       }
	v_fmac_f32_e32 v60, v103, v70
	v_fmac_f32_e32 v59, v103, v71
	v_fmac_f32_e32 v58, v103, v72
	v_fmac_f32_e32 v57, v103, v73
	s_waitcnt lgkmcnt(8)
	v_fmac_f32_e32 v56, v103, v74
	v_fmac_f32_e32 v55, v103, v75
	v_fmac_f32_e32 v54, v103, v76
	v_fmac_f32_e32 v53, v103, v77
	s_waitcnt lgkmcnt(5)
	v_fmac_f32_e32 v60, v38, v86
	v_fmac_f32_e32 v59, v38, v87
	v_fmac_f32_e32 v58, v38, v88
	v_fmac_f32_e32 v57, v38, v89
	s_waitcnt lgkmcnt(4)
	v_fmac_f32_e32 v56, v38, v90
	v_fmac_f32_e32 v55, v38, v91
	v_fmac_f32_e32 v54, v38, v92
	v_fmac_f32_e32 v53, v38, v93
	s_waitcnt lgkmcnt(1)
	v_fmac_f32_e32 v60, v39, v62
	v_fmac_f32_e32 v59, v39, v63
	v_fmac_f32_e32 v58, v39, v64
	v_fmac_f32_e32 v57, v39, v65
	s_waitcnt lgkmcnt(0)
	v_fmac_f32_e32 v56, v39, v66
	ds_read_b128 v[62:65], v45 offset:14336
	v_fmac_f32_e32 v55, v39, v67
	v_fmac_f32_e32 v54, v39, v68
	v_fmac_f32_e32 v53, v39, v69
	ds_read_b128 v[66:69], v45 offset:15360
	v_fmac_f32_e32 v52, v103, v78
	v_fmac_f32_e32 v51, v103, v79
	v_fmac_f32_e32 v50, v103, v80
	v_fmac_f32_e32 v49, v103, v81
	v_fmac_f32_e32 v48, v103, v82
	v_fmac_f32_e32 v47, v103, v83
	v_fmac_f32_e32 v46, v103, v84
	v_fmac_f32_e32 v1, v103, v85
	v_fmac_f32_e32 v52, v38, v94
	v_fmac_f32_e32 v51, v38, v95
	v_fmac_f32_e32 v50, v38, v96
	v_fmac_f32_e32 v49, v38, v97
	v_fmac_f32_e32 v48, v38, v98
	v_fmac_f32_e32 v47, v38, v99
	v_fmac_f32_e32 v46, v38, v100
	v_fmac_f32_e32 v1, v38, v101
	s_waitcnt lgkmcnt(1)
	v_fmac_f32_e32 v52, v39, v62
	v_fmac_f32_e32 v51, v39, v63
	v_fmac_f32_e32 v50, v39, v64
	v_fmac_f32_e32 v49, v39, v65
	s_waitcnt lgkmcnt(0)
	v_fmac_f32_e32 v48, v39, v66
	ds_read_b128 v[62:65], v45 offset:16384
	v_fmac_f32_e32 v47, v39, v67
	v_fmac_f32_e32 v46, v39, v68
	v_fmac_f32_e32 v1, v39, v69
	ds_read_b128 v[66:69], v45 offset:17408
	s_waitcnt lgkmcnt(1)
	v_fmac_f32_e32 v60, v36, v62
	v_fmac_f32_e32 v59, v36, v63
	v_fmac_f32_e32 v58, v36, v64
	v_fmac_f32_e32 v57, v36, v65
	s_waitcnt lgkmcnt(0)
	v_fmac_f32_e32 v56, v36, v66
	ds_read_b128 v[62:65], v45 offset:18432
	v_fmac_f32_e32 v55, v36, v67
	v_fmac_f32_e32 v54, v36, v68
	v_fmac_f32_e32 v53, v36, v69
	ds_read_b128 v[66:69], v45 offset:19456
	s_waitcnt lgkmcnt(1)
	v_fmac_f32_e32 v52, v36, v62
	v_fmac_f32_e32 v51, v36, v63
	v_fmac_f32_e32 v50, v36, v64
	v_fmac_f32_e32 v49, v36, v65
	s_waitcnt lgkmcnt(0)
	v_fmac_f32_e32 v48, v36, v66
	ds_read_b128 v[62:65], v45 offset:20480
	v_fmac_f32_e32 v47, v36, v67
	v_fmac_f32_e32 v46, v36, v68
	v_fmac_f32_e32 v1, v36, v69
	ds_read_b128 v[66:69], v45 offset:21504
	s_waitcnt lgkmcnt(1)
	v_fmac_f32_e32 v60, v37, v62
	v_fmac_f32_e32 v59, v37, v63
	v_fmac_f32_e32 v58, v37, v64
	v_fmac_f32_e32 v57, v37, v65
	s_waitcnt lgkmcnt(0)
	v_fmac_f32_e32 v56, v37, v66
	ds_read_b128 v[62:65], v45 offset:22528
	v_fmac_f32_e32 v55, v37, v67
	v_fmac_f32_e32 v54, v37, v68
	v_fmac_f32_e32 v53, v37, v69
	ds_read_b128 v[66:69], v45 offset:23552
	s_waitcnt lgkmcnt(1)
	v_fmac_f32_e32 v52, v37, v62
	v_fmac_f32_e32 v51, v37, v63
	v_fmac_f32_e32 v50, v37, v64
	v_fmac_f32_e32 v49, v37, v65
	s_waitcnt lgkmcnt(0)
	v_fmac_f32_e32 v48, v37, v66
	ds_read_b128 v[62:65], v45 offset:24576
	v_fmac_f32_e32 v47, v37, v67
	v_fmac_f32_e32 v46, v37, v68
	v_fmac_f32_e32 v1, v37, v69
	ds_read_b128 v[36:39], v45 offset:25600
	s_waitcnt lgkmcnt(1)
	v_fmac_f32_e32 v60, v34, v62
	v_fmac_f32_e32 v59, v34, v63
	v_fmac_f32_e32 v58, v34, v64
	v_fmac_f32_e32 v57, v34, v65
	s_waitcnt lgkmcnt(0)
	v_fmac_f32_e32 v56, v34, v36
	ds_read_b128 v[62:65], v45 offset:26624
	v_fmac_f32_e32 v55, v34, v37
	v_fmac_f32_e32 v54, v34, v38
	v_fmac_f32_e32 v53, v34, v39
	ds_read_b128 v[36:39], v45 offset:27648
	s_waitcnt lgkmcnt(1)
	v_fmac_f32_e32 v52, v34, v62
	v_fmac_f32_e32 v51, v34, v63
	v_fmac_f32_e32 v50, v34, v64
	v_fmac_f32_e32 v49, v34, v65
	s_waitcnt lgkmcnt(0)
	v_fmac_f32_e32 v48, v34, v36
	ds_read_b128 v[62:65], v45 offset:28672
	v_fmac_f32_e32 v47, v34, v37
	v_fmac_f32_e32 v46, v34, v38
	v_fmac_f32_e32 v1, v34, v39
	ds_read_b128 v[36:39], v45 offset:29696
	s_waitcnt lgkmcnt(1)
	v_fmac_f32_e32 v60, v35, v62
	v_fmac_f32_e32 v59, v35, v63
	v_fmac_f32_e32 v58, v35, v64
	v_fmac_f32_e32 v57, v35, v65
	s_waitcnt lgkmcnt(0)
	v_fmac_f32_e32 v56, v35, v36
	ds_read_b128 v[62:65], v45 offset:30720
	v_fmac_f32_e32 v55, v35, v37
	v_fmac_f32_e32 v54, v35, v38
	v_fmac_f32_e32 v53, v35, v39
	ds_read_b128 v[36:39], v45 offset:31744
	s_waitcnt lgkmcnt(1)
	v_fmac_f32_e32 v52, v35, v62
	v_fmac_f32_e32 v51, v35, v63
	v_fmac_f32_e32 v50, v35, v64
	v_fmac_f32_e32 v49, v35, v65
	s_waitcnt lgkmcnt(0)
	v_fmac_f32_e32 v48, v35, v36
	ds_read_b128 v[62:65], v45 offset:32768
	v_fmac_f32_e32 v47, v35, v37
	v_fmac_f32_e32 v46, v35, v38
	v_fmac_f32_e32 v1, v35, v39
	ds_read_b128 v[34:37], v45 offset:33792
	s_waitcnt lgkmcnt(1)
	v_fmac_f32_e32 v60, v32, v62
	v_fmac_f32_e32 v59, v32, v63
	v_fmac_f32_e32 v58, v32, v64
	v_fmac_f32_e32 v57, v32, v65
	s_waitcnt lgkmcnt(0)
	v_fmac_f32_e32 v56, v32, v34
	ds_read_b128 v[62:65], v45 offset:34816
	v_fmac_f32_e32 v55, v32, v35
	v_fmac_f32_e32 v54, v32, v36
	v_fmac_f32_e32 v53, v32, v37
	ds_read_b128 v[34:37], v45 offset:35840
	s_waitcnt lgkmcnt(1)
	v_fmac_f32_e32 v52, v32, v62
	v_fmac_f32_e32 v51, v32, v63
	v_fmac_f32_e32 v50, v32, v64
	v_fmac_f32_e32 v49, v32, v65
	s_waitcnt lgkmcnt(0)
	v_fmac_f32_e32 v48, v32, v34
	ds_read_b128 v[62:65], v45 offset:36864
	v_fmac_f32_e32 v47, v32, v35
	v_fmac_f32_e32 v46, v32, v36
	v_fmac_f32_e32 v1, v32, v37
	ds_read_b128 v[34:37], v45 offset:37888
	s_waitcnt lgkmcnt(1)
	v_fmac_f32_e32 v60, v33, v62
	v_fmac_f32_e32 v59, v33, v63
	v_fmac_f32_e32 v58, v33, v64
	v_fmac_f32_e32 v57, v33, v65
	s_waitcnt lgkmcnt(0)
; DI void norm_phase(const Params& p, int l, int mode, int B, int G, char* smem) {
;     ...
;       for (int i = 0; i < 4; ++i) {
;         const float xv[4] = {v[i].x, v[i].y, v[i].z, v[i].w};
; #pragma unroll
;         for (int e = 0; e < 4; ++e) {
;           asm volatile("" ::: "memory");
; #pragma unroll
;           for (int q = 0; q < 4; ++q) {
;             const float4 w = ((const float4*)wga)[((i * 4 + e) * 4 + q) * 64 + lane];
;             ga[q * 4 + 0] += xv[e] * w.x; ga[q * 4 + 1] += xv[e] * w.y; ga[q * 4 + 2] += xv[e] * w.z; ga[q * 4 + 3] += xv[e] * w.w;
;           }
;         }
;       }
;       float mine = 0.f;
; #pragma unroll
;       for (int r = 0; r < 16; ++r) { const float s = wave_sum(ga[r]); if (lane == r) mine = s; }
	v_fmac_f32_e32 v56, v33, v34
	ds_read_b128 v[62:65], v45 offset:38912
	v_fmac_f32_e32 v55, v33, v35
	v_fmac_f32_e32 v54, v33, v36
	v_fmac_f32_e32 v53, v33, v37
	ds_read_b128 v[34:37], v45 offset:39936
	s_waitcnt lgkmcnt(1)
	v_fmac_f32_e32 v52, v33, v62
	v_fmac_f32_e32 v51, v33, v63
	v_fmac_f32_e32 v50, v33, v64
	v_fmac_f32_e32 v49, v33, v65
	s_waitcnt lgkmcnt(0)
	v_fmac_f32_e32 v48, v33, v34
	ds_read_b128 v[62:65], v45 offset:40960
	v_fmac_f32_e32 v47, v33, v35
	v_fmac_f32_e32 v46, v33, v36
	v_fmac_f32_e32 v1, v33, v37
	ds_read_b128 v[32:35], v45 offset:41984
	ds_read_b128 v[36:39], v45 offset:43008
	s_waitcnt lgkmcnt(2)
	v_fmac_f32_e32 v60, v30, v62
	v_fmac_f32_e32 v59, v30, v63
	v_fmac_f32_e32 v58, v30, v64
	s_waitcnt lgkmcnt(1)
	v_fmac_f32_e32 v56, v30, v32
	v_fmac_f32_e32 v55, v30, v33
	v_fmac_f32_e32 v54, v30, v34
	v_fmac_f32_e32 v53, v30, v35
	ds_read_b128 v[32:35], v45 offset:44032
	s_waitcnt lgkmcnt(1)
	v_fmac_f32_e32 v52, v30, v36
	v_fmac_f32_e32 v51, v30, v37
	v_fmac_f32_e32 v50, v30, v38
	v_fmac_f32_e32 v49, v30, v39
	ds_read_b128 v[36:39], v45 offset:45056
	v_fmac_f32_e32 v57, v30, v65
	s_waitcnt lgkmcnt(1)
	v_fmac_f32_e32 v48, v30, v32
	v_fmac_f32_e32 v47, v30, v33
	v_fmac_f32_e32 v46, v30, v34
	v_fmac_f32_e32 v1, v30, v35
	ds_read_b128 v[32:35], v45 offset:46080
	s_waitcnt lgkmcnt(1)
	v_fmac_f32_e32 v60, v31, v36
	v_fmac_f32_e32 v59, v31, v37
	v_fmac_f32_e32 v58, v31, v38
	v_fmac_f32_e32 v57, v31, v39
	ds_read_b128 v[36:39], v45 offset:47104
	s_waitcnt lgkmcnt(1)
	v_fmac_f32_e32 v56, v31, v32
	v_fmac_f32_e32 v55, v31, v33
	v_fmac_f32_e32 v54, v31, v34
	v_fmac_f32_e32 v53, v31, v35
	ds_read_b128 v[32:35], v45 offset:48128
	s_waitcnt lgkmcnt(1)
	v_fmac_f32_e32 v52, v31, v36
	v_fmac_f32_e32 v51, v31, v37
	v_fmac_f32_e32 v50, v31, v38
	v_fmac_f32_e32 v49, v31, v39
	ds_read_b128 v[36:39], v45 offset:49152
	s_waitcnt lgkmcnt(1)
	v_fmac_f32_e32 v48, v31, v32
	v_fmac_f32_e32 v47, v31, v33
	v_fmac_f32_e32 v46, v31, v34
	v_fmac_f32_e32 v1, v31, v35
	ds_read_b128 v[30:33], v45 offset:50176
	s_waitcnt lgkmcnt(1)
	v_fmac_f32_e32 v60, v28, v36
	v_fmac_f32_e32 v59, v28, v37
	ds_read_b128 v[34:37], v45 offset:51200
	v_fmac_f32_e32 v58, v28, v38
	s_waitcnt lgkmcnt(1)
	v_fmac_f32_e32 v56, v28, v30
	v_fmac_f32_e32 v55, v28, v31
	v_fmac_f32_e32 v54, v28, v32
	v_fmac_f32_e32 v53, v28, v33
	ds_read_b128 v[30:33], v45 offset:52224
	s_waitcnt lgkmcnt(1)
	v_fmac_f32_e32 v52, v28, v34
	v_fmac_f32_e32 v51, v28, v35
	v_fmac_f32_e32 v50, v28, v36
	v_fmac_f32_e32 v49, v28, v37
	ds_read_b128 v[34:37], v45 offset:53248
	v_fmac_f32_e32 v57, v28, v39
	s_waitcnt lgkmcnt(1)
	v_fmac_f32_e32 v48, v28, v30
	v_fmac_f32_e32 v47, v28, v31
	v_fmac_f32_e32 v46, v28, v32
	v_fmac_f32_e32 v1, v28, v33
	ds_read_b128 v[30:33], v45 offset:54272
	s_waitcnt lgkmcnt(1)
	v_fmac_f32_e32 v60, v29, v34
	v_fmac_f32_e32 v59, v29, v35
	v_fmac_f32_e32 v58, v29, v36
	v_fmac_f32_e32 v57, v29, v37
	ds_read_b128 v[34:37], v45 offset:55296
	s_waitcnt lgkmcnt(1)
	v_fmac_f32_e32 v56, v29, v30
	v_fmac_f32_e32 v55, v29, v31
	v_fmac_f32_e32 v54, v29, v32
	v_fmac_f32_e32 v53, v29, v33
	ds_read_b128 v[30:33], v45 offset:56320
	s_waitcnt lgkmcnt(1)
	v_fmac_f32_e32 v52, v29, v34
	v_fmac_f32_e32 v51, v29, v35
	v_fmac_f32_e32 v50, v29, v36
	v_fmac_f32_e32 v49, v29, v37
	ds_read_b128 v[34:37], v45 offset:57344
	s_waitcnt lgkmcnt(1)
	v_fmac_f32_e32 v48, v29, v30
	v_fmac_f32_e32 v47, v29, v31
	v_fmac_f32_e32 v46, v29, v32
	v_fmac_f32_e32 v1, v29, v33
	ds_read_b128 v[28:31], v45 offset:58368
	s_waitcnt lgkmcnt(1)
	v_fmac_f32_e32 v60, v26, v34
	v_fmac_f32_e32 v59, v26, v35
	ds_read_b128 v[32:35], v45 offset:59392
	v_fmac_f32_e32 v58, v26, v36
	s_waitcnt lgkmcnt(1)
	v_fmac_f32_e32 v56, v26, v28
	v_fmac_f32_e32 v55, v26, v29
	v_fmac_f32_e32 v54, v26, v30
	v_fmac_f32_e32 v53, v26, v31
	ds_read_b128 v[28:31], v45 offset:60416
	s_waitcnt lgkmcnt(1)
	v_fmac_f32_e32 v52, v26, v32
	v_fmac_f32_e32 v51, v26, v33
	v_fmac_f32_e32 v50, v26, v34
	v_fmac_f32_e32 v49, v26, v35
	ds_read_b128 v[32:35], v45 offset:61440
	s_waitcnt lgkmcnt(1)
	v_fmac_f32_e32 v48, v26, v28
	v_fmac_f32_e32 v47, v26, v29
	v_fmac_f32_e32 v46, v26, v30
	v_fmac_f32_e32 v1, v26, v31
	ds_read_b128 v[28:31], v45 offset:62464
	s_waitcnt lgkmcnt(1)
	v_fmac_f32_e32 v60, v27, v32
	v_fmac_f32_e32 v57, v26, v37
	ds_bpermute_b32 v26, v2, v60
	v_fmac_f32_e32 v59, v27, v33
	v_fmac_f32_e32 v58, v27, v34
	v_fmac_f32_e32 v57, v27, v35
	ds_read_b128 v[32:35], v45 offset:63488
	s_waitcnt lgkmcnt(1)
	v_add_f32_e32 v26, v60, v26
	v_fmac_f32_e32 v56, v27, v28
	v_fmac_f32_e32 v55, v27, v29
	v_fmac_f32_e32 v54, v27, v30
	v_fmac_f32_e32 v53, v27, v31
	ds_read_b128 v[28:31], v45 offset:64512
	s_waitcnt lgkmcnt(1)
	v_fmac_f32_e32 v52, v27, v32
	ds_bpermute_b32 v32, v40, v26
	v_fmac_f32_e32 v51, v27, v33
	ds_bpermute_b32 v33, v2, v59
	s_waitcnt lgkmcnt(2)
	v_fmac_f32_e32 v48, v27, v28
	v_fmac_f32_e32 v47, v27, v29
	s_waitcnt lgkmcnt(1)
	v_add_f32_e32 v26, v26, v32
	ds_bpermute_b32 v28, v41, v26
	s_waitcnt lgkmcnt(1)
	v_add_f32_e32 v32, v59, v33
	ds_bpermute_b32 v33, v40, v32
	v_fmac_f32_e32 v50, v27, v34
	v_fmac_f32_e32 v49, v27, v35
	s_waitcnt lgkmcnt(1)
	v_add_f32_e32 v26, v26, v28
	ds_bpermute_b32 v28, v42, v26
	s_waitcnt lgkmcnt(1)
	v_add_f32_e32 v29, v32, v33
	v_fmac_f32_e32 v46, v27, v30
	ds_bpermute_b32 v30, v41, v29
	v_fmac_f32_e32 v1, v27, v31
	ds_bpermute_b32 v27, v2, v58
	s_waitcnt lgkmcnt(2)
	v_add_f32_e32 v26, v26, v28
	ds_bpermute_b32 v28, v43, v26
	s_waitcnt lgkmcnt(2)
	v_add_f32_e32 v29, v29, v30
	ds_bpermute_b32 v30, v42, v29
	s_waitcnt lgkmcnt(2)
	v_add_f32_e32 v27, v58, v27
	ds_bpermute_b32 v31, v40, v27
	s_waitcnt lgkmcnt(2)
; DI void norm_phase(const Params& p, int l, int mode, int B, int G, char* smem) {
;     ...
;       for (int r = 0; r < 16; ++r) { const float s = wave_sum(ga[r]); if (lane == r) mine = s; }
;       if (lane < 16) ((float*)(p.ws + O_GA))[(size_t)row * 16 + lane] = mine;
	v_add_f32_e32 v26, v26, v28
	ds_bpermute_b32 v28, v2, v57
	s_waitcnt lgkmcnt(2)
	v_add_f32_e32 v29, v29, v30
	ds_bpermute_b32 v30, v43, v29
	s_waitcnt lgkmcnt(2)
	v_add_f32_e32 v31, v27, v31
	ds_bpermute_b32 v32, v41, v31
	s_waitcnt lgkmcnt(2)
	v_add_f32_e32 v33, v57, v28
	ds_bpermute_b32 v34, v40, v33
	s_waitcnt lgkmcnt(2)
	v_add_f32_e32 v28, v29, v30
	ds_bpermute_b32 v38, v2, v54
	s_waitcnt lgkmcnt(2)
	v_add_f32_e32 v30, v31, v32
	ds_bpermute_b32 v31, v42, v30
	s_waitcnt lgkmcnt(2)
	v_add_f32_e32 v32, v33, v34
	ds_bpermute_b32 v34, v2, v56
	s_waitcnt lgkmcnt(2)
	v_add_f32_e32 v38, v54, v38
	ds_bpermute_b32 v39, v40, v38
	s_waitcnt lgkmcnt(2)
	v_add_f32_e32 v30, v30, v31
	ds_bpermute_b32 v31, v43, v30
	s_waitcnt lgkmcnt(2)
	v_add_f32_e32 v34, v56, v34
	ds_bpermute_b32 v35, v40, v34
	s_waitcnt lgkmcnt(2)
	v_add_f32_e32 v38, v38, v39
	ds_bpermute_b32 v39, v41, v38
	s_waitcnt lgkmcnt(2)
	v_add_f32_e32 v30, v30, v31
	ds_bpermute_b32 v31, v2, v55
	s_waitcnt lgkmcnt(2)
	v_add_f32_e32 v34, v34, v35
	ds_bpermute_b32 v35, v41, v34
	s_waitcnt lgkmcnt(2)
	v_add_f32_e32 v38, v38, v39
	ds_bpermute_b32 v39, v42, v38
	s_waitcnt lgkmcnt(2)
	v_add_f32_e32 v36, v55, v31
	ds_bpermute_b32 v55, v2, v52
	s_waitcnt lgkmcnt(2)
	v_add_f32_e32 v34, v34, v35
	ds_bpermute_b32 v35, v42, v34
	s_waitcnt lgkmcnt(2)
	v_add_f32_e32 v38, v38, v39
	ds_bpermute_b32 v39, v43, v38
	s_waitcnt lgkmcnt(2)
	v_add_f32_e32 v52, v52, v55
	ds_bpermute_b32 v55, v40, v52
	s_waitcnt lgkmcnt(2)
	v_add_f32_e32 v34, v34, v35
	ds_bpermute_b32 v35, v43, v34
	s_waitcnt lgkmcnt(2)
	v_add_f32_e32 v38, v38, v39
	ds_bpermute_b32 v39, v2, v51
	s_waitcnt lgkmcnt(2)
	v_add_f32_e32 v52, v52, v55
	ds_bpermute_b32 v55, v41, v52
	s_waitcnt lgkmcnt(2)
	v_add_f32_e32 v34, v34, v35
	ds_bpermute_b32 v35, v2, v53
	s_waitcnt lgkmcnt(2)
	v_add_f32_e32 v56, v51, v39
	ds_bpermute_b32 v57, v40, v56
	ds_bpermute_b32 v62, v2, v1
	ds_bpermute_b32 v37, v40, v36
	s_waitcnt lgkmcnt(3)
	v_add_f32_e32 v53, v53, v35
	ds_bpermute_b32 v54, v40, v53
	ds_bpermute_b32 v33, v41, v32
	s_waitcnt lgkmcnt(3)
	v_add_f32_e32 v1, v1, v62
	ds_bpermute_b32 v62, v40, v1
	s_waitcnt lgkmcnt(3)
	v_add_f32_e32 v36, v36, v37
	s_waitcnt lgkmcnt(2)
	v_add_f32_e32 v53, v53, v54
	ds_bpermute_b32 v54, v41, v53
	ds_bpermute_b32 v37, v41, v36
	s_waitcnt lgkmcnt(2)
	v_add_f32_e32 v1, v1, v62
	ds_bpermute_b32 v62, v41, v1
	v_add_f32_e32 v32, v32, v33
	s_waitcnt lgkmcnt(2)
	v_add_f32_e32 v53, v53, v54
	ds_bpermute_b32 v54, v42, v53
	s_waitcnt lgkmcnt(2)
	v_add_f32_e32 v36, v36, v37
	s_waitcnt lgkmcnt(1)
	v_add_f32_e32 v1, v1, v62
	ds_bpermute_b32 v33, v42, v32
	ds_bpermute_b32 v37, v42, v36
	s_waitcnt lgkmcnt(2)
	v_add_f32_e32 v53, v53, v54
	ds_bpermute_b32 v54, v43, v53
	ds_bpermute_b32 v62, v42, v1
	s_waitcnt lgkmcnt(3)
	v_add_f32_e32 v32, v32, v33
	s_waitcnt lgkmcnt(2)
	v_add_f32_e32 v36, v36, v37
	ds_bpermute_b32 v33, v43, v32
	s_waitcnt lgkmcnt(2)
	v_add_f32_e32 v51, v53, v54
	v_add_f32_e32 v53, v52, v55
	v_add_f32_e32 v55, v56, v57
	ds_bpermute_b32 v54, v42, v53
	ds_bpermute_b32 v56, v41, v55
	ds_bpermute_b32 v57, v2, v50
	s_waitcnt lgkmcnt(4)
	v_add_f32_e32 v62, v1, v62
	ds_bpermute_b32 v37, v43, v36
	s_waitcnt lgkmcnt(3)
	v_add_f32_e32 v53, v53, v54
	s_waitcnt lgkmcnt(2)
	v_add_f32_e32 v55, v55, v56
	s_waitcnt lgkmcnt(1)
	v_add_f32_e32 v57, v50, v57
	ds_bpermute_b32 v54, v43, v53
	ds_bpermute_b32 v56, v42, v55
	ds_bpermute_b32 v58, v40, v57
	ds_bpermute_b32 v64, v43, v62
	v_add_f32_e32 v32, v32, v33
	s_waitcnt lgkmcnt(3)
	v_add_f32_e32 v50, v53, v54
	s_waitcnt lgkmcnt(2)
	v_add_f32_e32 v54, v55, v56
	s_waitcnt lgkmcnt(1)
	v_add_f32_e32 v56, v57, v58
	ds_bpermute_b32 v55, v2, v49
	ds_bpermute_b32 v57, v41, v56
	ds_bpermute_b32 v58, v2, v48
	ds_bpermute_b32 v59, v43, v54
	v_add_f32_e32 v36, v36, v37
	s_waitcnt lgkmcnt(3)
	v_add_f32_e32 v49, v49, v55
	s_waitcnt lgkmcnt(2)
	v_add_f32_e32 v56, v56, v57
	s_waitcnt lgkmcnt(1)
	v_add_f32_e32 v57, v48, v58
	ds_bpermute_b32 v55, v40, v49
	ds_bpermute_b32 v58, v40, v57
	s_waitcnt lgkmcnt(2)
	v_add_f32_e32 v48, v54, v59
	ds_bpermute_b32 v60, v42, v56
	ds_bpermute_b32 v27, v44, v26
	s_waitcnt lgkmcnt(3)
	v_add_f32_e32 v49, v49, v55
	s_waitcnt lgkmcnt(2)
	v_add_f32_e32 v54, v57, v58
	ds_bpermute_b32 v55, v41, v49
	ds_bpermute_b32 v57, v41, v54
	s_waitcnt lgkmcnt(3)
	v_add_f32_e32 v56, v56, v60
	ds_bpermute_b32 v59, v43, v56
	ds_bpermute_b32 v29, v44, v28
	s_waitcnt lgkmcnt(3)
	v_add_f32_e32 v55, v49, v55
	s_waitcnt lgkmcnt(2)
	v_add_f32_e32 v57, v54, v57
	ds_bpermute_b32 v58, v42, v55
	ds_bpermute_b32 v60, v42, v57
	s_waitcnt lgkmcnt(3)
	v_add_f32_e32 v54, v56, v59
	ds_bpermute_b32 v31, v44, v30
	ds_bpermute_b32 v33, v44, v32
	s_waitcnt lgkmcnt(3)
	v_add_f32_e32 v58, v55, v58
	s_waitcnt lgkmcnt(2)
	v_add_f32_e32 v59, v57, v60
	ds_bpermute_b32 v61, v43, v58
	ds_bpermute_b32 v60, v43, v59
	ds_bpermute_b32 v35, v44, v34
	ds_bpermute_b32 v37, v44, v36
	ds_bpermute_b32 v39, v44, v38
	s_waitcnt lgkmcnt(4)
	v_add_f32_e32 v56, v58, v61
	ds_bpermute_b32 v61, v2, v47
	s_waitcnt lgkmcnt(4)
	v_add_f32_e32 v58, v59, v60
	ds_bpermute_b32 v60, v2, v46
	ds_bpermute_b32 v52, v44, v51
	ds_bpermute_b32 v53, v44, v50
	s_waitcnt lgkmcnt(3)
	v_add_f32_e32 v47, v47, v61
	ds_bpermute_b32 v61, v40, v47
	s_waitcnt lgkmcnt(3)
	v_add_f32_e32 v46, v46, v60
	ds_bpermute_b32 v60, v40, v46
	ds_bpermute_b32 v49, v44, v48
	ds_bpermute_b32 v55, v44, v54
	s_waitcnt lgkmcnt(3)
	v_add_f32_e32 v47, v47, v61
	ds_bpermute_b32 v61, v41, v47
	s_waitcnt lgkmcnt(3)
	v_add_f32_e32 v46, v46, v60
	ds_bpermute_b32 v60, v41, v46
	ds_bpermute_b32 v57, v44, v56
	ds_bpermute_b32 v59, v44, v58
	s_waitcnt lgkmcnt(3)
	v_add_f32_e32 v47, v47, v61
	ds_bpermute_b32 v61, v42, v47
	s_waitcnt lgkmcnt(3)
	v_add_f32_e32 v46, v46, v60
	ds_bpermute_b32 v60, v42, v46
	s_waitcnt lgkmcnt(1)
	v_add_f32_e32 v47, v47, v61
	ds_bpermute_b32 v61, v43, v47
	s_waitcnt lgkmcnt(1)
	v_add_f32_e32 v60, v46, v60
	ds_bpermute_b32 v63, v43, v60
	s_waitcnt lgkmcnt(1)
	v_add_f32_e32 v1, v47, v61
	v_add_f32_e32 v61, v62, v64
	s_waitcnt lgkmcnt(0)
	v_add_f32_e32 v47, v60, v63
	ds_bpermute_b32 v46, v44, v1
	ds_bpermute_b32 v60, v44, v47
	ds_bpermute_b32 v62, v44, v61
	s_and_saveexec_b64 s[12:13], vcc
	s_cbranch_execz .LBB0_78
; DI void norm_phase(const Params& p, int l, int mode, int B, int G, char* smem) {
;     ...
;       for (int r = 0; r < 16; ++r) { const float s = wave_sum(ga[r]); if (lane == r) mine = s; }
;       if (lane < 16) ((float*)(p.ws + O_GA))[(size_t)row * 16 + lane] = mine;
	v_add_f32_e32 v26, v26, v27
	v_add_f32_e32 v28, v28, v29
	v_cndmask_b32_e64 v26, 0, v26, s[68:69]
	v_add_f32_e32 v30, v30, v31
	v_cndmask_b32_e64 v26, v26, v28, s[66:67]
	v_add_f32_e32 v32, v32, v33
	v_cndmask_b32_e64 v26, v26, v30, s[64:65]
	v_add_f32_e32 v34, v34, v35
	v_cndmask_b32_e64 v26, v26, v32, s[62:63]
	v_add_f32_e32 v36, v36, v37
	v_cndmask_b32_e64 v26, v26, v34, s[60:61]
	v_add_f32_e32 v38, v38, v39
	v_cndmask_b32_e64 v26, v26, v36, s[58:59]
	v_add_f32_e32 v48, v48, v49
	v_add_f32_e32 v49, v50, v53
	v_add_f32_e32 v50, v51, v52
	v_cndmask_b32_e64 v26, v26, v38, s[56:57]
	v_cndmask_b32_e64 v26, v26, v50, s[54:55]
	v_cndmask_b32_e64 v26, v26, v49, s[52:53]
	v_add_f32_e32 v54, v54, v55
	v_cndmask_b32_e64 v26, v26, v48, s[50:51]
	v_add_f32_e32 v56, v56, v57
	v_cndmask_b32_e64 v26, v26, v54, s[48:49]
	s_waitcnt lgkmcnt(2)
	v_add_f32_e32 v1, v1, v46
	v_add_f32_e32 v46, v58, v59
	v_cndmask_b32_e64 v26, v26, v56, s[46:47]
	v_cndmask_b32_e64 v26, v26, v46, s[44:45]
	s_waitcnt lgkmcnt(1)
	v_add_f32_e32 v47, v47, v60
	v_cndmask_b32_e64 v1, v26, v1, s[42:43]
	s_waitcnt lgkmcnt(0)
	v_add_f32_e32 v61, v61, v62
	v_cndmask_b32_e64 v1, v1, v47, s[40:41]
	v_cndmask_b32_e64 v1, v1, v61, s[38:39]
	v_lshl_add_u64 v[26:27], s[94:95], 0, v[24:25]
	global_store_dword v[26:27], v1, off
	s_branch .LBB0_78

; DI int TID() { int t = threadIdx.x & 255; asm volatile("" : "+v"(t)); return t; }
; DI unsigned pack2(float a, float b) { f32v2_t v = {a, b}; bf16v2_t r = __builtin_convertvector(v, bf16v2_t); return __builtin_bit_cast(unsigned, r); }
; #define VB() (2 * B + (TID512() >> 8))
; #define HS() (smem + (TID512() >> 8) * HALF_LDS)
; DI void cache_conv_item(const Params& p, int l, int it, char* smem) {
;   const int tid = TID();
;   if (it < PB_KC) {
;     const float* src = p.in[2] + (size_t)l * SBT * PAST * 512;
;     u16* KS = (u16*)(p.ws + O_KS);
; #pragma unroll
;     for (int i = 0; i < 4; ++i) {
;       size_t e = (size_t)it * 4096 + (size_t)(tid + i * 256) * 4;
;       const f32x4 vv = __builtin_nontemporal_load((const f32x4*)(src + e));
;       const float4 v = {vv[0], vv[1], vv[2], vv[3]};
;       size_t b = e / ((size_t)PAST * 512), r = e % ((size_t)PAST * 512);
;       *(uint2*)(KS + b * SKP * 512 + r) = uint2{pack2(v.x, v.y), pack2(v.z, v.w)};
;     }
;     return;
; __global__ void __launch_bounds__(512, 2) mega(Params p) {
;     ...
;     if (ONLY < 0 || ONLY == 2) { int mt, nt; for (int k = 0; xcd_tile(B, G, k, 130, 16, mt, nt); ++k) projin_tile(p, l, mt, nt, smem); for (int it = VB(); it < PB_KC + PB_VC; it += vG) cache_conv_item(p, l, it, HS()); }
.Lmy_cc_entry:
	v_readlane_b32 s4, v251, 5
	s_lshr_b32 s5, s4, 4
	s_bfe_u32 s6, s4, 0x30001
	s_min_u32 s7, s5, 16
	s_lshl_b32 s7, s7, 1
	s_min_u32 s8, s6, 2
	s_cmp_lt_u32 s5, 16
	s_cselect_b32 s8, s8, 0
	s_cselect_b32 s9, 1, 0
	s_add_i32 s7, s7, s8
	s_cmp_lt_u32 s6, 2
	s_cselect_b32 s8, s9, 0
	s_add_i32 s7, s7, s5
	s_cmp_eq_u32 s6, 7
	s_cselect_b32 s8, 1, s8
	s_lshl_b32 s7, s7, 1
	s_sub_i32 s4, s4, s7
	s_mul_i32 s5, s60, 0x180
	s_add_i32 s62, s4, s5
	s_add_i32 s63, s62, 0x480
	s_cmp_eq_u32 s61, 0
	s_cselect_b32 s63, 0x2000, s63
	s_min_i32 s63, s63, 0x2000
	s_cmp_lg_u32 s8, 0
	s_cselect_b32 s63, 0, s63
	v_mov_b32_e32 v0, v184
	v_ashrrev_i32_e32 v0, 8, v0
	v_add_u32_e32 v2, s62, v0
	v_cmp_gt_i32_e32 vcc, s63, v2
	s_and_saveexec_b64 s[4:5], vcc
	s_cbranch_execz .LBB0_1259
	v_readlane_b32 s44, v254, 41
	v_readlane_b32 s45, v254, 42
	v_readlane_b32 s46, v254, 43
	v_readlane_b32 s47, v254, 44
	v_lshlrev_b32_e32 v10, 3, v2
	v_lshlrev_b32_e32 v11, 6, v2
	v_mov_b32_e32 v4, v2
	v_mov_b32_e32 v5, 0
	s_add_u32 s6, s46, s42
	s_addc_u32 s7, s47, s43
	v_lshlrev_b64 v[0:1], 14, v[4:5]
	v_lshl_add_u64 v[0:1], s[44:45], 0, v[0:1]
	v_lshlrev_b64 v[4:5], 12, v[4:5]
	s_mov_b64 s[8:9], 0
	v_readlane_b32 s48, v254, 45
	v_readlane_b32 s49, v254, 46
	v_readlane_b32 s50, v254, 47
	v_readlane_b32 s51, v254, 48
	v_readlane_b32 s52, v254, 49
	v_readlane_b32 s53, v254, 50
	v_readlane_b32 s54, v254, 51
	v_readlane_b32 s55, v254, 52
	v_readlane_b32 s56, v254, 53
	v_readlane_b32 s57, v254, 54
	v_readlane_b32 s58, v254, 55
	v_readlane_b32 s59, v254, 56
	s_branch .LBB0_1255
.LBB0_1254:
	s_or_b64 exec, exec, s[12:13]
	v_add_u32_e32 v2, 0x180, v2
	v_add_u32_e32 v10, 0xc00, v10
	v_add_u32_e32 v11, 0x6000, v11
	s_mov_b64 s[10:11], 0x600000
	v_lshl_add_u64 v[0:1], v[0:1], 0, s[10:11]
	v_cmp_le_i32_e32 vcc, s63, v2
	s_mov_b64 s[10:11], 0x180000
	s_or_b64 s[8:9], vcc, s[8:9]
	v_lshl_add_u64 v[4:5], v[4:5], 0, s[10:11]
	s_andn2_b64 exec, exec, s[8:9]
	s_cbranch_execz .LBB0_1259

; DI float bf2f(u16 h) { return __uint_as_float(((unsigned)h) << 16); }
; DI float sigmoidf_(float x) { return __builtin_amdgcn_rcpf(1.f + __expf(-x)); }
; DI void img_barrier() { asm volatile("s_waitcnt lgkmcnt(0)" ::: "memory"); __builtin_amdgcn_s_barrier(); }
; DI void gate_tile(const Params& p, int l, int mt, int nt, char* smem) {
;     ...
;   u16* img = (u16*)smem + (wr * 128 + fq * 4) * IMG_LD + wc * 64 + fr;
; #pragma unroll
;   for (int n = 0; n < 4; ++n) {
;     const float bv = bm[n * 16];
; #pragma unroll
;     for (int m = 0; m < 8; ++m)
; #pragma unroll
;       for (int j = 0; j < 4; ++j) {
;         u16* q = img + (m * 16 + j) * IMG_LD + n * 16;
;         *q = f2bf(sigmoidf_(acc[m][n][j] + bv) * bf2f(*q));
;       }
;   }
;   img_barrier();
.LBB0_2020:
	s_or_b64 exec, exec, s[6:7]
	s_lshl_b64 s[4:5], s[4:5], 2
	s_add_u32 s4, s12, s4
	v_and_b32_e32 v2, 0xc0, v132
	s_addc_u32 s5, s13, s5
	v_lshlrev_b32_e32 v172, 2, v2
	v_and_b32_e32 v133, 15, v132
	v_lshrrev_b32_e32 v134, 1, v132
	v_lshrrev_b32_e32 v132, 2, v132
	v_lshl_add_u64 v[0:1], s[4:5], 0, v[172:173]
	v_and_b32_e32 v132, 12, v132
	s_mov_b32 s4, 0xfffff80
	v_and_or_b32 v132, v134, s4, v132
	v_lshlrev_b32_e32 v172, 2, v133
	v_mul_lo_u32 v132, v132, s3
	v_lshl_add_u64 v[0:1], v[0:1], 0, v[172:173]
	v_add_u32_e32 v132, 16, v132
	v_lshlrev_b32_e32 v2, 1, v2
	v_lshlrev_b32_e32 v133, 1, v133
	s_waitcnt lgkmcnt(0)
	s_barrier
	v_add3_u32 v2, v132, v2, v133
	s_mov_b32 s28, 0x8000
	s_add_i32 s20, s20, 1
	s_mov_b64 s[6:7], 0
	ds_read_u16 v134, v2
	ds_read_u16 v135, v2 offset:528
	ds_read_u16 v136, v2 offset:1056
	ds_read_u16 v137, v2 offset:1584
	ds_read_u16 v138, v2 offset:8448
	ds_read_u16 v139, v2 offset:8976
	ds_read_u16 v140, v2 offset:9504
	ds_read_u16 v141, v2 offset:10032
	s_waitcnt lgkmcnt(4)
	v_lshlrev_b32_e32 v134, 16, v134
	v_lshlrev_b32_e32 v135, 16, v135
	v_lshlrev_b32_e32 v136, 16, v136
	v_lshlrev_b32_e32 v137, 16, v137
	v_mul_f32_e32 v128, v128, v134
	v_mul_f32_e32 v129, v129, v135
	v_mul_f32_e32 v130, v130, v136
	v_mul_f32_e32 v131, v131, v137
	v_cvt_pk_bf16_f32 v146, v128, v129
	v_cvt_pk_bf16_f32 v147, v130, v131
	ds_write_b16 v2, v146
	ds_write_b16_d16_hi v2, v146 offset:528
	ds_write_b16 v2, v147 offset:1056
	ds_write_b16_d16_hi v2, v147 offset:1584
	ds_read_u16 v134, v2 offset:16896
	ds_read_u16 v135, v2 offset:17424
	ds_read_u16 v136, v2 offset:17952
	ds_read_u16 v137, v2 offset:18480
	s_waitcnt lgkmcnt(8)
	v_lshlrev_b32_e32 v138, 16, v138
	v_lshlrev_b32_e32 v139, 16, v139
	v_lshlrev_b32_e32 v140, 16, v140
	v_lshlrev_b32_e32 v141, 16, v141
	v_mul_f32_e32 v124, v124, v138
	v_mul_f32_e32 v125, v125, v139
	v_mul_f32_e32 v126, v126, v140
	v_mul_f32_e32 v127, v127, v141
	v_cvt_pk_bf16_f32 v146, v124, v125
	v_cvt_pk_bf16_f32 v147, v126, v127
	ds_write_b16 v2, v146 offset:8448
	ds_write_b16_d16_hi v2, v146 offset:8976
	ds_write_b16 v2, v147 offset:9504
	ds_write_b16_d16_hi v2, v147 offset:10032
	ds_read_u16 v138, v2 offset:25344
	ds_read_u16 v139, v2 offset:25872
	ds_read_u16 v140, v2 offset:26400
	ds_read_u16 v141, v2 offset:26928
	s_waitcnt lgkmcnt(8)
	v_lshlrev_b32_e32 v134, 16, v134
	v_lshlrev_b32_e32 v135, 16, v135
	v_lshlrev_b32_e32 v136, 16, v136
	v_lshlrev_b32_e32 v137, 16, v137
	v_mul_f32_e32 v120, v120, v134
	v_mul_f32_e32 v121, v121, v135
	v_mul_f32_e32 v122, v122, v136
	v_mul_f32_e32 v123, v123, v137
	v_cvt_pk_bf16_f32 v146, v120, v121
	v_cvt_pk_bf16_f32 v147, v122, v123
	ds_write_b16 v2, v146 offset:16896
	ds_write_b16_d16_hi v2, v146 offset:17424
	ds_write_b16 v2, v147 offset:17952
	ds_write_b16_d16_hi v2, v147 offset:18480
	ds_read_u16 v134, v2 offset:33792
	ds_read_u16 v135, v2 offset:34320
	ds_read_u16 v136, v2 offset:34848
	ds_read_u16 v137, v2 offset:35376
	s_waitcnt lgkmcnt(8)
	v_lshlrev_b32_e32 v138, 16, v138
	v_lshlrev_b32_e32 v139, 16, v139
	v_lshlrev_b32_e32 v140, 16, v140
	v_lshlrev_b32_e32 v141, 16, v141
	v_mul_f32_e32 v116, v116, v138
	v_mul_f32_e32 v117, v117, v139
	v_mul_f32_e32 v118, v118, v140
	v_mul_f32_e32 v119, v119, v141
	v_cvt_pk_bf16_f32 v146, v116, v117
	v_cvt_pk_bf16_f32 v147, v118, v119
	ds_write_b16 v2, v146 offset:25344
	ds_write_b16_d16_hi v2, v146 offset:25872
	ds_write_b16 v2, v147 offset:26400
	ds_write_b16_d16_hi v2, v147 offset:26928
	ds_read_u16 v138, v2 offset:42240
	ds_read_u16 v139, v2 offset:42768
	ds_read_u16 v140, v2 offset:43296
	ds_read_u16 v141, v2 offset:43824
	s_waitcnt lgkmcnt(8)
	v_lshlrev_b32_e32 v134, 16, v134
	v_lshlrev_b32_e32 v135, 16, v135
	v_lshlrev_b32_e32 v136, 16, v136
	v_lshlrev_b32_e32 v137, 16, v137
	v_mul_f32_e32 v112, v112, v134
	v_mul_f32_e32 v113, v113, v135
	v_mul_f32_e32 v114, v114, v136
	v_mul_f32_e32 v115, v115, v137
	v_cvt_pk_bf16_f32 v146, v112, v113
	v_cvt_pk_bf16_f32 v147, v114, v115
	ds_write_b16 v2, v146 offset:33792
	ds_write_b16_d16_hi v2, v146 offset:34320
	ds_write_b16 v2, v147 offset:34848
	ds_write_b16_d16_hi v2, v147 offset:35376
	ds_read_u16 v134, v2 offset:50688
	ds_read_u16 v135, v2 offset:51216
	ds_read_u16 v136, v2 offset:51744
	ds_read_u16 v137, v2 offset:52272
	s_waitcnt lgkmcnt(8)
	v_lshlrev_b32_e32 v138, 16, v138
	v_lshlrev_b32_e32 v139, 16, v139
	v_lshlrev_b32_e32 v140, 16, v140
	v_lshlrev_b32_e32 v141, 16, v141
	v_mul_f32_e32 v108, v108, v138
	v_mul_f32_e32 v109, v109, v139
	v_mul_f32_e32 v110, v110, v140
	v_mul_f32_e32 v111, v111, v141
	v_cvt_pk_bf16_f32 v146, v108, v109
	v_cvt_pk_bf16_f32 v147, v110, v111
	ds_write_b16 v2, v146 offset:42240
	ds_write_b16_d16_hi v2, v146 offset:42768
	ds_write_b16 v2, v147 offset:43296
	ds_write_b16_d16_hi v2, v147 offset:43824
	ds_read_u16 v138, v2 offset:59136
	ds_read_u16 v139, v2 offset:59664
	ds_read_u16 v140, v2 offset:60192
	ds_read_u16 v141, v2 offset:60720
	s_waitcnt lgkmcnt(8)
	v_lshlrev_b32_e32 v134, 16, v134
	v_lshlrev_b32_e32 v135, 16, v135
	v_lshlrev_b32_e32 v136, 16, v136
	v_lshlrev_b32_e32 v137, 16, v137
	v_mul_f32_e32 v104, v104, v134
	v_mul_f32_e32 v105, v105, v135
	v_mul_f32_e32 v106, v106, v136
	v_mul_f32_e32 v107, v107, v137
	v_cvt_pk_bf16_f32 v146, v104, v105
	v_cvt_pk_bf16_f32 v147, v106, v107
	ds_write_b16 v2, v146 offset:50688
	ds_write_b16_d16_hi v2, v146 offset:51216
	ds_write_b16 v2, v147 offset:51744
	ds_write_b16_d16_hi v2, v147 offset:52272
	ds_read_u16 v134, v2 offset:32
	ds_read_u16 v135, v2 offset:560
	ds_read_u16 v136, v2 offset:1088
	ds_read_u16 v137, v2 offset:1616
	s_waitcnt lgkmcnt(8)
; DI float bf2f(u16 h) { return __uint_as_float(((unsigned)h) << 16); }
; DI float sigmoidf_(float x) { return __builtin_amdgcn_rcpf(1.f + __expf(-x)); }
; DI void img_barrier() { asm volatile("s_waitcnt lgkmcnt(0)" ::: "memory"); __builtin_amdgcn_s_barrier(); }
; DI void gate_tile(const Params& p, int l, int mt, int nt, char* smem) {
;     ...
;   u16* img = (u16*)smem + (wr * 128 + fq * 4) * IMG_LD + wc * 64 + fr;
; #pragma unroll
;   for (int n = 0; n < 4; ++n) {
;     const float bv = bm[n * 16];
; #pragma unroll
;     for (int m = 0; m < 8; ++m)
; #pragma unroll
;       for (int j = 0; j < 4; ++j) {
;         u16* q = img + (m * 16 + j) * IMG_LD + n * 16;
;         *q = f2bf(sigmoidf_(acc[m][n][j] + bv) * bf2f(*q));
;       }
;   }
;   img_barrier();
	v_lshlrev_b32_e32 v138, 16, v138
	v_lshlrev_b32_e32 v139, 16, v139
	v_lshlrev_b32_e32 v140, 16, v140
	v_lshlrev_b32_e32 v141, 16, v141
	v_mul_f32_e32 v100, v100, v138
	v_mul_f32_e32 v101, v101, v139
	v_mul_f32_e32 v102, v102, v140
	v_mul_f32_e32 v103, v103, v141
	v_cvt_pk_bf16_f32 v146, v100, v101
	v_cvt_pk_bf16_f32 v147, v102, v103
	ds_write_b16 v2, v146 offset:59136
	ds_write_b16_d16_hi v2, v146 offset:59664
	ds_write_b16 v2, v147 offset:60192
	ds_write_b16_d16_hi v2, v147 offset:60720
	ds_read_u16 v138, v2 offset:8480
	ds_read_u16 v139, v2 offset:9008
	ds_read_u16 v140, v2 offset:9536
	ds_read_u16 v141, v2 offset:10064
	s_waitcnt lgkmcnt(8)
	v_lshlrev_b32_e32 v134, 16, v134
	v_lshlrev_b32_e32 v135, 16, v135
	v_lshlrev_b32_e32 v136, 16, v136
	v_lshlrev_b32_e32 v137, 16, v137
	v_mul_f32_e32 v96, v96, v134
	v_mul_f32_e32 v97, v97, v135
	v_mul_f32_e32 v98, v98, v136
	v_mul_f32_e32 v99, v99, v137
	v_cvt_pk_bf16_f32 v146, v96, v97
	v_cvt_pk_bf16_f32 v147, v98, v99
	ds_write_b16 v2, v146 offset:32
	ds_write_b16_d16_hi v2, v146 offset:560
	ds_write_b16 v2, v147 offset:1088
	ds_write_b16_d16_hi v2, v147 offset:1616
	ds_read_u16 v134, v2 offset:16928
	ds_read_u16 v135, v2 offset:17456
	ds_read_u16 v136, v2 offset:17984
	ds_read_u16 v137, v2 offset:18512
	s_waitcnt lgkmcnt(8)
	v_lshlrev_b32_e32 v138, 16, v138
	v_lshlrev_b32_e32 v139, 16, v139
	v_lshlrev_b32_e32 v140, 16, v140
	v_lshlrev_b32_e32 v141, 16, v141
	v_mul_f32_e32 v92, v92, v138
	v_mul_f32_e32 v93, v93, v139
	v_mul_f32_e32 v94, v94, v140
	v_mul_f32_e32 v95, v95, v141
	v_cvt_pk_bf16_f32 v146, v92, v93
	v_cvt_pk_bf16_f32 v147, v94, v95
	ds_write_b16 v2, v146 offset:8480
	ds_write_b16_d16_hi v2, v146 offset:9008
	ds_write_b16 v2, v147 offset:9536
	ds_write_b16_d16_hi v2, v147 offset:10064
	ds_read_u16 v138, v2 offset:25376
	ds_read_u16 v139, v2 offset:25904
	ds_read_u16 v140, v2 offset:26432
	ds_read_u16 v141, v2 offset:26960
	s_waitcnt lgkmcnt(8)
	v_lshlrev_b32_e32 v134, 16, v134
	v_lshlrev_b32_e32 v135, 16, v135
	v_lshlrev_b32_e32 v136, 16, v136
	v_lshlrev_b32_e32 v137, 16, v137
	v_mul_f32_e32 v88, v88, v134
	v_mul_f32_e32 v89, v89, v135
	v_mul_f32_e32 v90, v90, v136
	v_mul_f32_e32 v91, v91, v137
	v_cvt_pk_bf16_f32 v146, v88, v89
	v_cvt_pk_bf16_f32 v147, v90, v91
	ds_write_b16 v2, v146 offset:16928
	ds_write_b16_d16_hi v2, v146 offset:17456
	ds_write_b16 v2, v147 offset:17984
	ds_write_b16_d16_hi v2, v147 offset:18512
	ds_read_u16 v134, v2 offset:33824
	ds_read_u16 v135, v2 offset:34352
	ds_read_u16 v136, v2 offset:34880
	ds_read_u16 v137, v2 offset:35408
	s_waitcnt lgkmcnt(8)
	v_lshlrev_b32_e32 v138, 16, v138
	v_lshlrev_b32_e32 v139, 16, v139
	v_lshlrev_b32_e32 v140, 16, v140
	v_lshlrev_b32_e32 v141, 16, v141
	v_mul_f32_e32 v84, v84, v138
	v_mul_f32_e32 v85, v85, v139
	v_mul_f32_e32 v86, v86, v140
	v_mul_f32_e32 v87, v87, v141
	v_cvt_pk_bf16_f32 v146, v84, v85
	v_cvt_pk_bf16_f32 v147, v86, v87
	ds_write_b16 v2, v146 offset:25376
	ds_write_b16_d16_hi v2, v146 offset:25904
	ds_write_b16 v2, v147 offset:26432
	ds_write_b16_d16_hi v2, v147 offset:26960
	ds_read_u16 v138, v2 offset:42272
	ds_read_u16 v139, v2 offset:42800
	ds_read_u16 v140, v2 offset:43328
	ds_read_u16 v141, v2 offset:43856
	s_waitcnt lgkmcnt(8)
	v_lshlrev_b32_e32 v134, 16, v134
	v_lshlrev_b32_e32 v135, 16, v135
	v_lshlrev_b32_e32 v136, 16, v136
	v_lshlrev_b32_e32 v137, 16, v137
	v_mul_f32_e32 v80, v80, v134
	v_mul_f32_e32 v81, v81, v135
	v_mul_f32_e32 v82, v82, v136
	v_mul_f32_e32 v83, v83, v137
	v_cvt_pk_bf16_f32 v146, v80, v81
	v_cvt_pk_bf16_f32 v147, v82, v83
	ds_write_b16 v2, v146 offset:33824
	ds_write_b16_d16_hi v2, v146 offset:34352
	ds_write_b16 v2, v147 offset:34880
	ds_write_b16_d16_hi v2, v147 offset:35408
	ds_read_u16 v134, v2 offset:50720
	ds_read_u16 v135, v2 offset:51248
	ds_read_u16 v136, v2 offset:51776
	ds_read_u16 v137, v2 offset:52304
	s_waitcnt lgkmcnt(8)
	v_lshlrev_b32_e32 v138, 16, v138
	v_lshlrev_b32_e32 v139, 16, v139
	v_lshlrev_b32_e32 v140, 16, v140
	v_lshlrev_b32_e32 v141, 16, v141
	v_mul_f32_e32 v76, v76, v138
	v_mul_f32_e32 v77, v77, v139
	v_mul_f32_e32 v78, v78, v140
	v_mul_f32_e32 v79, v79, v141
	v_cvt_pk_bf16_f32 v146, v76, v77
	v_cvt_pk_bf16_f32 v147, v78, v79
	ds_write_b16 v2, v146 offset:42272
	ds_write_b16_d16_hi v2, v146 offset:42800
	ds_write_b16 v2, v147 offset:43328
	ds_write_b16_d16_hi v2, v147 offset:43856
	ds_read_u16 v138, v2 offset:59168
	ds_read_u16 v139, v2 offset:59696
	ds_read_u16 v140, v2 offset:60224
	ds_read_u16 v141, v2 offset:60752
	s_waitcnt lgkmcnt(8)
	v_lshlrev_b32_e32 v134, 16, v134
	v_lshlrev_b32_e32 v135, 16, v135
	v_lshlrev_b32_e32 v136, 16, v136
	v_lshlrev_b32_e32 v137, 16, v137
	v_mul_f32_e32 v72, v72, v134
	v_mul_f32_e32 v73, v73, v135
	v_mul_f32_e32 v74, v74, v136
	v_mul_f32_e32 v75, v75, v137
	v_cvt_pk_bf16_f32 v146, v72, v73
	v_cvt_pk_bf16_f32 v147, v74, v75
	ds_write_b16 v2, v146 offset:50720
	ds_write_b16_d16_hi v2, v146 offset:51248
	ds_write_b16 v2, v147 offset:51776
	ds_write_b16_d16_hi v2, v147 offset:52304
	ds_read_u16 v134, v2 offset:64
	ds_read_u16 v135, v2 offset:592
	ds_read_u16 v136, v2 offset:1120
	ds_read_u16 v137, v2 offset:1648
	s_waitcnt lgkmcnt(8)
	v_lshlrev_b32_e32 v138, 16, v138
	v_lshlrev_b32_e32 v139, 16, v139
	v_lshlrev_b32_e32 v140, 16, v140
	v_lshlrev_b32_e32 v141, 16, v141
	v_mul_f32_e32 v68, v68, v138
	v_mul_f32_e32 v69, v69, v139
	v_mul_f32_e32 v70, v70, v140
	v_mul_f32_e32 v71, v71, v141
	v_cvt_pk_bf16_f32 v146, v68, v69
	v_cvt_pk_bf16_f32 v147, v70, v71
	ds_write_b16 v2, v146 offset:59168
	ds_write_b16_d16_hi v2, v146 offset:59696
	ds_write_b16 v2, v147 offset:60224
	ds_write_b16_d16_hi v2, v147 offset:60752
	ds_read_u16 v138, v2 offset:8512
	ds_read_u16 v139, v2 offset:9040
	ds_read_u16 v140, v2 offset:9568
	ds_read_u16 v141, v2 offset:10096
	s_waitcnt lgkmcnt(8)
; DI float bf2f(u16 h) { return __uint_as_float(((unsigned)h) << 16); }
; DI float sigmoidf_(float x) { return __builtin_amdgcn_rcpf(1.f + __expf(-x)); }
; DI void img_barrier() { asm volatile("s_waitcnt lgkmcnt(0)" ::: "memory"); __builtin_amdgcn_s_barrier(); }
; DI void gate_tile(const Params& p, int l, int mt, int nt, char* smem) {
;     ...
;   u16* img = (u16*)smem + (wr * 128 + fq * 4) * IMG_LD + wc * 64 + fr;
; #pragma unroll
;   for (int n = 0; n < 4; ++n) {
;     const float bv = bm[n * 16];
; #pragma unroll
;     for (int m = 0; m < 8; ++m)
; #pragma unroll
;       for (int j = 0; j < 4; ++j) {
;         u16* q = img + (m * 16 + j) * IMG_LD + n * 16;
;         *q = f2bf(sigmoidf_(acc[m][n][j] + bv) * bf2f(*q));
;       }
;   }
;   img_barrier();
	v_lshlrev_b32_e32 v134, 16, v134
	v_lshlrev_b32_e32 v135, 16, v135
	v_lshlrev_b32_e32 v136, 16, v136
	v_lshlrev_b32_e32 v137, 16, v137
	v_mul_f32_e32 v64, v64, v134
	v_mul_f32_e32 v65, v65, v135
	v_mul_f32_e32 v66, v66, v136
	v_mul_f32_e32 v67, v67, v137
	v_cvt_pk_bf16_f32 v146, v64, v65
	v_cvt_pk_bf16_f32 v147, v66, v67
	ds_write_b16 v2, v146 offset:64
	ds_write_b16_d16_hi v2, v146 offset:592
	ds_write_b16 v2, v147 offset:1120
	ds_write_b16_d16_hi v2, v147 offset:1648
	ds_read_u16 v134, v2 offset:16960
	ds_read_u16 v135, v2 offset:17488
	ds_read_u16 v136, v2 offset:18016
	ds_read_u16 v137, v2 offset:18544
	s_waitcnt lgkmcnt(8)
	v_lshlrev_b32_e32 v138, 16, v138
	v_lshlrev_b32_e32 v139, 16, v139
	v_lshlrev_b32_e32 v140, 16, v140
	v_lshlrev_b32_e32 v141, 16, v141
	v_mul_f32_e32 v60, v60, v138
	v_mul_f32_e32 v61, v61, v139
	v_mul_f32_e32 v62, v62, v140
	v_mul_f32_e32 v63, v63, v141
	v_cvt_pk_bf16_f32 v146, v60, v61
	v_cvt_pk_bf16_f32 v147, v62, v63
	ds_write_b16 v2, v146 offset:8512
	ds_write_b16_d16_hi v2, v146 offset:9040
	ds_write_b16 v2, v147 offset:9568
	ds_write_b16_d16_hi v2, v147 offset:10096
	ds_read_u16 v138, v2 offset:25408
	ds_read_u16 v139, v2 offset:25936
	ds_read_u16 v140, v2 offset:26464
	ds_read_u16 v141, v2 offset:26992
	s_waitcnt lgkmcnt(8)
	v_lshlrev_b32_e32 v134, 16, v134
	v_lshlrev_b32_e32 v135, 16, v135
	v_lshlrev_b32_e32 v136, 16, v136
	v_lshlrev_b32_e32 v137, 16, v137
	v_mul_f32_e32 v56, v56, v134
	v_mul_f32_e32 v57, v57, v135
	v_mul_f32_e32 v58, v58, v136
	v_mul_f32_e32 v59, v59, v137
	v_cvt_pk_bf16_f32 v146, v56, v57
	v_cvt_pk_bf16_f32 v147, v58, v59
	ds_write_b16 v2, v146 offset:16960
	ds_write_b16_d16_hi v2, v146 offset:17488
	ds_write_b16 v2, v147 offset:18016
	ds_write_b16_d16_hi v2, v147 offset:18544
	ds_read_u16 v134, v2 offset:33856
	ds_read_u16 v135, v2 offset:34384
	ds_read_u16 v136, v2 offset:34912
	ds_read_u16 v137, v2 offset:35440
	s_waitcnt lgkmcnt(8)
	v_lshlrev_b32_e32 v138, 16, v138
	v_lshlrev_b32_e32 v139, 16, v139
	v_lshlrev_b32_e32 v140, 16, v140
	v_lshlrev_b32_e32 v141, 16, v141
	v_mul_f32_e32 v52, v52, v138
	v_mul_f32_e32 v53, v53, v139
	v_mul_f32_e32 v54, v54, v140
	v_mul_f32_e32 v55, v55, v141
	v_cvt_pk_bf16_f32 v146, v52, v53
	v_cvt_pk_bf16_f32 v147, v54, v55
	ds_write_b16 v2, v146 offset:25408
	ds_write_b16_d16_hi v2, v146 offset:25936
	ds_write_b16 v2, v147 offset:26464
	ds_write_b16_d16_hi v2, v147 offset:26992
	ds_read_u16 v138, v2 offset:42304
	ds_read_u16 v139, v2 offset:42832
	ds_read_u16 v140, v2 offset:43360
	ds_read_u16 v141, v2 offset:43888
	s_waitcnt lgkmcnt(8)
	v_lshlrev_b32_e32 v134, 16, v134
	v_lshlrev_b32_e32 v135, 16, v135
	v_lshlrev_b32_e32 v136, 16, v136
	v_lshlrev_b32_e32 v137, 16, v137
	v_mul_f32_e32 v48, v48, v134
	v_mul_f32_e32 v49, v49, v135
	v_mul_f32_e32 v50, v50, v136
	v_mul_f32_e32 v51, v51, v137
	v_cvt_pk_bf16_f32 v146, v48, v49
	v_cvt_pk_bf16_f32 v147, v50, v51
	ds_write_b16 v2, v146 offset:33856
	ds_write_b16_d16_hi v2, v146 offset:34384
	ds_write_b16 v2, v147 offset:34912
	ds_write_b16_d16_hi v2, v147 offset:35440
	ds_read_u16 v134, v2 offset:50752
	ds_read_u16 v135, v2 offset:51280
	ds_read_u16 v136, v2 offset:51808
	ds_read_u16 v137, v2 offset:52336
	s_waitcnt lgkmcnt(8)
	v_lshlrev_b32_e32 v138, 16, v138
	v_lshlrev_b32_e32 v139, 16, v139
	v_lshlrev_b32_e32 v140, 16, v140
	v_lshlrev_b32_e32 v141, 16, v141
	v_mul_f32_e32 v44, v44, v138
	v_mul_f32_e32 v45, v45, v139
	v_mul_f32_e32 v46, v46, v140
	v_mul_f32_e32 v47, v47, v141
	v_cvt_pk_bf16_f32 v146, v44, v45
	v_cvt_pk_bf16_f32 v147, v46, v47
	ds_write_b16 v2, v146 offset:42304
	ds_write_b16_d16_hi v2, v146 offset:42832
	ds_write_b16 v2, v147 offset:43360
	ds_write_b16_d16_hi v2, v147 offset:43888
	ds_read_u16 v138, v2 offset:59200
	ds_read_u16 v139, v2 offset:59728
	ds_read_u16 v140, v2 offset:60256
	ds_read_u16 v141, v2 offset:60784
	s_waitcnt lgkmcnt(8)
	v_lshlrev_b32_e32 v134, 16, v134
	v_lshlrev_b32_e32 v135, 16, v135
	v_lshlrev_b32_e32 v136, 16, v136
	v_lshlrev_b32_e32 v137, 16, v137
	v_mul_f32_e32 v40, v40, v134
	v_mul_f32_e32 v41, v41, v135
	v_mul_f32_e32 v42, v42, v136
	v_mul_f32_e32 v43, v43, v137
	v_cvt_pk_bf16_f32 v146, v40, v41
	v_cvt_pk_bf16_f32 v147, v42, v43
	ds_write_b16 v2, v146 offset:50752
	ds_write_b16_d16_hi v2, v146 offset:51280
	ds_write_b16 v2, v147 offset:51808
	ds_write_b16_d16_hi v2, v147 offset:52336
	ds_read_u16 v134, v2 offset:96
	ds_read_u16 v135, v2 offset:624
	ds_read_u16 v136, v2 offset:1152
	ds_read_u16 v137, v2 offset:1680
	s_waitcnt lgkmcnt(8)
	v_lshlrev_b32_e32 v138, 16, v138
	v_lshlrev_b32_e32 v139, 16, v139
	v_lshlrev_b32_e32 v140, 16, v140
	v_lshlrev_b32_e32 v141, 16, v141
	v_mul_f32_e32 v36, v36, v138
	v_mul_f32_e32 v37, v37, v139
	v_mul_f32_e32 v38, v38, v140
	v_mul_f32_e32 v39, v39, v141
	v_cvt_pk_bf16_f32 v146, v36, v37
	v_cvt_pk_bf16_f32 v147, v38, v39
	ds_write_b16 v2, v146 offset:59200
	ds_write_b16_d16_hi v2, v146 offset:59728
	ds_write_b16 v2, v147 offset:60256
	ds_write_b16_d16_hi v2, v147 offset:60784
	ds_read_u16 v138, v2 offset:8544
	ds_read_u16 v139, v2 offset:9072
	ds_read_u16 v140, v2 offset:9600
	ds_read_u16 v141, v2 offset:10128
	s_waitcnt lgkmcnt(8)
	v_lshlrev_b32_e32 v134, 16, v134
	v_lshlrev_b32_e32 v135, 16, v135
	v_lshlrev_b32_e32 v136, 16, v136
	v_lshlrev_b32_e32 v137, 16, v137
	v_mul_f32_e32 v32, v32, v134
	v_mul_f32_e32 v33, v33, v135
	v_mul_f32_e32 v34, v34, v136
	v_mul_f32_e32 v35, v35, v137
	v_cvt_pk_bf16_f32 v146, v32, v33
	v_cvt_pk_bf16_f32 v147, v34, v35
	ds_write_b16 v2, v146 offset:96
	ds_write_b16_d16_hi v2, v146 offset:624
	ds_write_b16 v2, v147 offset:1152
	ds_write_b16_d16_hi v2, v147 offset:1680
	ds_read_u16 v134, v2 offset:16992
	ds_read_u16 v135, v2 offset:17520
	ds_read_u16 v136, v2 offset:18048
	ds_read_u16 v137, v2 offset:18576
	s_waitcnt lgkmcnt(8)
; DI float bf2f(u16 h) { return __uint_as_float(((unsigned)h) << 16); }
; DI float sigmoidf_(float x) { return __builtin_amdgcn_rcpf(1.f + __expf(-x)); }
; DI void img_barrier() { asm volatile("s_waitcnt lgkmcnt(0)" ::: "memory"); __builtin_amdgcn_s_barrier(); }
; DI void gate_tile(const Params& p, int l, int mt, int nt, char* smem) {
;     ...
;   u16* img = (u16*)smem + (wr * 128 + fq * 4) * IMG_LD + wc * 64 + fr;
; #pragma unroll
;   for (int n = 0; n < 4; ++n) {
;     const float bv = bm[n * 16];
; #pragma unroll
;     for (int m = 0; m < 8; ++m)
; #pragma unroll
;       for (int j = 0; j < 4; ++j) {
;         u16* q = img + (m * 16 + j) * IMG_LD + n * 16;
;         *q = f2bf(sigmoidf_(acc[m][n][j] + bv) * bf2f(*q));
;       }
;   }
;   img_barrier();
;   img_store_bf16(Y, 3072, smem, 0);
	v_lshlrev_b32_e32 v138, 16, v138
	v_lshlrev_b32_e32 v139, 16, v139
	v_lshlrev_b32_e32 v140, 16, v140
	v_lshlrev_b32_e32 v141, 16, v141
	v_mul_f32_e32 v28, v28, v138
	v_mul_f32_e32 v29, v29, v139
	v_mul_f32_e32 v30, v30, v140
	v_mul_f32_e32 v31, v31, v141
	v_cvt_pk_bf16_f32 v146, v28, v29
	v_cvt_pk_bf16_f32 v147, v30, v31
	ds_write_b16 v2, v146 offset:8544
	ds_write_b16_d16_hi v2, v146 offset:9072
	ds_write_b16 v2, v147 offset:9600
	ds_write_b16_d16_hi v2, v147 offset:10128
	ds_read_u16 v138, v2 offset:25440
	ds_read_u16 v139, v2 offset:25968
	ds_read_u16 v140, v2 offset:26496
	ds_read_u16 v141, v2 offset:27024
	s_waitcnt lgkmcnt(8)
	v_lshlrev_b32_e32 v134, 16, v134
	v_lshlrev_b32_e32 v135, 16, v135
	v_lshlrev_b32_e32 v136, 16, v136
	v_lshlrev_b32_e32 v137, 16, v137
	v_mul_f32_e32 v24, v24, v134
	v_mul_f32_e32 v25, v25, v135
	v_mul_f32_e32 v26, v26, v136
	v_mul_f32_e32 v27, v27, v137
	v_cvt_pk_bf16_f32 v146, v24, v25
	v_cvt_pk_bf16_f32 v147, v26, v27
	ds_write_b16 v2, v146 offset:16992
	ds_write_b16_d16_hi v2, v146 offset:17520
	ds_write_b16 v2, v147 offset:18048
	ds_write_b16_d16_hi v2, v147 offset:18576
	ds_read_u16 v134, v2 offset:33888
	ds_read_u16 v135, v2 offset:34416
	ds_read_u16 v136, v2 offset:34944
	ds_read_u16 v137, v2 offset:35472
	s_waitcnt lgkmcnt(8)
	v_lshlrev_b32_e32 v138, 16, v138
	v_lshlrev_b32_e32 v139, 16, v139
	v_lshlrev_b32_e32 v140, 16, v140
	v_lshlrev_b32_e32 v141, 16, v141
	v_mul_f32_e32 v20, v20, v138
	v_mul_f32_e32 v21, v21, v139
	v_mul_f32_e32 v22, v22, v140
	v_mul_f32_e32 v23, v23, v141
	v_cvt_pk_bf16_f32 v146, v20, v21
	v_cvt_pk_bf16_f32 v147, v22, v23
	ds_write_b16 v2, v146 offset:25440
	ds_write_b16_d16_hi v2, v146 offset:25968
	ds_write_b16 v2, v147 offset:26496
	ds_write_b16_d16_hi v2, v147 offset:27024
	ds_read_u16 v138, v2 offset:42336
	ds_read_u16 v139, v2 offset:42864
	ds_read_u16 v140, v2 offset:43392
	ds_read_u16 v141, v2 offset:43920
	s_waitcnt lgkmcnt(8)
	v_lshlrev_b32_e32 v134, 16, v134
	v_lshlrev_b32_e32 v135, 16, v135
	v_lshlrev_b32_e32 v136, 16, v136
	v_lshlrev_b32_e32 v137, 16, v137
	v_mul_f32_e32 v16, v16, v134
	v_mul_f32_e32 v17, v17, v135
	v_mul_f32_e32 v18, v18, v136
	v_mul_f32_e32 v19, v19, v137
	v_cvt_pk_bf16_f32 v146, v16, v17
	v_cvt_pk_bf16_f32 v147, v18, v19
	ds_write_b16 v2, v146 offset:33888
	ds_write_b16_d16_hi v2, v146 offset:34416
	ds_write_b16 v2, v147 offset:34944
	ds_write_b16_d16_hi v2, v147 offset:35472
	ds_read_u16 v134, v2 offset:50784
	ds_read_u16 v135, v2 offset:51312
	ds_read_u16 v136, v2 offset:51840
	ds_read_u16 v137, v2 offset:52368
	s_waitcnt lgkmcnt(8)
	v_lshlrev_b32_e32 v138, 16, v138
	v_lshlrev_b32_e32 v139, 16, v139
	v_lshlrev_b32_e32 v140, 16, v140
	v_lshlrev_b32_e32 v141, 16, v141
	v_mul_f32_e32 v12, v12, v138
	v_mul_f32_e32 v13, v13, v139
	v_mul_f32_e32 v14, v14, v140
	v_mul_f32_e32 v15, v15, v141
	v_cvt_pk_bf16_f32 v146, v12, v13
	v_cvt_pk_bf16_f32 v147, v14, v15
	ds_write_b16 v2, v146 offset:42336
	ds_write_b16_d16_hi v2, v146 offset:42864
	ds_write_b16 v2, v147 offset:43392
	ds_write_b16_d16_hi v2, v147 offset:43920
	ds_read_u16 v138, v2 offset:59232
	ds_read_u16 v139, v2 offset:59760
	ds_read_u16 v140, v2 offset:60288
	ds_read_u16 v141, v2 offset:60816
	s_waitcnt lgkmcnt(8)
	v_lshlrev_b32_e32 v134, 16, v134
	v_lshlrev_b32_e32 v135, 16, v135
	v_lshlrev_b32_e32 v136, 16, v136
	v_lshlrev_b32_e32 v137, 16, v137
	v_mul_f32_e32 v8, v8, v134
	v_mul_f32_e32 v9, v9, v135
	v_mul_f32_e32 v10, v10, v136
	v_mul_f32_e32 v11, v11, v137
	v_cvt_pk_bf16_f32 v146, v8, v9
	v_cvt_pk_bf16_f32 v147, v10, v11
	ds_write_b16 v2, v146 offset:50784
	ds_write_b16_d16_hi v2, v146 offset:51312
	ds_write_b16 v2, v147 offset:51840
	ds_write_b16_d16_hi v2, v147 offset:52368
	s_waitcnt lgkmcnt(4)
	v_lshlrev_b32_e32 v138, 16, v138
	v_lshlrev_b32_e32 v139, 16, v139
	v_lshlrev_b32_e32 v140, 16, v140
	v_lshlrev_b32_e32 v141, 16, v141
	v_mul_f32_e32 v4, v4, v138
	v_mul_f32_e32 v5, v5, v139
	v_mul_f32_e32 v6, v6, v140
	v_mul_f32_e32 v7, v7, v141
	v_cvt_pk_bf16_f32 v146, v4, v5
	v_cvt_pk_bf16_f32 v147, v6, v7
	ds_write_b16 v2, v146 offset:59232
	ds_write_b16_d16_hi v2, v146 offset:59760
	ds_write_b16 v2, v147 offset:60288
	ds_write_b16_d16_hi v2, v147 offset:60816
	v_mov_b32_e32 v1, v184
	s_waitcnt lgkmcnt(0)
	s_barrier
; DI int TID512() { int t = threadIdx.x; asm volatile("" : "+v"(t)); return t; }
; DI void img_store_bf16(u16* dst, int ld, const char* smem, int rowoff) {
;   const int tid = TID512();
; #pragma unroll
;   for (int q = 0; q < 16; ++q) {
;     const int slot = tid + q * 512, row = slot >> 5, c16 = slot & 31;
;     *(u32x4*)(dst + (size_t)row * ld + c16 * 8) = *(const u32x4*)(smem + (row + rowoff) * (IMG_LD * 2) + c16 * 16);
;   }
; }
	s_nop 0
	v_lshlrev_b32_e32 v0, 4, v1
	v_and_b32_e32 v172, 0x1f0, v0
	v_add_u32_e32 v0, 16, v172
	v_ashrrev_i32_e32 v2, 5, v1
	v_mad_u64_u32 v[4:5], s[4:5], v2, s3, v[0:1]
	ds_read_b128 v[4:7], v4
	v_lshl_add_u64 v[8:9], s[38:39], 0, v[172:173]
	v_mad_i64_i32 v[10:11], s[4:5], v2, s97, v[8:9]
	v_add_u32_e32 v2, 0x200, v1
	v_ashrrev_i32_e32 v2, 5, v2
	s_waitcnt lgkmcnt(0)
	global_store_dwordx4 v[10:11], v[4:7], off
	v_mad_i64_i32 v[10:11], s[4:5], v2, s97, v[8:9]
	s_nop 0
	v_mad_u64_u32 v[4:5], s[4:5], v2, s3, v[0:1]
	ds_read_b128 v[4:7], v4
	v_add_u32_e32 v2, 0x400, v1
	v_ashrrev_i32_e32 v2, 5, v2
	s_waitcnt lgkmcnt(0)
	global_store_dwordx4 v[10:11], v[4:7], off
	s_nop 1
	v_mad_u64_u32 v[4:5], s[4:5], v2, s3, v[0:1]
	ds_read_b128 v[4:7], v4
	v_mad_i64_i32 v[10:11], s[4:5], v2, s97, v[8:9]
	v_add_u32_e32 v2, 0x600, v1
	v_ashrrev_i32_e32 v2, 5, v2
	s_waitcnt lgkmcnt(0)
	global_store_dwordx4 v[10:11], v[4:7], off
	v_mad_i64_i32 v[10:11], s[4:5], v2, s97, v[8:9]
	s_nop 0
	v_mad_u64_u32 v[4:5], s[4:5], v2, s3, v[0:1]
	ds_read_b128 v[4:7], v4
	v_add_u32_e32 v2, 0x800, v1
	v_ashrrev_i32_e32 v2, 5, v2
	s_waitcnt lgkmcnt(0)
	global_store_dwordx4 v[10:11], v[4:7], off
	s_nop 1
	v_mad_u64_u32 v[4:5], s[4:5], v2, s3, v[0:1]
	ds_read_b128 v[4:7], v4
	v_mad_i64_i32 v[10:11], s[4:5], v2, s97, v[8:9]
	v_add_u32_e32 v2, 0xa00, v1
	v_ashrrev_i32_e32 v2, 5, v2
	s_waitcnt lgkmcnt(0)
	global_store_dwordx4 v[10:11], v[4:7], off
	v_mad_i64_i32 v[10:11], s[4:5], v2, s97, v[8:9]
	s_nop 0
	v_mad_u64_u32 v[4:5], s[4:5], v2, s3, v[0:1]
	ds_read_b128 v[4:7], v4
	v_add_u32_e32 v2, 0xc00, v1
	v_ashrrev_i32_e32 v2, 5, v2
	s_waitcnt lgkmcnt(0)
	global_store_dwordx4 v[10:11], v[4:7], off
	s_nop 1
	v_mad_u64_u32 v[4:5], s[4:5], v2, s3, v[0:1]
	ds_read_b128 v[4:7], v4
	v_mad_i64_i32 v[10:11], s[4:5], v2, s97, v[8:9]
	v_add_u32_e32 v2, 0xe00, v1
	v_ashrrev_i32_e32 v2, 5, v2
	s_waitcnt lgkmcnt(0)
	global_store_dwordx4 v[10:11], v[4:7], off
	v_mad_i64_i32 v[10:11], s[4:5], v2, s97, v[8:9]
	s_nop 0
	v_mad_u64_u32 v[4:5], s[4:5], v2, s3, v[0:1]
	ds_read_b128 v[4:7], v4
	v_add_u32_e32 v2, 0x1000, v1
	v_ashrrev_i32_e32 v2, 5, v2
	s_waitcnt lgkmcnt(0)
	global_store_dwordx4 v[10:11], v[4:7], off
	s_nop 1
	v_mad_u64_u32 v[4:5], s[4:5], v2, s3, v[0:1]
	ds_read_b128 v[4:7], v4
	v_mad_i64_i32 v[10:11], s[4:5], v2, s97, v[8:9]
	v_add_u32_e32 v2, 0x1200, v1
	v_ashrrev_i32_e32 v2, 5, v2
	s_waitcnt lgkmcnt(0)
	global_store_dwordx4 v[10:11], v[4:7], off
	v_mad_i64_i32 v[10:11], s[4:5], v2, s97, v[8:9]
	s_nop 0
	v_mad_u64_u32 v[4:5], s[4:5], v2, s3, v[0:1]
	ds_read_b128 v[4:7], v4
	v_add_u32_e32 v2, 0x1400, v1
	v_ashrrev_i32_e32 v2, 5, v2
	s_waitcnt lgkmcnt(0)
	global_store_dwordx4 v[10:11], v[4:7], off
	s_nop 1
	v_mad_u64_u32 v[4:5], s[4:5], v2, s3, v[0:1]
	ds_read_b128 v[4:7], v4
	v_mad_i64_i32 v[10:11], s[4:5], v2, s97, v[8:9]
	v_add_u32_e32 v2, 0x1600, v1
	v_ashrrev_i32_e32 v2, 5, v2
	s_waitcnt lgkmcnt(0)
	global_store_dwordx4 v[10:11], v[4:7], off
	v_mad_i64_i32 v[10:11], s[4:5], v2, s97, v[8:9]
	s_nop 0
	v_mad_u64_u32 v[4:5], s[4:5], v2, s3, v[0:1]
	ds_read_b128 v[4:7], v4
	v_add_u32_e32 v2, 0x1800, v1
	v_ashrrev_i32_e32 v2, 5, v2
	s_waitcnt lgkmcnt(0)
	global_store_dwordx4 v[10:11], v[4:7], off
	s_nop 1
	v_mad_u64_u32 v[4:5], s[4:5], v2, s3, v[0:1]
	ds_read_b128 v[4:7], v4
	v_mad_i64_i32 v[10:11], s[4:5], v2, s97, v[8:9]
	v_add_u32_e32 v2, 0x1a00, v1
	v_ashrrev_i32_e32 v2, 5, v2
	s_waitcnt lgkmcnt(0)
	global_store_dwordx4 v[10:11], v[4:7], off
	v_mad_i64_i32 v[10:11], s[4:5], v2, s97, v[8:9]
	s_nop 0
	v_mad_u64_u32 v[4:5], s[4:5], v2, s3, v[0:1]
	ds_read_b128 v[4:7], v4
	v_add_u32_e32 v2, 0x1c00, v1
	v_ashrrev_i32_e32 v2, 5, v2
	s_waitcnt lgkmcnt(0)
	global_store_dwordx4 v[10:11], v[4:7], off
	s_nop 1
	v_mad_u64_u32 v[4:5], s[4:5], v2, s3, v[0:1]
	ds_read_b128 v[4:7], v4
	v_add_u32_e32 v1, 0x1e00, v1
	v_mad_i64_i32 v[10:11], s[4:5], v2, s97, v[8:9]
	v_ashrrev_i32_e32 v2, 5, v1
	v_mad_u64_u32 v[0:1], s[4:5], v2, s3, v[0:1]
	s_waitcnt lgkmcnt(0)
	global_store_dwordx4 v[10:11], v[4:7], off
	ds_read_b128 v[4:7], v0
	v_mad_i64_i32 v[0:1], s[4:5], v2, s97, v[8:9]
	s_waitcnt lgkmcnt(0)
	global_store_dwordx4 v[0:1], v[4:7], off

; #define MFMA16(a, b, c) __builtin_amdgcn_mfma_f32_16x16x32_bf16((a), (b), (c), 0, 0, 0)
; DI void gemm512(const u16* __restrict__ A, int lda, const u16* __restrict__ B, int ldb, int K, f32x4 (&acc)[8][4], char* smem) {
;     ...
;   for (int kt = 0; kt < nk; ++kt) {
;     const int buf = kt & 1;
;     const bool more = kt + 1 < nk;
;     char* st = smem + (buf ^ 1) * 65536 + soff;
;     const u16* An = A + (kt + 1) * 64;
;     const u16* Bn = B + (kt + 1) * 64;
;     const char* Sb = smem + buf * 65536;
; #pragma unroll
;     for (int ks = 0; ks < 2; ++ks) {
;       const int co = ((ks * 4 + fq) ^ sw) << 4;
;       bf16x8 bfr[4], af[8];
; #pragma unroll
;       for (int n = 0; n < 4; ++n) bfr[n] = *(const bf16x8*)(Sb + boff + n * 2048 + co);
; #pragma unroll
;       for (int m = 0; m < 8; ++m) af[m] = *(const bf16x8*)(Sb + aoff + m * 2048 + co);
;       __builtin_amdgcn_sched_barrier(0);
; #pragma unroll
;       for (int g = 0; g < 4; ++g) {
; #pragma unroll
;         for (int mm = 0; mm < 2; ++mm)
; #pragma unroll
;           for (int n = 0; n < 4; ++n) acc[g * 2 + mm][n] = MFMA16(af[g * 2 + mm], bfr[n], acc[g * 2 + mm][n]);
;         __builtin_amdgcn_sched_barrier(0);
;         if (more && ks == 0) {
;           __builtin_amdgcn_global_load_lds((const unsigned*)((An + (size_t)g * 64 * lda) + aov), (unsigned*)(st + g * 8192), 16, 0, 0);
;           __builtin_amdgcn_global_load_lds((const unsigned*)((Bn + (size_t)g * 64 * ldb) + bov), (unsigned*)(st + 32768 + g * 8192), 16, 0, 0);
;         }
;         __builtin_amdgcn_sched_barrier(0);
;       }
.LBB0_2026:
	s_and_b32 s24, s9, 0x10000
	s_mov_b32 s25, s24
	s_add_i32 s24, s24, 16
	v_add_u32_e32 v204, s24, v134
	v_add_u32_e32 v205, s24, v136
	v_add_u32_e32 v150, v204, v137
	v_add_u32_e32 v170, v205, v137
	ds_read_b128 v[154:157], v170
	ds_read_b128 v[138:141], v150 offset:32768
	ds_read_b128 v[142:145], v150 offset:34816
	ds_read_b128 v[146:149], v150 offset:36864
	ds_read_b128 v[150:153], v150 offset:38912
	ds_read_b128 v[158:161], v170 offset:2048
	ds_read_b128 v[162:165], v170 offset:4096
	ds_read_b128 v[166:169], v170 offset:6144
	ds_read_b128 v[176:179], v170 offset:8192
	ds_read_b128 v[180:183], v170 offset:10240
	ds_read_b128 v[222:225], v170 offset:12288
	ds_read_b128 v[226:229], v170 offset:14336
	s_waitcnt lgkmcnt(10)
	v_mfma_f32_16x16x32_bf16 v[128:131], v[154:157], v[138:141], v[128:131]
	s_waitcnt lgkmcnt(9)
	v_mfma_f32_16x16x32_bf16 v[124:127], v[154:157], v[142:145], v[124:127]
	s_waitcnt lgkmcnt(8)
	v_mfma_f32_16x16x32_bf16 v[120:123], v[154:157], v[146:149], v[120:123]
	s_waitcnt lgkmcnt(7)
	v_mfma_f32_16x16x32_bf16 v[116:119], v[154:157], v[150:153], v[116:119]
	s_waitcnt lgkmcnt(6)
	v_mfma_f32_16x16x32_bf16 v[112:115], v[158:161], v[138:141], v[112:115]
	v_mfma_f32_16x16x32_bf16 v[108:111], v[158:161], v[142:145], v[108:111]
	v_mfma_f32_16x16x32_bf16 v[104:107], v[158:161], v[146:149], v[104:107]
	v_mfma_f32_16x16x32_bf16 v[100:103], v[158:161], v[150:153], v[100:103]
	s_waitcnt lgkmcnt(5)
	v_mfma_f32_16x16x32_bf16 v[96:99], v[162:165], v[138:141], v[96:99]
	v_mfma_f32_16x16x32_bf16 v[92:95], v[162:165], v[142:145], v[92:95]
	v_mfma_f32_16x16x32_bf16 v[88:91], v[162:165], v[146:149], v[88:91]
	v_mfma_f32_16x16x32_bf16 v[84:87], v[162:165], v[150:153], v[84:87]
	s_waitcnt lgkmcnt(4)
	v_mfma_f32_16x16x32_bf16 v[80:83], v[166:169], v[138:141], v[80:83]
	v_mfma_f32_16x16x32_bf16 v[76:79], v[166:169], v[142:145], v[76:79]
	v_mfma_f32_16x16x32_bf16 v[72:75], v[166:169], v[146:149], v[72:75]
	v_mfma_f32_16x16x32_bf16 v[68:71], v[166:169], v[150:153], v[68:71]
	s_waitcnt lgkmcnt(3)
	v_mfma_f32_16x16x32_bf16 v[64:67], v[176:179], v[138:141], v[64:67]
	v_mfma_f32_16x16x32_bf16 v[60:63], v[176:179], v[142:145], v[60:63]
	v_mfma_f32_16x16x32_bf16 v[56:59], v[176:179], v[146:149], v[56:59]
	v_mfma_f32_16x16x32_bf16 v[52:55], v[176:179], v[150:153], v[52:55]
	s_waitcnt lgkmcnt(2)
	v_mfma_f32_16x16x32_bf16 v[48:51], v[180:183], v[138:141], v[48:51]
	v_mfma_f32_16x16x32_bf16 v[44:47], v[180:183], v[142:145], v[44:47]
	v_mfma_f32_16x16x32_bf16 v[40:43], v[180:183], v[146:149], v[40:43]
	v_mfma_f32_16x16x32_bf16 v[36:39], v[180:183], v[150:153], v[36:39]
	s_waitcnt lgkmcnt(1)
	v_mfma_f32_16x16x32_bf16 v[32:35], v[222:225], v[138:141], v[32:35]
	v_mfma_f32_16x16x32_bf16 v[28:31], v[222:225], v[142:145], v[28:31]
	v_mfma_f32_16x16x32_bf16 v[24:27], v[222:225], v[146:149], v[24:27]
	v_mfma_f32_16x16x32_bf16 v[20:23], v[222:225], v[150:153], v[20:23]
	s_waitcnt lgkmcnt(0)
	v_mfma_f32_16x16x32_bf16 v[16:19], v[226:229], v[138:141], v[16:19]
	v_mfma_f32_16x16x32_bf16 v[12:15], v[226:229], v[142:145], v[12:15]
	v_mfma_f32_16x16x32_bf16 v[8:11], v[226:229], v[146:149], v[8:11]
	v_mfma_f32_16x16x32_bf16 v[4:7], v[226:229], v[150:153], v[4:7]
	v_add_u32_e32 v150, v204, v2
	v_add_u32_e32 v170, v205, v2
	ds_read_b128 v[138:141], v150 offset:32768
	ds_read_b128 v[142:145], v150 offset:34816
	ds_read_b128 v[146:149], v150 offset:36864
	ds_read_b128 v[150:153], v150 offset:38912
	ds_read_b128 v[154:157], v170
	ds_read_b128 v[158:161], v170 offset:2048
	ds_read_b128 v[162:165], v170 offset:4096
	ds_read_b128 v[166:169], v170 offset:6144
	ds_read_b128 v[176:179], v170 offset:8192
	ds_read_b128 v[180:183], v170 offset:10240
	ds_read_b128 v[222:225], v170 offset:12288
	ds_read_b128 v[226:229], v170 offset:14336
	v_add_u32_e32 v172, s25, v135
	v_lshl_add_u64 v[170:171], v[132:133], 0, s[6:7]
	v_lshl_add_u64 v[200:201], v[0:1], 0, s[6:7]
	s_mov_b64 s[24:25], 0x880080
	v_lshl_add_u64 v[198:199], v[170:171], 0, s[82:83]
	v_lshl_add_u64 v[202:203], v[200:201], 0, s[24:25]
	s_waitcnt lgkmcnt(0)
	s_barrier
	v_mfma_f32_16x16x32_bf16 v[128:131], v[154:157], v[138:141], v[128:131]
	v_mfma_f32_16x16x32_bf16 v[124:127], v[154:157], v[142:145], v[124:127]
	v_mfma_f32_16x16x32_bf16 v[120:123], v[154:157], v[146:149], v[120:123]
	v_mfma_f32_16x16x32_bf16 v[116:119], v[154:157], v[150:153], v[116:119]
	v_mfma_f32_16x16x32_bf16 v[112:115], v[158:161], v[138:141], v[112:115]
	v_mfma_f32_16x16x32_bf16 v[108:111], v[158:161], v[142:145], v[108:111]
	v_mfma_f32_16x16x32_bf16 v[104:107], v[158:161], v[146:149], v[104:107]
	v_mfma_f32_16x16x32_bf16 v[100:103], v[158:161], v[150:153], v[100:103]
	v_add_u32_e32 v154, 0x8000, v172
	v_readfirstlane_b32 s24, v172
	s_mov_b32 m0, s24
	v_readfirstlane_b32 s24, v154
	global_load_lds_dwordx4 v[198:199], off
	s_mov_b32 m0, s24
	s_nop 0
	global_load_lds_dwordx4 v[202:203], off
	v_mfma_f32_16x16x32_bf16 v[96:99], v[162:165], v[138:141], v[96:99]
	v_mfma_f32_16x16x32_bf16 v[92:95], v[162:165], v[142:145], v[92:95]
	v_mfma_f32_16x16x32_bf16 v[88:91], v[162:165], v[146:149], v[88:91]
	v_mfma_f32_16x16x32_bf16 v[84:87], v[162:165], v[150:153], v[84:87]
	v_mfma_f32_16x16x32_bf16 v[80:83], v[166:169], v[138:141], v[80:83]
	v_mfma_f32_16x16x32_bf16 v[76:79], v[166:169], v[142:145], v[76:79]
	v_mfma_f32_16x16x32_bf16 v[72:75], v[166:169], v[146:149], v[72:75]
	v_mfma_f32_16x16x32_bf16 v[68:71], v[166:169], v[150:153], v[68:71]
	s_mov_b64 s[24:25], 0x8a2080
	v_add_u32_e32 v159, 0x2000, v172
	v_add_u32_e32 v158, 0xa000, v172
	v_lshl_add_u64 v[154:155], v[200:201], 0, s[24:25]
	v_readfirstlane_b32 s24, v159
	v_lshl_add_u64 v[156:157], v[170:171], 0, s[80:81]
; #define MFMA16(a, b, c) __builtin_amdgcn_mfma_f32_16x16x32_bf16((a), (b), (c), 0, 0, 0)
; DI void gemm512(const u16* __restrict__ A, int lda, const u16* __restrict__ B, int ldb, int K, f32x4 (&acc)[8][4], char* smem) {
;     ...
;   for (int kt = 0; kt < nk; ++kt) {
;     const int buf = kt & 1;
;     const bool more = kt + 1 < nk;
;     char* st = smem + (buf ^ 1) * 65536 + soff;
;     const u16* An = A + (kt + 1) * 64;
;     const u16* Bn = B + (kt + 1) * 64;
;     const char* Sb = smem + buf * 65536;
; #pragma unroll
;     for (int ks = 0; ks < 2; ++ks) {
;       const int co = ((ks * 4 + fq) ^ sw) << 4;
;       bf16x8 bfr[4], af[8];
; #pragma unroll
;       for (int n = 0; n < 4; ++n) bfr[n] = *(const bf16x8*)(Sb + boff + n * 2048 + co);
; #pragma unroll
;       for (int m = 0; m < 8; ++m) af[m] = *(const bf16x8*)(Sb + aoff + m * 2048 + co);
;       __builtin_amdgcn_sched_barrier(0);
; #pragma unroll
;       for (int g = 0; g < 4; ++g) {
; #pragma unroll
;         for (int mm = 0; mm < 2; ++mm)
; #pragma unroll
;           for (int n = 0; n < 4; ++n) acc[g * 2 + mm][n] = MFMA16(af[g * 2 + mm], bfr[n], acc[g * 2 + mm][n]);
;         __builtin_amdgcn_sched_barrier(0);
;         if (more && ks == 0) {
;           __builtin_amdgcn_global_load_lds((const unsigned*)((An + (size_t)g * 64 * lda) + aov), (unsigned*)(st + g * 8192), 16, 0, 0);
;           __builtin_amdgcn_global_load_lds((const unsigned*)((Bn + (size_t)g * 64 * ldb) + bov), (unsigned*)(st + 32768 + g * 8192), 16, 0, 0);
;         }
;         __builtin_amdgcn_sched_barrier(0);
;       }
;     }
;     asm volatile("s_waitcnt vmcnt(0) lgkmcnt(0)" ::: "memory");
;     __builtin_amdgcn_s_barrier();
;   }
	s_mov_b32 m0, s24
	v_readfirstlane_b32 s24, v158
	global_load_lds_dwordx4 v[156:157], off
	s_mov_b32 m0, s24
	s_nop 0
	global_load_lds_dwordx4 v[154:155], off
	v_mfma_f32_16x16x32_bf16 v[64:67], v[176:179], v[138:141], v[64:67]
	v_mfma_f32_16x16x32_bf16 v[60:63], v[176:179], v[142:145], v[60:63]
	v_mfma_f32_16x16x32_bf16 v[56:59], v[176:179], v[146:149], v[56:59]
	v_mfma_f32_16x16x32_bf16 v[52:55], v[176:179], v[150:153], v[52:55]
	v_mfma_f32_16x16x32_bf16 v[48:51], v[180:183], v[138:141], v[48:51]
	v_mfma_f32_16x16x32_bf16 v[44:47], v[180:183], v[142:145], v[44:47]
	v_mfma_f32_16x16x32_bf16 v[40:43], v[180:183], v[146:149], v[40:43]
	v_mfma_f32_16x16x32_bf16 v[36:39], v[180:183], v[150:153], v[36:39]
	s_mov_b64 s[24:25], 0x8c4080
	v_add_u32_e32 v159, 0x4000, v172
	v_add_u32_e32 v158, 0xc000, v172
	v_lshl_add_u64 v[154:155], v[200:201], 0, s[24:25]
	v_readfirstlane_b32 s24, v159
	v_lshl_add_u64 v[156:157], v[170:171], 0, s[86:87]
	s_mov_b32 m0, s24
	v_readfirstlane_b32 s24, v158
	global_load_lds_dwordx4 v[156:157], off
	s_mov_b32 m0, s24
	s_nop 0
	global_load_lds_dwordx4 v[154:155], off
	v_mfma_f32_16x16x32_bf16 v[32:35], v[222:225], v[138:141], v[32:35]
	v_mfma_f32_16x16x32_bf16 v[28:31], v[222:225], v[142:145], v[28:31]
	v_mfma_f32_16x16x32_bf16 v[24:27], v[222:225], v[146:149], v[24:27]
	v_mfma_f32_16x16x32_bf16 v[20:23], v[222:225], v[150:153], v[20:23]
	v_mfma_f32_16x16x32_bf16 v[16:19], v[226:229], v[138:141], v[16:19]
	v_mfma_f32_16x16x32_bf16 v[12:15], v[226:229], v[142:145], v[12:15]
	v_mfma_f32_16x16x32_bf16 v[8:11], v[226:229], v[146:149], v[8:11]
	v_mfma_f32_16x16x32_bf16 v[4:7], v[226:229], v[150:153], v[4:7]
	s_mov_b64 s[24:25], 0x8e6080
	v_add_u32_e32 v143, 0x6000, v172
	v_add_u32_e32 v142, 0xe000, v172
	v_lshl_add_u64 v[138:139], v[200:201], 0, s[24:25]
	v_readfirstlane_b32 s24, v143
	v_lshl_add_u64 v[140:141], v[170:171], 0, s[22:23]
	s_mov_b32 m0, s24
	v_readfirstlane_b32 s24, v142
	global_load_lds_dwordx4 v[140:141], off
	s_mov_b32 m0, s24
	s_nop 0
	global_load_lds_dwordx4 v[138:139], off
	s_add_i32 s9, s9, 0x10000
	s_waitcnt vmcnt(8)
	s_add_u32 s6, s6, 0x80
	s_addc_u32 s7, s7, 0
	s_cmpk_lg_i32 s6, 0x780
	s_barrier
	s_cbranch_scc1 .LBB0_2026
	s_and_b32 s24, s9, 0x10000
	s_mov_b32 s25, s24
	s_add_i32 s24, s24, 16
	v_add_u32_e32 v204, s24, v134
	v_add_u32_e32 v205, s24, v136
	v_add_u32_e32 v150, v204, v137
	v_add_u32_e32 v170, v205, v137
	ds_read_b128 v[154:157], v170
	ds_read_b128 v[138:141], v150 offset:32768
	ds_read_b128 v[142:145], v150 offset:34816
	ds_read_b128 v[146:149], v150 offset:36864
	ds_read_b128 v[150:153], v150 offset:38912
	ds_read_b128 v[158:161], v170 offset:2048
	ds_read_b128 v[162:165], v170 offset:4096
	ds_read_b128 v[166:169], v170 offset:6144
	ds_read_b128 v[176:179], v170 offset:8192
	ds_read_b128 v[180:183], v170 offset:10240
	ds_read_b128 v[222:225], v170 offset:12288
	ds_read_b128 v[226:229], v170 offset:14336
	s_waitcnt lgkmcnt(10)
	v_mfma_f32_16x16x32_bf16 v[128:131], v[154:157], v[138:141], v[128:131]
	s_waitcnt lgkmcnt(9)
	v_mfma_f32_16x16x32_bf16 v[124:127], v[154:157], v[142:145], v[124:127]
	s_waitcnt lgkmcnt(8)
	v_mfma_f32_16x16x32_bf16 v[120:123], v[154:157], v[146:149], v[120:123]
	s_waitcnt lgkmcnt(7)
	v_mfma_f32_16x16x32_bf16 v[116:119], v[154:157], v[150:153], v[116:119]
	s_waitcnt lgkmcnt(6)
	v_mfma_f32_16x16x32_bf16 v[112:115], v[158:161], v[138:141], v[112:115]
	v_mfma_f32_16x16x32_bf16 v[108:111], v[158:161], v[142:145], v[108:111]
	v_mfma_f32_16x16x32_bf16 v[104:107], v[158:161], v[146:149], v[104:107]
	v_mfma_f32_16x16x32_bf16 v[100:103], v[158:161], v[150:153], v[100:103]
	s_waitcnt lgkmcnt(5)
	v_mfma_f32_16x16x32_bf16 v[96:99], v[162:165], v[138:141], v[96:99]
	v_mfma_f32_16x16x32_bf16 v[92:95], v[162:165], v[142:145], v[92:95]
	v_mfma_f32_16x16x32_bf16 v[88:91], v[162:165], v[146:149], v[88:91]
	v_mfma_f32_16x16x32_bf16 v[84:87], v[162:165], v[150:153], v[84:87]
	s_waitcnt lgkmcnt(4)
	v_mfma_f32_16x16x32_bf16 v[80:83], v[166:169], v[138:141], v[80:83]
	v_mfma_f32_16x16x32_bf16 v[76:79], v[166:169], v[142:145], v[76:79]
	v_mfma_f32_16x16x32_bf16 v[72:75], v[166:169], v[146:149], v[72:75]
	v_mfma_f32_16x16x32_bf16 v[68:71], v[166:169], v[150:153], v[68:71]
	s_waitcnt lgkmcnt(3)
	v_mfma_f32_16x16x32_bf16 v[64:67], v[176:179], v[138:141], v[64:67]
	v_mfma_f32_16x16x32_bf16 v[60:63], v[176:179], v[142:145], v[60:63]
	v_mfma_f32_16x16x32_bf16 v[56:59], v[176:179], v[146:149], v[56:59]
	v_mfma_f32_16x16x32_bf16 v[52:55], v[176:179], v[150:153], v[52:55]
	s_waitcnt lgkmcnt(2)
	v_mfma_f32_16x16x32_bf16 v[48:51], v[180:183], v[138:141], v[48:51]
	v_mfma_f32_16x16x32_bf16 v[44:47], v[180:183], v[142:145], v[44:47]
	v_mfma_f32_16x16x32_bf16 v[40:43], v[180:183], v[146:149], v[40:43]
	v_mfma_f32_16x16x32_bf16 v[36:39], v[180:183], v[150:153], v[36:39]
	s_waitcnt lgkmcnt(1)
	v_mfma_f32_16x16x32_bf16 v[32:35], v[222:225], v[138:141], v[32:35]
	v_mfma_f32_16x16x32_bf16 v[28:31], v[222:225], v[142:145], v[28:31]
	v_mfma_f32_16x16x32_bf16 v[24:27], v[222:225], v[146:149], v[24:27]
	v_mfma_f32_16x16x32_bf16 v[20:23], v[222:225], v[150:153], v[20:23]
	s_waitcnt lgkmcnt(0)
	v_mfma_f32_16x16x32_bf16 v[16:19], v[226:229], v[138:141], v[16:19]
	v_mfma_f32_16x16x32_bf16 v[12:15], v[226:229], v[142:145], v[12:15]
	v_mfma_f32_16x16x32_bf16 v[8:11], v[226:229], v[146:149], v[8:11]
	v_mfma_f32_16x16x32_bf16 v[4:7], v[226:229], v[150:153], v[4:7]
	v_add_u32_e32 v150, v204, v2
	v_add_u32_e32 v170, v205, v2
	ds_read_b128 v[154:157], v170
	ds_read_b128 v[138:141], v150 offset:32768
	ds_read_b128 v[142:145], v150 offset:34816
	ds_read_b128 v[146:149], v150 offset:36864
	ds_read_b128 v[150:153], v150 offset:38912
	ds_read_b128 v[158:161], v170 offset:2048
	ds_read_b128 v[162:165], v170 offset:4096
	ds_read_b128 v[166:169], v170 offset:6144
	ds_read_b128 v[176:179], v170 offset:8192
	ds_read_b128 v[180:183], v170 offset:10240
	ds_read_b128 v[222:225], v170 offset:12288
	ds_read_b128 v[226:229], v170 offset:14336
	s_waitcnt lgkmcnt(10)
; #define MFMA16(a, b, c) __builtin_amdgcn_mfma_f32_16x16x32_bf16((a), (b), (c), 0, 0, 0)
; DI void gemm512(const u16* __restrict__ A, int lda, const u16* __restrict__ B, int ldb, int K, f32x4 (&acc)[8][4], char* smem) {
;     ...
; #pragma unroll
;     for (int ks = 0; ks < 2; ++ks) {
;       const int co = ((ks * 4 + fq) ^ sw) << 4;
;       bf16x8 bfr[4], af[8];
; #pragma unroll
;       for (int n = 0; n < 4; ++n) bfr[n] = *(const bf16x8*)(Sb + boff + n * 2048 + co);
; #pragma unroll
;       for (int m = 0; m < 8; ++m) af[m] = *(const bf16x8*)(Sb + aoff + m * 2048 + co);
;       __builtin_amdgcn_sched_barrier(0);
; #pragma unroll
;       for (int g = 0; g < 4; ++g) {
; #pragma unroll
;         for (int mm = 0; mm < 2; ++mm)
; #pragma unroll
;           for (int n = 0; n < 4; ++n) acc[g * 2 + mm][n] = MFMA16(af[g * 2 + mm], bfr[n], acc[g * 2 + mm][n]);
;         __builtin_amdgcn_sched_barrier(0);
;         if (more && ks == 0) {
;           __builtin_amdgcn_global_load_lds((const unsigned*)((An + (size_t)g * 64 * lda) + aov), (unsigned*)(st + g * 8192), 16, 0, 0);
;           __builtin_amdgcn_global_load_lds((const unsigned*)((Bn + (size_t)g * 64 * ldb) + bov), (unsigned*)(st + 32768 + g * 8192), 16, 0, 0);
;         }
;         __builtin_amdgcn_sched_barrier(0);
;       }
;     }
;     asm volatile("s_waitcnt vmcnt(0) lgkmcnt(0)" ::: "memory");
;     __builtin_amdgcn_s_barrier();
;   }
	v_mfma_f32_16x16x32_bf16 v[128:131], v[154:157], v[138:141], v[128:131]
	s_waitcnt lgkmcnt(9)
	v_mfma_f32_16x16x32_bf16 v[124:127], v[154:157], v[142:145], v[124:127]
	s_waitcnt lgkmcnt(8)
	v_mfma_f32_16x16x32_bf16 v[120:123], v[154:157], v[146:149], v[120:123]
	s_waitcnt lgkmcnt(7)
	v_mfma_f32_16x16x32_bf16 v[116:119], v[154:157], v[150:153], v[116:119]
	s_waitcnt lgkmcnt(6)
	v_mfma_f32_16x16x32_bf16 v[112:115], v[158:161], v[138:141], v[112:115]
	v_mfma_f32_16x16x32_bf16 v[108:111], v[158:161], v[142:145], v[108:111]
	v_mfma_f32_16x16x32_bf16 v[104:107], v[158:161], v[146:149], v[104:107]
	v_mfma_f32_16x16x32_bf16 v[100:103], v[158:161], v[150:153], v[100:103]
	s_waitcnt lgkmcnt(5)
	v_mfma_f32_16x16x32_bf16 v[96:99], v[162:165], v[138:141], v[96:99]
	v_mfma_f32_16x16x32_bf16 v[92:95], v[162:165], v[142:145], v[92:95]
	v_mfma_f32_16x16x32_bf16 v[88:91], v[162:165], v[146:149], v[88:91]
	v_mfma_f32_16x16x32_bf16 v[84:87], v[162:165], v[150:153], v[84:87]
	s_waitcnt lgkmcnt(4)
	v_mfma_f32_16x16x32_bf16 v[80:83], v[166:169], v[138:141], v[80:83]
	v_mfma_f32_16x16x32_bf16 v[76:79], v[166:169], v[142:145], v[76:79]
	v_mfma_f32_16x16x32_bf16 v[72:75], v[166:169], v[146:149], v[72:75]
	v_mfma_f32_16x16x32_bf16 v[68:71], v[166:169], v[150:153], v[68:71]
	s_waitcnt lgkmcnt(3)
	v_mfma_f32_16x16x32_bf16 v[64:67], v[176:179], v[138:141], v[64:67]
	v_mfma_f32_16x16x32_bf16 v[60:63], v[176:179], v[142:145], v[60:63]
	v_mfma_f32_16x16x32_bf16 v[56:59], v[176:179], v[146:149], v[56:59]
	v_mfma_f32_16x16x32_bf16 v[52:55], v[176:179], v[150:153], v[52:55]
	s_waitcnt lgkmcnt(2)
	v_mfma_f32_16x16x32_bf16 v[48:51], v[180:183], v[138:141], v[48:51]
	v_mfma_f32_16x16x32_bf16 v[44:47], v[180:183], v[142:145], v[44:47]
	v_mfma_f32_16x16x32_bf16 v[40:43], v[180:183], v[146:149], v[40:43]
	v_mfma_f32_16x16x32_bf16 v[36:39], v[180:183], v[150:153], v[36:39]
	s_waitcnt lgkmcnt(1)
	v_mfma_f32_16x16x32_bf16 v[32:35], v[222:225], v[138:141], v[32:35]
	v_mfma_f32_16x16x32_bf16 v[28:31], v[222:225], v[142:145], v[28:31]
	v_mfma_f32_16x16x32_bf16 v[24:27], v[222:225], v[146:149], v[24:27]
	v_mfma_f32_16x16x32_bf16 v[20:23], v[222:225], v[150:153], v[20:23]
	s_waitcnt lgkmcnt(0)
	v_mfma_f32_16x16x32_bf16 v[16:19], v[226:229], v[138:141], v[16:19]
	v_mfma_f32_16x16x32_bf16 v[12:15], v[226:229], v[142:145], v[12:15]
	v_mfma_f32_16x16x32_bf16 v[8:11], v[226:229], v[146:149], v[8:11]
	v_mfma_f32_16x16x32_bf16 v[4:7], v[226:229], v[150:153], v[4:7]
	s_waitcnt vmcnt(0)
	s_barrier
	s_add_i32 s6, 16, 0x10000
	v_add_u32_e32 v0, s6, v134
	v_add_u32_e32 v1, s6, v136
	v_add_u32_e32 v136, v0, v137
	ds_read_b128 v[132:135], v136 offset:32768
	ds_read_b128 v[138:141], v136 offset:34816
	ds_read_b128 v[142:145], v136 offset:36864
	ds_read_b128 v[146:149], v136 offset:38912
	v_add_u32_e32 v136, v1, v137
	ds_read_b128 v[150:153], v136
	ds_read_b128 v[154:157], v136 offset:2048
	ds_read_b128 v[158:161], v136 offset:4096
	ds_read_b128 v[162:165], v136 offset:6144
	ds_read_b128 v[166:169], v136 offset:8192
	ds_read_b128 v[176:179], v136 offset:10240
	ds_read_b128 v[180:183], v136 offset:12288
	ds_read_b128 v[222:225], v136 offset:14336
	s_waitcnt lgkmcnt(7)
	v_mfma_f32_16x16x32_bf16 v[128:131], v[150:153], v[132:135], v[128:131]
	v_mfma_f32_16x16x32_bf16 v[124:127], v[150:153], v[138:141], v[124:127]
	v_mfma_f32_16x16x32_bf16 v[120:123], v[150:153], v[142:145], v[120:123]
	v_mfma_f32_16x16x32_bf16 v[116:119], v[150:153], v[146:149], v[116:119]
	s_waitcnt lgkmcnt(6)
	v_mfma_f32_16x16x32_bf16 v[112:115], v[154:157], v[132:135], v[112:115]
	v_mfma_f32_16x16x32_bf16 v[108:111], v[154:157], v[138:141], v[108:111]
	v_mfma_f32_16x16x32_bf16 v[104:107], v[154:157], v[142:145], v[104:107]
	v_mfma_f32_16x16x32_bf16 v[100:103], v[154:157], v[146:149], v[100:103]
	s_waitcnt lgkmcnt(5)
	v_mfma_f32_16x16x32_bf16 v[84:87], v[158:161], v[146:149], v[84:87]
	s_waitcnt lgkmcnt(4)
	v_mfma_f32_16x16x32_bf16 v[80:83], v[162:165], v[132:135], v[80:83]
	v_mfma_f32_16x16x32_bf16 v[76:79], v[162:165], v[138:141], v[76:79]
	v_mfma_f32_16x16x32_bf16 v[72:75], v[162:165], v[142:145], v[72:75]
	v_mfma_f32_16x16x32_bf16 v[68:71], v[162:165], v[146:149], v[68:71]
	v_mfma_f32_16x16x32_bf16 v[150:153], v[158:161], v[132:135], v[96:99]
	v_mfma_f32_16x16x32_bf16 v[154:157], v[158:161], v[138:141], v[92:95]
	v_mfma_f32_16x16x32_bf16 v[226:229], v[158:161], v[142:145], v[88:91]
	s_waitcnt lgkmcnt(2)
	v_mfma_f32_16x16x32_bf16 v[44:47], v[176:179], v[138:141], v[44:47]
	v_mfma_f32_16x16x32_bf16 v[40:43], v[176:179], v[142:145], v[40:43]
	v_mfma_f32_16x16x32_bf16 v[36:39], v[176:179], v[146:149], v[36:39]
	v_mfma_f32_16x16x32_bf16 v[158:161], v[166:169], v[132:135], v[64:67]
	v_mfma_f32_16x16x32_bf16 v[162:165], v[166:169], v[138:141], v[60:63]
	v_mfma_f32_16x16x32_bf16 v[230:233], v[166:169], v[142:145], v[56:59]
	v_mfma_f32_16x16x32_bf16 v[166:169], v[166:169], v[146:149], v[52:55]
	v_mfma_f32_16x16x32_bf16 v[234:237], v[176:179], v[132:135], v[48:51]
	s_waitcnt lgkmcnt(1)
	v_mfma_f32_16x16x32_bf16 v[176:179], v[180:183], v[132:135], v[32:35]
	s_waitcnt lgkmcnt(0)
	v_mfma_f32_16x16x32_bf16 v[132:135], v[222:225], v[132:135], v[16:19]
	v_mfma_f32_16x16x32_bf16 v[4:7], v[222:225], v[146:149], v[4:7]
	v_mfma_f32_16x16x32_bf16 v[238:241], v[180:183], v[138:141], v[28:31]
	v_mfma_f32_16x16x32_bf16 v[242:245], v[180:183], v[142:145], v[24:27]
	v_mfma_f32_16x16x32_bf16 v[180:183], v[180:183], v[146:149], v[20:23]
	v_mfma_f32_16x16x32_bf16 v[136:139], v[222:225], v[138:141], v[12:15]
	v_mfma_f32_16x16x32_bf16 v[140:143], v[222:225], v[142:145], v[8:11]
	v_add_u32_e32 v0, v0, v2
	ds_read_b128 v[144:147], v0 offset:32768
	ds_read_b128 v[222:225], v0 offset:34816
	ds_read_b128 v[246:249], v0 offset:36864
	ds_read_b128 v[198:201], v0 offset:38912
	v_add_u32_e32 v0, v1, v2
	ds_read_b128 v[8:11], v0
	ds_read_b128 v[12:15], v0 offset:2048
	ds_read_b128 v[16:19], v0 offset:4096
	ds_read_b128 v[20:23], v0 offset:6144
	ds_read_b128 v[206:209], v0 offset:8192
	ds_read_b128 v[202:205], v0 offset:10240
	ds_read_b128 v[214:217], v0 offset:12288
	ds_read_b128 v[218:221], v0 offset:14336
	s_waitcnt lgkmcnt(7)
; DI int TID512() { int t = threadIdx.x; asm volatile("" : "+v"(t)); return t; }
; DI void img_load_bf16(const u16* src, int ld, char* smem, int nrows, int rowoff) {
;   for (int slot = TID512(); slot < nrows * 32; slot += 512) {
;     const int row = slot >> 5, c16 = slot & 31;
;     *(u32x4*)(smem + (row + rowoff) * (IMG_LD * 2) + c16 * 16) = __builtin_nontemporal_load((const u32x4*)(src + (size_t)row * ld + c16 * 8));
;   }
; }
; DI void gate_tile(const Params& p, int l, int mt, int nt, char* smem) {
;     ...
;   EPI_IDS;
;   u16* Y = (u16*)(p.ws + O_YP) + (size_t)row0 * 3072 + col0;
;   const float* bm = p.in[26] + (size_t)l * 3072 + col0 + wc * 64 + fr;
;   img_load_bf16(Y, 3072, smem, 256, 0);
	v_mfma_f32_16x16x32_bf16 v[128:131], v[8:11], v[144:147], v[128:131]
	v_mfma_f32_16x16x32_bf16 v[96:99], v[8:11], v[222:225], v[124:127]
	v_mfma_f32_16x16x32_bf16 v[64:67], v[8:11], v[246:249], v[120:123]
	v_mfma_f32_16x16x32_bf16 v[32:35], v[8:11], v[198:201], v[116:119]
	s_waitcnt lgkmcnt(6)
	v_mfma_f32_16x16x32_bf16 v[124:127], v[12:15], v[144:147], v[112:115]
	v_mfma_f32_16x16x32_bf16 v[92:95], v[12:15], v[222:225], v[108:111]
	v_mfma_f32_16x16x32_bf16 v[60:63], v[12:15], v[246:249], v[104:107]
	v_mfma_f32_16x16x32_bf16 v[28:31], v[12:15], v[198:201], v[100:103]
	s_waitcnt lgkmcnt(5)
	v_mfma_f32_16x16x32_bf16 v[120:123], v[16:19], v[144:147], v[150:153]
	v_mfma_f32_16x16x32_bf16 v[88:91], v[16:19], v[222:225], v[154:157]
	v_mfma_f32_16x16x32_bf16 v[56:59], v[16:19], v[246:249], v[226:229]
	v_mfma_f32_16x16x32_bf16 v[24:27], v[16:19], v[198:201], v[84:87]
	s_waitcnt lgkmcnt(4)
	v_mfma_f32_16x16x32_bf16 v[116:119], v[20:23], v[144:147], v[80:83]
	v_mfma_f32_16x16x32_bf16 v[84:87], v[20:23], v[222:225], v[76:79]
	v_mfma_f32_16x16x32_bf16 v[52:55], v[20:23], v[246:249], v[72:75]
	v_mfma_f32_16x16x32_bf16 v[20:23], v[20:23], v[198:201], v[68:71]
	s_waitcnt lgkmcnt(3)
	v_mfma_f32_16x16x32_bf16 v[112:115], v[206:209], v[144:147], v[158:161]
	v_mfma_f32_16x16x32_bf16 v[80:83], v[206:209], v[222:225], v[162:165]
	v_mfma_f32_16x16x32_bf16 v[48:51], v[206:209], v[246:249], v[230:233]
	v_mfma_f32_16x16x32_bf16 v[16:19], v[206:209], v[198:201], v[166:169]
	s_waitcnt lgkmcnt(2)
	v_mfma_f32_16x16x32_bf16 v[108:111], v[202:205], v[144:147], v[234:237]
	v_mfma_f32_16x16x32_bf16 v[76:79], v[202:205], v[222:225], v[44:47]
	v_mfma_f32_16x16x32_bf16 v[44:47], v[202:205], v[246:249], v[40:43]
	v_mfma_f32_16x16x32_bf16 v[12:15], v[202:205], v[198:201], v[36:39]
	s_waitcnt lgkmcnt(1)
	v_mfma_f32_16x16x32_bf16 v[104:107], v[214:217], v[144:147], v[176:179]
	v_mfma_f32_16x16x32_bf16 v[72:75], v[214:217], v[222:225], v[238:241]
	v_mfma_f32_16x16x32_bf16 v[40:43], v[214:217], v[246:249], v[242:245]
	v_mfma_f32_16x16x32_bf16 v[8:11], v[214:217], v[198:201], v[180:183]
	s_waitcnt lgkmcnt(0)
	v_mfma_f32_16x16x32_bf16 v[100:103], v[218:221], v[144:147], v[132:135]
	v_mfma_f32_16x16x32_bf16 v[68:71], v[218:221], v[222:225], v[136:139]
	v_mfma_f32_16x16x32_bf16 v[36:39], v[218:221], v[246:249], v[140:143]
	v_mfma_f32_16x16x32_bf16 v[4:7], v[218:221], v[198:201], v[4:7]
	s_mul_i32 s7, s8, 0x1800
	s_mul_hi_i32 s6, s8, 0x1800
	s_add_u32 s8, s88, s7
	s_waitcnt vmcnt(0) lgkmcnt(0)
	s_addc_u32 s9, s89, s6
	s_lshl_b64 s[6:7], s[4:5], 1
	v_mov_b32_e32 v132, v184
	s_add_u32 s38, s8, s6
	v_mov_b32_e32 v133, v184
	s_movk_i32 s6, 0x2000
	s_barrier
	s_addc_u32 s39, s9, s7
	s_nop 0
	v_cmp_gt_i32_e32 vcc, s6, v133
	s_and_saveexec_b64 s[6:7], vcc
	s_cbranch_execz .LBB0_2020
	v_lshlrev_b32_e32 v0, 4, v133
	v_and_b32_e32 v172, 0x1f0, v0
	v_lshl_add_u64 v[0:1], s[38:39], 0, v[172:173]
	v_add_u32_e32 v2, 16, v172
	s_mov_b64 s[8:9], 0
	s_lshl_b64 s[36:37], s[4:5], 2
	s_add_u32 s36, s12, s36
	s_addc_u32 s37, s13, s37
	v_and_b32_e32 v230, 0xc0, v132
	v_lshlrev_b32_e32 v230, 2, v230
	v_and_b32_e32 v231, 15, v132
	v_lshl_add_u32 v230, v231, 2, v230
	global_load_dword v226, v230, s[36:37]
	global_load_dword v227, v230, s[36:37] offset:64
	global_load_dword v228, v230, s[36:37] offset:128
	global_load_dword v229, v230, s[36:37] offset:192
.LBB0_2029:
	v_ashrrev_i32_e32 v138, 5, v133
	v_mad_i64_i32 v[134:135], s[24:25], v138, s97, v[0:1]
	v_mad_u64_u32 v[138:139], s[24:25], v138, s3, v[2:3]
	s_lshl_b32 s34, s97, 4
	s_mov_b32 s35, 0
	s_lshl_b32 s32, s3, 4
	global_load_dwordx4 v[140:143], v[134:135], off nt
	v_lshl_add_u64 v[134:135], v[134:135], 0, s[34:35]
	global_load_dwordx4 v[144:147], v[134:135], off nt
	v_lshl_add_u64 v[134:135], v[134:135], 0, s[34:35]
	global_load_dwordx4 v[148:151], v[134:135], off nt
	v_lshl_add_u64 v[134:135], v[134:135], 0, s[34:35]
	global_load_dwordx4 v[152:155], v[134:135], off nt
	v_lshl_add_u64 v[134:135], v[134:135], 0, s[34:35]
	global_load_dwordx4 v[156:159], v[134:135], off nt
	v_lshl_add_u64 v[134:135], v[134:135], 0, s[34:35]
	global_load_dwordx4 v[160:163], v[134:135], off nt
	v_lshl_add_u64 v[134:135], v[134:135], 0, s[34:35]
	global_load_dwordx4 v[164:167], v[134:135], off nt
	v_lshl_add_u64 v[134:135], v[134:135], 0, s[34:35]
	global_load_dwordx4 v[168:171], v[134:135], off nt
	v_lshl_add_u64 v[134:135], v[134:135], 0, s[34:35]
	global_load_dwordx4 v[176:179], v[134:135], off nt
	v_lshl_add_u64 v[134:135], v[134:135], 0, s[34:35]
	global_load_dwordx4 v[180:183], v[134:135], off nt
	v_lshl_add_u64 v[134:135], v[134:135], 0, s[34:35]
	global_load_dwordx4 v[198:201], v[134:135], off nt
	v_lshl_add_u64 v[134:135], v[134:135], 0, s[34:35]
	global_load_dwordx4 v[202:205], v[134:135], off nt
	v_lshl_add_u64 v[134:135], v[134:135], 0, s[34:35]
	global_load_dwordx4 v[206:209], v[134:135], off nt
	v_lshl_add_u64 v[134:135], v[134:135], 0, s[34:35]
	global_load_dwordx4 v[214:217], v[134:135], off nt
	v_lshl_add_u64 v[134:135], v[134:135], 0, s[34:35]
	global_load_dwordx4 v[218:221], v[134:135], off nt
	v_lshl_add_u64 v[134:135], v[134:135], 0, s[34:35]
	global_load_dwordx4 v[222:225], v[134:135], off nt
	v_lshl_add_u64 v[134:135], v[134:135], 0, s[34:35]
	s_waitcnt vmcnt(16)
; DI float bf2f(u16 h) { return __uint_as_float(((unsigned)h) << 16); }
; DI float sigmoidf_(float x) { return __builtin_amdgcn_rcpf(1.f + __expf(-x)); }
; DI void gate_tile(const Params& p, int l, int mt, int nt, char* smem) {
;     ...
;   for (int n = 0; n < 4; ++n) {
;     const float bv = bm[n * 16];
; #pragma unroll
;     for (int m = 0; m < 8; ++m)
; #pragma unroll
;       for (int j = 0; j < 4; ++j) {
;         u16* q = img + (m * 16 + j) * IMG_LD + n * 16;
;         *q = f2bf(sigmoidf_(acc[m][n][j] + bv) * bf2f(*q));
	v_add_f32_e32 v128, v128, v226
	v_add_f32_e32 v129, v129, v226
	v_add_f32_e32 v130, v130, v226
	v_add_f32_e32 v131, v131, v226
	v_mul_f32_e32 v128, 0xbfb8aa3b, v128
	v_mul_f32_e32 v129, 0xbfb8aa3b, v129
	v_mul_f32_e32 v130, 0xbfb8aa3b, v130
	v_mul_f32_e32 v131, 0xbfb8aa3b, v131
	v_exp_f32_e32 v128, v128
	v_exp_f32_e32 v129, v129
	v_exp_f32_e32 v130, v130
	v_exp_f32_e32 v131, v131
	v_add_f32_e32 v128, 1.0, v128
	v_add_f32_e32 v129, 1.0, v129
	v_add_f32_e32 v130, 1.0, v130
	v_add_f32_e32 v131, 1.0, v131
	v_rcp_f32_e32 v128, v128
	v_rcp_f32_e32 v129, v129
	v_rcp_f32_e32 v130, v130
	v_rcp_f32_e32 v131, v131
	v_add_f32_e32 v124, v124, v226
	v_add_f32_e32 v125, v125, v226
	v_add_f32_e32 v126, v126, v226
	v_add_f32_e32 v127, v127, v226
	v_mul_f32_e32 v124, 0xbfb8aa3b, v124
	v_mul_f32_e32 v125, 0xbfb8aa3b, v125
	v_mul_f32_e32 v126, 0xbfb8aa3b, v126
	v_mul_f32_e32 v127, 0xbfb8aa3b, v127
	v_exp_f32_e32 v124, v124
	v_exp_f32_e32 v125, v125
	v_exp_f32_e32 v126, v126
	v_exp_f32_e32 v127, v127
	v_add_f32_e32 v124, 1.0, v124
	v_add_f32_e32 v125, 1.0, v125
	v_add_f32_e32 v126, 1.0, v126
	v_add_f32_e32 v127, 1.0, v127
	v_rcp_f32_e32 v124, v124
	v_rcp_f32_e32 v125, v125
	v_rcp_f32_e32 v126, v126
	v_rcp_f32_e32 v127, v127
	v_add_f32_e32 v120, v120, v226
	v_add_f32_e32 v121, v121, v226
	v_add_f32_e32 v122, v122, v226
	v_add_f32_e32 v123, v123, v226
	v_mul_f32_e32 v120, 0xbfb8aa3b, v120
	v_mul_f32_e32 v121, 0xbfb8aa3b, v121
	v_mul_f32_e32 v122, 0xbfb8aa3b, v122
	v_mul_f32_e32 v123, 0xbfb8aa3b, v123
	v_exp_f32_e32 v120, v120
	v_exp_f32_e32 v121, v121
	v_exp_f32_e32 v122, v122
	v_exp_f32_e32 v123, v123
	v_add_f32_e32 v120, 1.0, v120
	v_add_f32_e32 v121, 1.0, v121
	v_add_f32_e32 v122, 1.0, v122
	v_add_f32_e32 v123, 1.0, v123
	v_rcp_f32_e32 v120, v120
	v_rcp_f32_e32 v121, v121
	v_rcp_f32_e32 v122, v122
	v_rcp_f32_e32 v123, v123
	v_add_f32_e32 v116, v116, v226
	v_add_f32_e32 v117, v117, v226
	v_add_f32_e32 v118, v118, v226
	v_add_f32_e32 v119, v119, v226
	v_mul_f32_e32 v116, 0xbfb8aa3b, v116
	v_mul_f32_e32 v117, 0xbfb8aa3b, v117
	v_mul_f32_e32 v118, 0xbfb8aa3b, v118
	v_mul_f32_e32 v119, 0xbfb8aa3b, v119
	v_exp_f32_e32 v116, v116
	v_exp_f32_e32 v117, v117
	v_exp_f32_e32 v118, v118
	v_exp_f32_e32 v119, v119
	v_add_f32_e32 v116, 1.0, v116
	v_add_f32_e32 v117, 1.0, v117
	v_add_f32_e32 v118, 1.0, v118
	v_add_f32_e32 v119, 1.0, v119
	v_rcp_f32_e32 v116, v116
	v_rcp_f32_e32 v117, v117
	v_rcp_f32_e32 v118, v118
	v_rcp_f32_e32 v119, v119
	v_add_f32_e32 v112, v112, v226
	v_add_f32_e32 v113, v113, v226
	v_add_f32_e32 v114, v114, v226
	v_add_f32_e32 v115, v115, v226
	v_mul_f32_e32 v112, 0xbfb8aa3b, v112
	v_mul_f32_e32 v113, 0xbfb8aa3b, v113
	v_mul_f32_e32 v114, 0xbfb8aa3b, v114
	v_mul_f32_e32 v115, 0xbfb8aa3b, v115
	v_exp_f32_e32 v112, v112
	v_exp_f32_e32 v113, v113
	v_exp_f32_e32 v114, v114
	v_exp_f32_e32 v115, v115
	v_add_f32_e32 v112, 1.0, v112
	v_add_f32_e32 v113, 1.0, v113
	v_add_f32_e32 v114, 1.0, v114
	v_add_f32_e32 v115, 1.0, v115
	v_rcp_f32_e32 v112, v112
	v_rcp_f32_e32 v113, v113
	v_rcp_f32_e32 v114, v114
	v_rcp_f32_e32 v115, v115
	v_add_f32_e32 v108, v108, v226
	v_add_f32_e32 v109, v109, v226
	v_add_f32_e32 v110, v110, v226
	v_add_f32_e32 v111, v111, v226
	v_mul_f32_e32 v108, 0xbfb8aa3b, v108
	v_mul_f32_e32 v109, 0xbfb8aa3b, v109
	v_mul_f32_e32 v110, 0xbfb8aa3b, v110
	v_mul_f32_e32 v111, 0xbfb8aa3b, v111
	v_exp_f32_e32 v108, v108
	v_exp_f32_e32 v109, v109
	v_exp_f32_e32 v110, v110
	v_exp_f32_e32 v111, v111
	v_add_f32_e32 v108, 1.0, v108
	v_add_f32_e32 v109, 1.0, v109
	v_add_f32_e32 v110, 1.0, v110
	v_add_f32_e32 v111, 1.0, v111
	v_rcp_f32_e32 v108, v108
	v_rcp_f32_e32 v109, v109
	v_rcp_f32_e32 v110, v110
	v_rcp_f32_e32 v111, v111
	v_add_f32_e32 v104, v104, v226
	v_add_f32_e32 v105, v105, v226
	v_add_f32_e32 v106, v106, v226
	v_add_f32_e32 v107, v107, v226
	v_mul_f32_e32 v104, 0xbfb8aa3b, v104
	v_mul_f32_e32 v105, 0xbfb8aa3b, v105
	v_mul_f32_e32 v106, 0xbfb8aa3b, v106
	v_mul_f32_e32 v107, 0xbfb8aa3b, v107
	v_exp_f32_e32 v104, v104
	v_exp_f32_e32 v105, v105
	v_exp_f32_e32 v106, v106
	v_exp_f32_e32 v107, v107
	v_add_f32_e32 v104, 1.0, v104
	v_add_f32_e32 v105, 1.0, v105
	v_add_f32_e32 v106, 1.0, v106
	v_add_f32_e32 v107, 1.0, v107
	v_rcp_f32_e32 v104, v104
	v_rcp_f32_e32 v105, v105
	v_rcp_f32_e32 v106, v106
	v_rcp_f32_e32 v107, v107
	v_add_f32_e32 v100, v100, v226
	v_add_f32_e32 v101, v101, v226
	v_add_f32_e32 v102, v102, v226
	v_add_f32_e32 v103, v103, v226
	v_mul_f32_e32 v100, 0xbfb8aa3b, v100
	v_mul_f32_e32 v101, 0xbfb8aa3b, v101
	v_mul_f32_e32 v102, 0xbfb8aa3b, v102
	v_mul_f32_e32 v103, 0xbfb8aa3b, v103
	v_exp_f32_e32 v100, v100
	v_exp_f32_e32 v101, v101
	v_exp_f32_e32 v102, v102
	v_exp_f32_e32 v103, v103
	v_add_f32_e32 v100, 1.0, v100
	v_add_f32_e32 v101, 1.0, v101
	v_add_f32_e32 v102, 1.0, v102
	v_add_f32_e32 v103, 1.0, v103
	v_rcp_f32_e32 v100, v100
	v_rcp_f32_e32 v101, v101
	v_rcp_f32_e32 v102, v102
	v_rcp_f32_e32 v103, v103
	v_add_f32_e32 v96, v96, v227
	v_add_f32_e32 v97, v97, v227
	v_add_f32_e32 v98, v98, v227
	v_add_f32_e32 v99, v99, v227
	v_mul_f32_e32 v96, 0xbfb8aa3b, v96
	v_mul_f32_e32 v97, 0xbfb8aa3b, v97
	v_mul_f32_e32 v98, 0xbfb8aa3b, v98
	v_mul_f32_e32 v99, 0xbfb8aa3b, v99
	v_exp_f32_e32 v96, v96
	v_exp_f32_e32 v97, v97
	v_exp_f32_e32 v98, v98
	v_exp_f32_e32 v99, v99
	v_add_f32_e32 v96, 1.0, v96
	v_add_f32_e32 v97, 1.0, v97
	v_add_f32_e32 v98, 1.0, v98
	v_add_f32_e32 v99, 1.0, v99
	v_rcp_f32_e32 v96, v96
	v_rcp_f32_e32 v97, v97
	v_rcp_f32_e32 v98, v98
	v_rcp_f32_e32 v99, v99
	v_add_f32_e32 v92, v92, v227
	v_add_f32_e32 v93, v93, v227
	v_add_f32_e32 v94, v94, v227
	v_add_f32_e32 v95, v95, v227
	v_mul_f32_e32 v92, 0xbfb8aa3b, v92
; DI float bf2f(u16 h) { return __uint_as_float(((unsigned)h) << 16); }
; DI float sigmoidf_(float x) { return __builtin_amdgcn_rcpf(1.f + __expf(-x)); }
; DI void gate_tile(const Params& p, int l, int mt, int nt, char* smem) {
;     ...
;   for (int n = 0; n < 4; ++n) {
;     const float bv = bm[n * 16];
; #pragma unroll
;     for (int m = 0; m < 8; ++m)
; #pragma unroll
;       for (int j = 0; j < 4; ++j) {
;         u16* q = img + (m * 16 + j) * IMG_LD + n * 16;
;         *q = f2bf(sigmoidf_(acc[m][n][j] + bv) * bf2f(*q));
	v_mul_f32_e32 v93, 0xbfb8aa3b, v93
	v_mul_f32_e32 v94, 0xbfb8aa3b, v94
	v_mul_f32_e32 v95, 0xbfb8aa3b, v95
	v_exp_f32_e32 v92, v92
	v_exp_f32_e32 v93, v93
	v_exp_f32_e32 v94, v94
	v_exp_f32_e32 v95, v95
	v_add_f32_e32 v92, 1.0, v92
	v_add_f32_e32 v93, 1.0, v93
	v_add_f32_e32 v94, 1.0, v94
	v_add_f32_e32 v95, 1.0, v95
	v_rcp_f32_e32 v92, v92
	v_rcp_f32_e32 v93, v93
	v_rcp_f32_e32 v94, v94
	v_rcp_f32_e32 v95, v95
	v_add_f32_e32 v88, v88, v227
	v_add_f32_e32 v89, v89, v227
	v_add_f32_e32 v90, v90, v227
	v_add_f32_e32 v91, v91, v227
	v_mul_f32_e32 v88, 0xbfb8aa3b, v88
	v_mul_f32_e32 v89, 0xbfb8aa3b, v89
	v_mul_f32_e32 v90, 0xbfb8aa3b, v90
	v_mul_f32_e32 v91, 0xbfb8aa3b, v91
	v_exp_f32_e32 v88, v88
	v_exp_f32_e32 v89, v89
	v_exp_f32_e32 v90, v90
	v_exp_f32_e32 v91, v91
	v_add_f32_e32 v88, 1.0, v88
	v_add_f32_e32 v89, 1.0, v89
	v_add_f32_e32 v90, 1.0, v90
	v_add_f32_e32 v91, 1.0, v91
	v_rcp_f32_e32 v88, v88
	v_rcp_f32_e32 v89, v89
	v_rcp_f32_e32 v90, v90
	v_rcp_f32_e32 v91, v91
	v_add_f32_e32 v84, v84, v227
	v_add_f32_e32 v85, v85, v227
	v_add_f32_e32 v86, v86, v227
	v_add_f32_e32 v87, v87, v227
	v_mul_f32_e32 v84, 0xbfb8aa3b, v84
	v_mul_f32_e32 v85, 0xbfb8aa3b, v85
	v_mul_f32_e32 v86, 0xbfb8aa3b, v86
	v_mul_f32_e32 v87, 0xbfb8aa3b, v87
	v_exp_f32_e32 v84, v84
	v_exp_f32_e32 v85, v85
	v_exp_f32_e32 v86, v86
	v_exp_f32_e32 v87, v87
	v_add_f32_e32 v84, 1.0, v84
	v_add_f32_e32 v85, 1.0, v85
	v_add_f32_e32 v86, 1.0, v86
	v_add_f32_e32 v87, 1.0, v87
	v_rcp_f32_e32 v84, v84
	v_rcp_f32_e32 v85, v85
	v_rcp_f32_e32 v86, v86
	v_rcp_f32_e32 v87, v87
	v_add_f32_e32 v80, v80, v227
	v_add_f32_e32 v81, v81, v227
	v_add_f32_e32 v82, v82, v227
	v_add_f32_e32 v83, v83, v227
	v_mul_f32_e32 v80, 0xbfb8aa3b, v80
	v_mul_f32_e32 v81, 0xbfb8aa3b, v81
	v_mul_f32_e32 v82, 0xbfb8aa3b, v82
	v_mul_f32_e32 v83, 0xbfb8aa3b, v83
	v_exp_f32_e32 v80, v80
	v_exp_f32_e32 v81, v81
	v_exp_f32_e32 v82, v82
	v_exp_f32_e32 v83, v83
	v_add_f32_e32 v80, 1.0, v80
	v_add_f32_e32 v81, 1.0, v81
	v_add_f32_e32 v82, 1.0, v82
	v_add_f32_e32 v83, 1.0, v83
	v_rcp_f32_e32 v80, v80
	v_rcp_f32_e32 v81, v81
	v_rcp_f32_e32 v82, v82
	v_rcp_f32_e32 v83, v83
	v_add_f32_e32 v76, v76, v227
	v_add_f32_e32 v77, v77, v227
	v_add_f32_e32 v78, v78, v227
	v_add_f32_e32 v79, v79, v227
	v_mul_f32_e32 v76, 0xbfb8aa3b, v76
	v_mul_f32_e32 v77, 0xbfb8aa3b, v77
	v_mul_f32_e32 v78, 0xbfb8aa3b, v78
	v_mul_f32_e32 v79, 0xbfb8aa3b, v79
	v_exp_f32_e32 v76, v76
	v_exp_f32_e32 v77, v77
	v_exp_f32_e32 v78, v78
	v_exp_f32_e32 v79, v79
	v_add_f32_e32 v76, 1.0, v76
	v_add_f32_e32 v77, 1.0, v77
	v_add_f32_e32 v78, 1.0, v78
	v_add_f32_e32 v79, 1.0, v79
	v_rcp_f32_e32 v76, v76
	v_rcp_f32_e32 v77, v77
	v_rcp_f32_e32 v78, v78
	v_rcp_f32_e32 v79, v79
	v_add_f32_e32 v72, v72, v227
	v_add_f32_e32 v73, v73, v227
	v_add_f32_e32 v74, v74, v227
	v_add_f32_e32 v75, v75, v227
	v_mul_f32_e32 v72, 0xbfb8aa3b, v72
	v_mul_f32_e32 v73, 0xbfb8aa3b, v73
	v_mul_f32_e32 v74, 0xbfb8aa3b, v74
	v_mul_f32_e32 v75, 0xbfb8aa3b, v75
	v_exp_f32_e32 v72, v72
	v_exp_f32_e32 v73, v73
	v_exp_f32_e32 v74, v74
	v_exp_f32_e32 v75, v75
	v_add_f32_e32 v72, 1.0, v72
	v_add_f32_e32 v73, 1.0, v73
	v_add_f32_e32 v74, 1.0, v74
	v_add_f32_e32 v75, 1.0, v75
	v_rcp_f32_e32 v72, v72
	v_rcp_f32_e32 v73, v73
	v_rcp_f32_e32 v74, v74
	v_rcp_f32_e32 v75, v75
	v_add_f32_e32 v68, v68, v227
	v_add_f32_e32 v69, v69, v227
	v_add_f32_e32 v70, v70, v227
	v_add_f32_e32 v71, v71, v227
	v_mul_f32_e32 v68, 0xbfb8aa3b, v68
	v_mul_f32_e32 v69, 0xbfb8aa3b, v69
	v_mul_f32_e32 v70, 0xbfb8aa3b, v70
	v_mul_f32_e32 v71, 0xbfb8aa3b, v71
	v_exp_f32_e32 v68, v68
	v_exp_f32_e32 v69, v69
	v_exp_f32_e32 v70, v70
	v_exp_f32_e32 v71, v71
	v_add_f32_e32 v68, 1.0, v68
	v_add_f32_e32 v69, 1.0, v69
	v_add_f32_e32 v70, 1.0, v70
	v_add_f32_e32 v71, 1.0, v71
	v_rcp_f32_e32 v68, v68
	v_rcp_f32_e32 v69, v69
	v_rcp_f32_e32 v70, v70
	v_rcp_f32_e32 v71, v71
	v_add_f32_e32 v64, v64, v228
	v_add_f32_e32 v65, v65, v228
	v_add_f32_e32 v66, v66, v228
	v_add_f32_e32 v67, v67, v228
	v_mul_f32_e32 v64, 0xbfb8aa3b, v64
	v_mul_f32_e32 v65, 0xbfb8aa3b, v65
	v_mul_f32_e32 v66, 0xbfb8aa3b, v66
	v_mul_f32_e32 v67, 0xbfb8aa3b, v67
	v_exp_f32_e32 v64, v64
	v_exp_f32_e32 v65, v65
	v_exp_f32_e32 v66, v66
	v_exp_f32_e32 v67, v67
	v_add_f32_e32 v64, 1.0, v64
	v_add_f32_e32 v65, 1.0, v65
	v_add_f32_e32 v66, 1.0, v66
	v_add_f32_e32 v67, 1.0, v67
	v_rcp_f32_e32 v64, v64
	v_rcp_f32_e32 v65, v65
	v_rcp_f32_e32 v66, v66
	v_rcp_f32_e32 v67, v67
	v_add_f32_e32 v60, v60, v228
	v_add_f32_e32 v61, v61, v228
	v_add_f32_e32 v62, v62, v228
	v_add_f32_e32 v63, v63, v228
	v_mul_f32_e32 v60, 0xbfb8aa3b, v60
	v_mul_f32_e32 v61, 0xbfb8aa3b, v61
	v_mul_f32_e32 v62, 0xbfb8aa3b, v62
	v_mul_f32_e32 v63, 0xbfb8aa3b, v63
	v_exp_f32_e32 v60, v60
	v_exp_f32_e32 v61, v61
	v_exp_f32_e32 v62, v62
	v_exp_f32_e32 v63, v63
	v_add_f32_e32 v60, 1.0, v60
	v_add_f32_e32 v61, 1.0, v61
	v_add_f32_e32 v62, 1.0, v62
	v_add_f32_e32 v63, 1.0, v63
	v_rcp_f32_e32 v60, v60
	v_rcp_f32_e32 v61, v61
	v_rcp_f32_e32 v62, v62
	v_rcp_f32_e32 v63, v63
	v_add_f32_e32 v56, v56, v228
	v_add_f32_e32 v57, v57, v228
	v_add_f32_e32 v58, v58, v228
	v_add_f32_e32 v59, v59, v228
	v_mul_f32_e32 v56, 0xbfb8aa3b, v56
	v_mul_f32_e32 v57, 0xbfb8aa3b, v57
	v_mul_f32_e32 v58, 0xbfb8aa3b, v58
	v_mul_f32_e32 v59, 0xbfb8aa3b, v59
	v_exp_f32_e32 v56, v56
	v_exp_f32_e32 v57, v57
	v_exp_f32_e32 v58, v58
	v_exp_f32_e32 v59, v59
	v_add_f32_e32 v56, 1.0, v56
	v_add_f32_e32 v57, 1.0, v57
	v_add_f32_e32 v58, 1.0, v58
	v_add_f32_e32 v59, 1.0, v59
	v_rcp_f32_e32 v56, v56
	v_rcp_f32_e32 v57, v57
	v_rcp_f32_e32 v58, v58
	v_rcp_f32_e32 v59, v59
	v_add_f32_e32 v52, v52, v228
	v_add_f32_e32 v53, v53, v228
	v_add_f32_e32 v54, v54, v228
; DI float bf2f(u16 h) { return __uint_as_float(((unsigned)h) << 16); }
; DI float sigmoidf_(float x) { return __builtin_amdgcn_rcpf(1.f + __expf(-x)); }
; DI void gate_tile(const Params& p, int l, int mt, int nt, char* smem) {
;     ...
;   for (int n = 0; n < 4; ++n) {
;     const float bv = bm[n * 16];
; #pragma unroll
;     for (int m = 0; m < 8; ++m)
; #pragma unroll
;       for (int j = 0; j < 4; ++j) {
;         u16* q = img + (m * 16 + j) * IMG_LD + n * 16;
;         *q = f2bf(sigmoidf_(acc[m][n][j] + bv) * bf2f(*q));
	v_add_f32_e32 v55, v55, v228
	v_mul_f32_e32 v52, 0xbfb8aa3b, v52
	v_mul_f32_e32 v53, 0xbfb8aa3b, v53
	v_mul_f32_e32 v54, 0xbfb8aa3b, v54
	v_mul_f32_e32 v55, 0xbfb8aa3b, v55
	v_exp_f32_e32 v52, v52
	v_exp_f32_e32 v53, v53
	v_exp_f32_e32 v54, v54
	v_exp_f32_e32 v55, v55
	v_add_f32_e32 v52, 1.0, v52
	v_add_f32_e32 v53, 1.0, v53
	v_add_f32_e32 v54, 1.0, v54
	v_add_f32_e32 v55, 1.0, v55
	v_rcp_f32_e32 v52, v52
	v_rcp_f32_e32 v53, v53
	v_rcp_f32_e32 v54, v54
	v_rcp_f32_e32 v55, v55
	v_add_f32_e32 v48, v48, v228
	v_add_f32_e32 v49, v49, v228
	v_add_f32_e32 v50, v50, v228
	v_add_f32_e32 v51, v51, v228
	v_mul_f32_e32 v48, 0xbfb8aa3b, v48
	v_mul_f32_e32 v49, 0xbfb8aa3b, v49
	v_mul_f32_e32 v50, 0xbfb8aa3b, v50
	v_mul_f32_e32 v51, 0xbfb8aa3b, v51
	v_exp_f32_e32 v48, v48
	v_exp_f32_e32 v49, v49
	v_exp_f32_e32 v50, v50
	v_exp_f32_e32 v51, v51
	v_add_f32_e32 v48, 1.0, v48
	v_add_f32_e32 v49, 1.0, v49
	v_add_f32_e32 v50, 1.0, v50
	v_add_f32_e32 v51, 1.0, v51
	v_rcp_f32_e32 v48, v48
	v_rcp_f32_e32 v49, v49
	v_rcp_f32_e32 v50, v50
	v_rcp_f32_e32 v51, v51
	v_add_f32_e32 v44, v44, v228
	v_add_f32_e32 v45, v45, v228
	v_add_f32_e32 v46, v46, v228
	v_add_f32_e32 v47, v47, v228
	v_mul_f32_e32 v44, 0xbfb8aa3b, v44
	v_mul_f32_e32 v45, 0xbfb8aa3b, v45
	v_mul_f32_e32 v46, 0xbfb8aa3b, v46
	v_mul_f32_e32 v47, 0xbfb8aa3b, v47
	v_exp_f32_e32 v44, v44
	v_exp_f32_e32 v45, v45
	v_exp_f32_e32 v46, v46
	v_exp_f32_e32 v47, v47
	v_add_f32_e32 v44, 1.0, v44
	v_add_f32_e32 v45, 1.0, v45
	v_add_f32_e32 v46, 1.0, v46
	v_add_f32_e32 v47, 1.0, v47
	v_rcp_f32_e32 v44, v44
	v_rcp_f32_e32 v45, v45
	v_rcp_f32_e32 v46, v46
	v_rcp_f32_e32 v47, v47
	v_add_f32_e32 v40, v40, v228
	v_add_f32_e32 v41, v41, v228
	v_add_f32_e32 v42, v42, v228
	v_add_f32_e32 v43, v43, v228
	v_mul_f32_e32 v40, 0xbfb8aa3b, v40
	v_mul_f32_e32 v41, 0xbfb8aa3b, v41
	v_mul_f32_e32 v42, 0xbfb8aa3b, v42
	v_mul_f32_e32 v43, 0xbfb8aa3b, v43
	v_exp_f32_e32 v40, v40
	v_exp_f32_e32 v41, v41
	v_exp_f32_e32 v42, v42
	v_exp_f32_e32 v43, v43
	v_add_f32_e32 v40, 1.0, v40
	v_add_f32_e32 v41, 1.0, v41
	v_add_f32_e32 v42, 1.0, v42
	v_add_f32_e32 v43, 1.0, v43
	v_rcp_f32_e32 v40, v40
	v_rcp_f32_e32 v41, v41
	v_rcp_f32_e32 v42, v42
	v_rcp_f32_e32 v43, v43
	v_add_f32_e32 v36, v36, v228
	v_add_f32_e32 v37, v37, v228
	v_add_f32_e32 v38, v38, v228
	v_add_f32_e32 v39, v39, v228
	v_mul_f32_e32 v36, 0xbfb8aa3b, v36
	v_mul_f32_e32 v37, 0xbfb8aa3b, v37
	v_mul_f32_e32 v38, 0xbfb8aa3b, v38
	v_mul_f32_e32 v39, 0xbfb8aa3b, v39
	v_exp_f32_e32 v36, v36
	v_exp_f32_e32 v37, v37
	v_exp_f32_e32 v38, v38
	v_exp_f32_e32 v39, v39
	v_add_f32_e32 v36, 1.0, v36
	v_add_f32_e32 v37, 1.0, v37
	v_add_f32_e32 v38, 1.0, v38
	v_add_f32_e32 v39, 1.0, v39
	v_rcp_f32_e32 v36, v36
	v_rcp_f32_e32 v37, v37
	v_rcp_f32_e32 v38, v38
	v_rcp_f32_e32 v39, v39
	v_add_f32_e32 v32, v32, v229
	v_add_f32_e32 v33, v33, v229
	v_add_f32_e32 v34, v34, v229
	v_add_f32_e32 v35, v35, v229
	v_mul_f32_e32 v32, 0xbfb8aa3b, v32
	v_mul_f32_e32 v33, 0xbfb8aa3b, v33
	v_mul_f32_e32 v34, 0xbfb8aa3b, v34
	v_mul_f32_e32 v35, 0xbfb8aa3b, v35
	v_exp_f32_e32 v32, v32
	v_exp_f32_e32 v33, v33
	v_exp_f32_e32 v34, v34
	v_exp_f32_e32 v35, v35
	v_add_f32_e32 v32, 1.0, v32
	v_add_f32_e32 v33, 1.0, v33
	v_add_f32_e32 v34, 1.0, v34
	v_add_f32_e32 v35, 1.0, v35
	v_rcp_f32_e32 v32, v32
	v_rcp_f32_e32 v33, v33
	v_rcp_f32_e32 v34, v34
	v_rcp_f32_e32 v35, v35
	v_add_f32_e32 v28, v28, v229
	v_add_f32_e32 v29, v29, v229
	v_add_f32_e32 v30, v30, v229
	v_add_f32_e32 v31, v31, v229
	v_mul_f32_e32 v28, 0xbfb8aa3b, v28
	v_mul_f32_e32 v29, 0xbfb8aa3b, v29
	v_mul_f32_e32 v30, 0xbfb8aa3b, v30
	v_mul_f32_e32 v31, 0xbfb8aa3b, v31
	v_exp_f32_e32 v28, v28
	v_exp_f32_e32 v29, v29
	v_exp_f32_e32 v30, v30
	v_exp_f32_e32 v31, v31
	v_add_f32_e32 v28, 1.0, v28
	v_add_f32_e32 v29, 1.0, v29
	v_add_f32_e32 v30, 1.0, v30
	v_add_f32_e32 v31, 1.0, v31
	v_rcp_f32_e32 v28, v28
	v_rcp_f32_e32 v29, v29
	v_rcp_f32_e32 v30, v30
	v_rcp_f32_e32 v31, v31
	v_add_f32_e32 v24, v24, v229
	v_add_f32_e32 v25, v25, v229
	v_add_f32_e32 v26, v26, v229
	v_add_f32_e32 v27, v27, v229
	v_mul_f32_e32 v24, 0xbfb8aa3b, v24
	v_mul_f32_e32 v25, 0xbfb8aa3b, v25
	v_mul_f32_e32 v26, 0xbfb8aa3b, v26
	v_mul_f32_e32 v27, 0xbfb8aa3b, v27
	v_exp_f32_e32 v24, v24
	v_exp_f32_e32 v25, v25
	v_exp_f32_e32 v26, v26
	v_exp_f32_e32 v27, v27
	v_add_f32_e32 v24, 1.0, v24
	v_add_f32_e32 v25, 1.0, v25
; DI int TID512() { int t = threadIdx.x; asm volatile("" : "+v"(t)); return t; }
; DI float bf2f(u16 h) { return __uint_as_float(((unsigned)h) << 16); }
; DI float sigmoidf_(float x) { return __builtin_amdgcn_rcpf(1.f + __expf(-x)); }
; DI void img_load_bf16(const u16* src, int ld, char* smem, int nrows, int rowoff) {
;   for (int slot = TID512(); slot < nrows * 32; slot += 512) {
;     const int row = slot >> 5, c16 = slot & 31;
;     *(u32x4*)(smem + (row + rowoff) * (IMG_LD * 2) + c16 * 16) = __builtin_nontemporal_load((const u32x4*)(src + (size_t)row * ld + c16 * 8));
;   }
; }
; DI void gate_tile(const Params& p, int l, int mt, int nt, char* smem) {
;     ...
;   for (int n = 0; n < 4; ++n) {
;     const float bv = bm[n * 16];
; #pragma unroll
;     for (int m = 0; m < 8; ++m)
; #pragma unroll
;       for (int j = 0; j < 4; ++j) {
;         u16* q = img + (m * 16 + j) * IMG_LD + n * 16;
;         *q = f2bf(sigmoidf_(acc[m][n][j] + bv) * bf2f(*q));
	v_add_f32_e32 v26, 1.0, v26
	v_add_f32_e32 v27, 1.0, v27
	v_rcp_f32_e32 v24, v24
	v_rcp_f32_e32 v25, v25
	v_rcp_f32_e32 v26, v26
	v_rcp_f32_e32 v27, v27
	v_add_f32_e32 v20, v20, v229
	v_add_f32_e32 v21, v21, v229
	v_add_f32_e32 v22, v22, v229
	v_add_f32_e32 v23, v23, v229
	v_mul_f32_e32 v20, 0xbfb8aa3b, v20
	v_mul_f32_e32 v21, 0xbfb8aa3b, v21
	v_mul_f32_e32 v22, 0xbfb8aa3b, v22
	v_mul_f32_e32 v23, 0xbfb8aa3b, v23
	v_exp_f32_e32 v20, v20
	v_exp_f32_e32 v21, v21
	v_exp_f32_e32 v22, v22
	v_exp_f32_e32 v23, v23
	v_add_f32_e32 v20, 1.0, v20
	v_add_f32_e32 v21, 1.0, v21
	v_add_f32_e32 v22, 1.0, v22
	v_add_f32_e32 v23, 1.0, v23
	v_rcp_f32_e32 v20, v20
	v_rcp_f32_e32 v21, v21
	v_rcp_f32_e32 v22, v22
	v_rcp_f32_e32 v23, v23
	v_add_f32_e32 v16, v16, v229
	v_add_f32_e32 v17, v17, v229
	v_add_f32_e32 v18, v18, v229
	v_add_f32_e32 v19, v19, v229
	v_mul_f32_e32 v16, 0xbfb8aa3b, v16
	v_mul_f32_e32 v17, 0xbfb8aa3b, v17
	v_mul_f32_e32 v18, 0xbfb8aa3b, v18
	v_mul_f32_e32 v19, 0xbfb8aa3b, v19
	v_exp_f32_e32 v16, v16
	v_exp_f32_e32 v17, v17
	v_exp_f32_e32 v18, v18
	v_exp_f32_e32 v19, v19
	v_add_f32_e32 v16, 1.0, v16
	v_add_f32_e32 v17, 1.0, v17
	v_add_f32_e32 v18, 1.0, v18
	v_add_f32_e32 v19, 1.0, v19
	v_rcp_f32_e32 v16, v16
	v_rcp_f32_e32 v17, v17
	v_rcp_f32_e32 v18, v18
	v_rcp_f32_e32 v19, v19
	v_add_f32_e32 v12, v12, v229
	v_add_f32_e32 v13, v13, v229
	v_add_f32_e32 v14, v14, v229
	v_add_f32_e32 v15, v15, v229
	v_mul_f32_e32 v12, 0xbfb8aa3b, v12
	v_mul_f32_e32 v13, 0xbfb8aa3b, v13
	v_mul_f32_e32 v14, 0xbfb8aa3b, v14
	v_mul_f32_e32 v15, 0xbfb8aa3b, v15
	v_exp_f32_e32 v12, v12
	v_exp_f32_e32 v13, v13
	v_exp_f32_e32 v14, v14
	v_exp_f32_e32 v15, v15
	v_add_f32_e32 v12, 1.0, v12
	v_add_f32_e32 v13, 1.0, v13
	v_add_f32_e32 v14, 1.0, v14
	v_add_f32_e32 v15, 1.0, v15
	v_rcp_f32_e32 v12, v12
	v_rcp_f32_e32 v13, v13
	v_rcp_f32_e32 v14, v14
	v_rcp_f32_e32 v15, v15
	v_add_f32_e32 v8, v8, v229
	v_add_f32_e32 v9, v9, v229
	v_add_f32_e32 v10, v10, v229
	v_add_f32_e32 v11, v11, v229
	v_mul_f32_e32 v8, 0xbfb8aa3b, v8
	v_mul_f32_e32 v9, 0xbfb8aa3b, v9
	v_mul_f32_e32 v10, 0xbfb8aa3b, v10
	v_mul_f32_e32 v11, 0xbfb8aa3b, v11
	v_exp_f32_e32 v8, v8
	v_exp_f32_e32 v9, v9
	v_exp_f32_e32 v10, v10
	v_exp_f32_e32 v11, v11
	v_add_f32_e32 v8, 1.0, v8
	v_add_f32_e32 v9, 1.0, v9
	v_add_f32_e32 v10, 1.0, v10
	v_add_f32_e32 v11, 1.0, v11
	v_rcp_f32_e32 v8, v8
	v_rcp_f32_e32 v9, v9
	v_rcp_f32_e32 v10, v10
	v_rcp_f32_e32 v11, v11
	v_add_f32_e32 v4, v4, v229
	v_add_f32_e32 v5, v5, v229
	v_add_f32_e32 v6, v6, v229
	v_add_f32_e32 v7, v7, v229
	v_mul_f32_e32 v4, 0xbfb8aa3b, v4
	v_mul_f32_e32 v5, 0xbfb8aa3b, v5
	v_mul_f32_e32 v6, 0xbfb8aa3b, v6
	v_mul_f32_e32 v7, 0xbfb8aa3b, v7
	v_exp_f32_e32 v4, v4
	v_exp_f32_e32 v5, v5
	v_exp_f32_e32 v6, v6
	v_exp_f32_e32 v7, v7
	v_add_f32_e32 v4, 1.0, v4
	v_add_f32_e32 v5, 1.0, v5
	v_add_f32_e32 v6, 1.0, v6
	v_add_f32_e32 v7, 1.0, v7
	v_rcp_f32_e32 v4, v4
	v_rcp_f32_e32 v5, v5
	v_rcp_f32_e32 v6, v6
	v_rcp_f32_e32 v7, v7
	s_waitcnt vmcnt(15)
	ds_write_b128 v138, v[140:143]
	v_add_u32_e32 v138, s32, v138
	s_waitcnt vmcnt(14)
	ds_write_b128 v138, v[144:147]
	v_add_u32_e32 v138, s32, v138
	s_waitcnt vmcnt(13)
	ds_write_b128 v138, v[148:151]
	v_add_u32_e32 v138, s32, v138
	s_waitcnt vmcnt(12)
	ds_write_b128 v138, v[152:155]
	v_add_u32_e32 v138, s32, v138
	s_waitcnt vmcnt(11)
	ds_write_b128 v138, v[156:159]
	v_add_u32_e32 v138, s32, v138
	s_waitcnt vmcnt(10)
	ds_write_b128 v138, v[160:163]
	v_add_u32_e32 v138, s32, v138
	s_waitcnt vmcnt(9)
	ds_write_b128 v138, v[164:167]
	v_add_u32_e32 v138, s32, v138
	s_waitcnt vmcnt(8)
	ds_write_b128 v138, v[168:171]
	v_add_u32_e32 v138, s32, v138
	s_waitcnt vmcnt(7)
	ds_write_b128 v138, v[176:179]
	v_add_u32_e32 v138, s32, v138
	s_waitcnt vmcnt(6)
	ds_write_b128 v138, v[180:183]
	v_add_u32_e32 v138, s32, v138
	s_waitcnt vmcnt(5)
	ds_write_b128 v138, v[198:201]
	v_add_u32_e32 v138, s32, v138
	s_waitcnt vmcnt(4)
	ds_write_b128 v138, v[202:205]
	v_add_u32_e32 v138, s32, v138
	s_waitcnt vmcnt(3)
	ds_write_b128 v138, v[206:209]
	v_add_u32_e32 v138, s32, v138
	s_waitcnt vmcnt(2)
	ds_write_b128 v138, v[214:217]
	v_add_u32_e32 v138, s32, v138
	s_waitcnt vmcnt(1)
	ds_write_b128 v138, v[218:221]
	v_add_u32_e32 v138, s32, v138
	s_waitcnt vmcnt(0)
	ds_write_b128 v138, v[222:225]
	v_add_u32_e32 v138, s32, v138
	s_branch .LBB0_2020

; DI unsigned pack2(float a, float b) { f32v2_t v = {a, b}; bf16v2_t r = __builtin_convertvector(v, bf16v2_t); return __builtin_bit_cast(unsigned, r); }
; DI void norm_phase(const Params& p, int l, int mode, int B, int G, char* smem) {
;     ...
;   for (int row = B * 8 + wid; row < MT; row += G * 8) {
;     float* X = p.out + (size_t)row * 1024;
;     const float* Xr = (mode == 0 && l == 0 && row < MP) ? p.in[0] + (size_t)row * 1024 : X;
;     float4 v[4];
;     float ss = 0.f;
; #pragma unroll
;     for (int i = 0; i < 4; ++i) { { const f32x4 t4 = __builtin_nontemporal_load((const f32x4*)(Xr + i * 256 + lane * 4)); v[i] = float4{t4[0], t4[1], t4[2], t4[3]}; } ss += v[i].x * v[i].x + v[i].y * v[i].y + v[i].z * v[i].z + v[i].w * v[i].w; }
;     ss = wave_sum(ss);
;     const float rs = rsqrtf(ss * (1.f / 1024.f) + EPS);
;     u16* XN = (u16*)(p.ws + O_XN) + (size_t)row * LDK;
; #pragma unroll
;     for (int i = 0; i < 4; ++i) {
;       v[i] = float4{v[i].x * rs * g[i].x, v[i].y * rs * g[i].y, v[i].z * rs * g[i].z, v[i].w * rs * g[i].w};
;       if (mode == 2) *(float4*)(X + i * 256 + lane * 4) = v[i];
;       else *(uint2*)(XN + i * 256 + lane * 4) = uint2{pack2(v[i].x, v[i].y), pack2(v[i].z, v[i].w)};
;     }
.LBB0_2167:
	s_or_b64 exec, exec, s[4:5]
	v_mov_b32_e32 v20, v184
	s_waitcnt lgkmcnt(0)
	s_barrier
	v_readlane_b32 s4, v253, 47
	v_ashrrev_i32_e32 v0, 6, v20
	v_readlane_b32 s5, v253, 48
	v_add_u32_e32 v2, s4, v0
	s_mov_b32 s4, 0x8200
	v_cmp_gt_i32_e32 vcc, s4, v2
	s_and_saveexec_b64 s[4:5], vcc
	s_cbranch_execz .LBB0_2170
	v_readlane_b32 s6, v254, 3
	v_readlane_b32 s8, v254, 37
	v_readlane_b32 s7, v254, 4
	v_readlane_b32 s9, v254, 38
	s_add_u32 s6, s6, s8
	v_lshlrev_b32_e32 v1, 4, v20
	s_addc_u32 s7, s7, s9
	v_and_b32_e32 v1, 0x3f0, v1
	global_load_dwordx4 v[4:7], v1, s[6:7]
	global_load_dwordx4 v[8:11], v1, s[6:7] offset:1024
	global_load_dwordx4 v[12:15], v1, s[6:7] offset:2048
	global_load_dwordx4 v[16:19], v1, s[6:7] offset:3072
	v_xor_b32_e32 v1, 32, v190
	v_cmp_lt_i32_e32 vcc, v1, v191
	v_readlane_b32 s6, v253, 47
	v_readlane_b32 s7, v253, 48
	v_cndmask_b32_e32 v1, v190, v1, vcc
	v_lshlrev_b32_e32 v22, 2, v1
	v_xor_b32_e32 v1, 16, v190
	v_cmp_lt_i32_e32 vcc, v1, v191
	v_and_b32_e32 v30, 63, v20
	v_lshlrev_b32_e32 v172, 3, v30
	v_cndmask_b32_e32 v1, v190, v1, vcc
	v_cmp_lt_i32_e32 vcc, v195, v191
	v_lshlrev_b32_e32 v23, 2, v1
	s_movk_i32 s8, 0x880
	v_cndmask_b32_e32 v1, v190, v195, vcc
	v_cmp_lt_i32_e32 vcc, v194, v191
	v_lshlrev_b32_e32 v24, 2, v1
	s_nop 0
	v_cndmask_b32_e32 v1, v190, v194, vcc
	v_cmp_lt_i32_e32 vcc, v193, v191
	v_lshlrev_b32_e32 v25, 2, v1
	s_nop 0
	v_cndmask_b32_e32 v1, v190, v193, vcc
	v_cmp_lt_i32_e32 vcc, v192, v191
	v_lshlrev_b32_e32 v26, 2, v1
	s_nop 0
	v_cndmask_b32_e32 v1, v190, v192, vcc
	v_lshlrev_b32_e32 v27, 2, v1
	v_ashrrev_i32_e32 v1, 31, v0
	v_lshl_add_u64 v[28:29], s[6:7], 0, v[0:1]
	v_mad_u64_u32 v[0:1], s[6:7], v28, s8, v[172:173]
	v_readlane_b32 s6, v253, 45
	v_mad_i32_i24 v1, v29, s8, v1
	v_readlane_b32 s7, v253, 46
	v_lshlrev_b64 v[20:21], 12, v[28:29]
	v_lshl_or_b32 v20, v30, 4, v20
	v_lshl_add_u64 v[0:1], s[6:7], 0, v[0:1]
	v_readlane_b32 s6, v253, 49
	v_readlane_b32 s7, v253, 50
	s_nop 1
	v_lshl_add_u64 v[20:21], s[6:7], 0, v[20:21]
	s_mov_b64 s[6:7], 0
	global_load_dwordx4 v[60:63], v[20:21], off offset:-3072 nt
	global_load_dwordx4 v[64:67], v[20:21], off offset:-2048 nt
	global_load_dwordx4 v[68:71], v[20:21], off offset:-1024 nt
	global_load_dwordx4 v[72:75], v[20:21], off nt
.LBB0_2169:
	s_waitcnt vmcnt(0)
	v_mov_b32_e32 v28, v60
	v_mov_b32_e32 v29, v61
	v_mov_b32_e32 v30, v62
	v_mov_b32_e32 v31, v63
	v_mov_b32_e32 v32, v64
	v_mov_b32_e32 v33, v65
	v_mov_b32_e32 v34, v66
	v_mov_b32_e32 v35, v67
	v_mov_b32_e32 v76, v68
	v_mov_b32_e32 v77, v69
	v_mov_b32_e32 v78, v70
	v_mov_b32_e32 v79, v71
	v_mov_b32_e32 v80, v72
	v_mov_b32_e32 v81, v73
	v_mov_b32_e32 v82, v74
	v_mov_b32_e32 v83, v75
	v_add_u32_e32 v2, s20, v2
	v_cmp_ge_i32_e64 s[34:35], s42, v2
	v_lshl_add_u64 v[84:85], v[20:21], 0, s[38:39]
	s_nop 0
	v_cndmask_b32_e64 v20, v20, v84, s[34:35]
	v_cndmask_b32_e64 v21, v21, v85, s[34:35]
	global_load_dwordx4 v[60:63], v[20:21], off offset:-3072 nt
	global_load_dwordx4 v[64:67], v[20:21], off offset:-2048 nt
	global_load_dwordx4 v[68:71], v[20:21], off offset:-1024 nt
	global_load_dwordx4 v[72:75], v[20:21], off nt
	v_mov_b32_e32 v38, v29
	v_mov_b32_e32 v39, v33
	v_mov_b32_e32 v36, v28
	v_mov_b32_e32 v37, v32
	v_pk_mul_f32 v[38:39], v[38:39], v[38:39]
	s_nop 0
	v_pk_fma_f32 v[36:37], v[36:37], v[36:37], v[38:39]
	v_mov_b32_e32 v38, v30
	v_mov_b32_e32 v39, v34
	v_pk_fma_f32 v[36:37], v[38:39], v[38:39], v[36:37]
	v_mov_b32_e32 v38, v31
	v_mov_b32_e32 v39, v35
	v_pk_fma_f32 v[44:45], v[38:39], v[38:39], v[36:37]
	v_add_f32_e32 v44, v44, v45
	v_mov_b32_e32 v48, v77
	v_mov_b32_e32 v49, v81
	v_mov_b32_e32 v46, v76
	v_mov_b32_e32 v47, v80
	v_pk_mul_f32 v[48:49], v[48:49], v[48:49]
	s_nop 0
	v_pk_fma_f32 v[46:47], v[46:47], v[46:47], v[48:49]
	v_mov_b32_e32 v48, v78
	v_mov_b32_e32 v49, v82
	v_pk_fma_f32 v[46:47], v[48:49], v[48:49], v[46:47]
	v_mov_b32_e32 v48, v79
	v_mov_b32_e32 v49, v83
	v_pk_fma_f32 v[46:47], v[48:49], v[48:49], v[46:47]
	s_nop 0
	v_add_f32_e32 v44, v44, v46
	v_add_f32_e32 v44, v44, v47
	ds_bpermute_b32 v45, v22, v44
	s_waitcnt lgkmcnt(0)
	v_add_f32_e32 v44, v44, v45
	ds_bpermute_b32 v45, v23, v44
	s_waitcnt lgkmcnt(0)
	v_add_f32_e32 v44, v44, v45
	ds_bpermute_b32 v45, v24, v44
	s_waitcnt lgkmcnt(0)
	v_add_f32_e32 v44, v44, v45
	ds_bpermute_b32 v45, v25, v44
	s_waitcnt lgkmcnt(0)
	v_add_f32_e32 v44, v44, v45
	ds_bpermute_b32 v45, v26, v44
	s_waitcnt lgkmcnt(0)
	v_add_f32_e32 v44, v44, v45
	ds_bpermute_b32 v45, v27, v44
	s_waitcnt lgkmcnt(0)
	v_add_f32_e32 v44, v44, v45
	v_fmamk_f32 v44, v44, 0x3a800000, v186
	v_cmp_gt_f32_e32 vcc, s1, v44
	v_mul_f32_e32 v45, 0x4b800000, v44
	s_nop 0
	v_cndmask_b32_e32 v44, v44, v45, vcc
	v_rsq_f32_e32 v44, v44
	s_nop 0
	v_mul_f32_e32 v45, 0x45800000, v44
	v_cndmask_b32_e32 v44, v44, v45, vcc
	v_pk_mul_f32 v[28:29], v[28:29], v[44:45] op_sel_hi:[1,0]
	v_pk_mul_f32 v[30:31], v[30:31], v[44:45] op_sel_hi:[1,0]
	v_pk_mul_f32 v[28:29], v[4:5], v[28:29]
	v_pk_mul_f32 v[30:31], v[6:7], v[30:31]
	v_cvt_pk_bf16_f32 v28, v28, v29
	v_cvt_pk_bf16_f32 v29, v30, v31
	global_store_dwordx2 v[0:1], v[28:29], off offset:-1024
	v_pk_mul_f32 v[28:29], v[32:33], v[44:45] op_sel_hi:[1,0]
	v_pk_mul_f32 v[30:31], v[34:35], v[44:45] op_sel_hi:[1,0]
	v_pk_mul_f32 v[28:29], v[8:9], v[28:29]
	v_pk_mul_f32 v[30:31], v[10:11], v[30:31]
	v_cvt_pk_bf16_f32 v28, v28, v29
	v_cvt_pk_bf16_f32 v29, v30, v31
	global_store_dwordx2 v[0:1], v[28:29], off offset:-512
	v_pk_mul_f32 v[28:29], v[76:77], v[44:45] op_sel_hi:[1,0]
	v_pk_mul_f32 v[30:31], v[78:79], v[44:45] op_sel_hi:[1,0]
	v_pk_mul_f32 v[28:29], v[12:13], v[28:29]
	v_pk_mul_f32 v[30:31], v[14:15], v[30:31]
	v_cvt_pk_bf16_f32 v28, v28, v29
	v_cvt_pk_bf16_f32 v29, v30, v31
	global_store_dwordx2 v[0:1], v[28:29], off
	v_pk_mul_f32 v[28:29], v[80:81], v[44:45] op_sel_hi:[1,0]
	v_pk_mul_f32 v[30:31], v[82:83], v[44:45] op_sel_hi:[1,0]
	v_pk_mul_f32 v[28:29], v[16:17], v[28:29]
	v_pk_mul_f32 v[30:31], v[18:19], v[30:31]
	v_cvt_pk_bf16_f32 v28, v28, v29
	v_cvt_pk_bf16_f32 v29, v30, v31
	v_cmp_lt_i32_e32 vcc, s42, v2
	global_store_dwordx2 v[0:1], v[28:29], off offset:512
	v_lshl_add_u64 v[0:1], v[0:1], 0, s[40:41]
	s_or_b64 s[6:7], vcc, s[6:7]
	s_andn2_b64 exec, exec, s[6:7]
	s_cbranch_execnz .LBB0_2169

; DI float bf2f(u16 h) { return __uint_as_float(((unsigned)h) << 16); }
; DI float gelu_tanh(float x) { float u = 0.7978845608028654f * (x + 0.044715f * x * x * x); return x * sigmoidf_(2.f * u); }
; DI void img_barrier() { asm volatile("s_waitcnt lgkmcnt(0)" ::: "memory"); __builtin_amdgcn_s_barrier(); }
; DI void ffup_tile(const Params& p, int l, int mt, int nt, char* smem) {
;     ...
;     if (row0 >= 2) img_load_bf16(GUt - 2 * DFF, DFF, smem, 258, 0); else img_load_bf16(GUt, DFF, smem, 256, 2);
;     img_barrier();
;     const u16* img = (const u16*)smem + (wr * 128 + fq * 4) * IMG_LD + wc * 64 + fr;
; #pragma unroll
;     for (int n = 0; n < 4; ++n) {
;       const int col = col0 + wc * 64 + n * 16 + fr;
;       const float* cw = p.in[30] + (size_t)l * 3 * DFF + col;
;       const float w0 = cw[0], w1 = cw[DFF], w2 = cw[2 * DFF], cb = p.in[31][(size_t)l * DFF + col];
; #pragma unroll
;       for (int m = 0; m < 8; ++m) {
;         if ((m & 1) == 0) asm volatile("" ::: "memory");
;         const int t = (row0 + wr * 128 + m * 16 + fq * 4) & 8191;
;         float g[6];
; #pragma unroll
;         for (int d = 0; d < 6; ++d) { const float gv = bf2f(img[(m * 16 + d) * IMG_LD + n * 16]); g[d] = (d >= 2 || t - 2 + d >= 0) ? gv : 0.f; }
; #pragma unroll
;         for (int j = 0; j < 4; ++j) acc[m][n][j] *= gelu_tanh(cb + w0 * g[j] + w1 * g[j + 1] + w2 * g[j + 2]);
;       }
.LBB0_2354:
	v_and_b32_e32 v0, 0xc0, v132
	v_and_b32_e32 v1, 15, v132
	v_ashrrev_i32_e32 v133, 1, v132
	v_lshrrev_b32_e32 v2, 2, v132
	v_and_b32_e32 v132, 12, v2
	s_mov_b32 s5, 0xfffff80
	v_lshlrev_b32_e32 v134, 1, v0
	v_lshlrev_b32_e32 v135, 1, v1
	v_or3_b32 v0, v0, s46, v1
	v_add_u32_e32 v1, s13, v133
	s_movk_i32 s4, 0x1f80
	v_and_or_b32 v2, v133, s5, v132
	v_and_or_b32 v142, v1, s4, v132
	v_ashrrev_i32_e32 v1, 31, v0
	v_mul_lo_u32 v2, v2, s3
	v_lshlrev_b64 v[0:1], 2, v[0:1]
	v_add_u32_e32 v2, 16, v2
	v_lshl_add_u64 v[132:133], s[40:41], 0, v[0:1]
	s_movk_i32 s4, 0x2000
	v_add3_u32 v2, v2, v134, v135
	v_add_co_u32_e32 v134, vcc, s4, v132
	s_movk_i32 s4, 0x5000
	s_nop 0
	v_addc_co_u32_e32 v135, vcc, 0, v133, vcc
	v_lshl_add_u64 v[0:1], s[44:45], 0, v[0:1]
	v_add_co_u32_e32 v136, vcc, s4, v132
	s_nop 1
	v_addc_co_u32_e32 v137, vcc, 0, v133, vcc
	global_load_dword v138, v[132:133], off
	global_load_dword v139, v[134:135], off offset:3072
	global_load_dword v140, v[136:137], off offset:2048
	global_load_dword v141, v[0:1], off
	global_load_dword v150, v[132:133], off offset:64
	global_load_dword v151, v[134:135], off offset:3136
	global_load_dword v152, v[136:137], off offset:2112
	global_load_dword v153, v[0:1], off offset:64
	global_load_dword v154, v[132:133], off offset:128
	global_load_dword v155, v[134:135], off offset:3200
	global_load_dword v156, v[136:137], off offset:2176
	global_load_dword v157, v[0:1], off offset:128
	global_load_dword v158, v[132:133], off offset:192
	global_load_dword v159, v[134:135], off offset:3264
	global_load_dword v160, v[136:137], off offset:2240
	global_load_dword v161, v[0:1], off offset:192
	s_waitcnt lgkmcnt(0)
	s_barrier
	v_cmp_eq_u32_e32 vcc, 0, v142
	ds_read_u16 v142, v2
	ds_read_u16 v143, v2 offset:528
	ds_read_u16 v144, v2 offset:1056
	ds_read_u16 v145, v2 offset:1584
	ds_read_u16 v146, v2 offset:2112
	ds_read_u16 v147, v2 offset:2640
	s_waitcnt lgkmcnt(0)
	v_lshlrev_b32_e32 v142, 16, v142
	v_cndmask_b32_e64 v142, v142, 0, vcc
	v_lshlrev_b32_e32 v143, 16, v143
	v_cndmask_b32_e64 v143, v143, 0, vcc
	v_lshlrev_b32_e32 v144, 16, v144
	v_lshlrev_b32_e32 v145, 16, v145
	v_lshlrev_b32_e32 v146, 16, v146
	v_lshlrev_b32_e32 v147, 16, v147
	s_add_u32 s4, s76, s38
	s_waitcnt vmcnt(12)
	v_fma_f32 v142, v138, v142, v141
	v_fmac_f32_e32 v142, v139, v143
	v_fmac_f32_e32 v142, v140, v144
	v_mul_f32_e32 v148, 0x3d372713, v142
	v_mul_f32_e32 v148, v142, v148
	v_fma_f32 v148, v142, v148, v142
	v_mul_f32_e32 v148, 0x3f4c422a, v148
	v_add_f32_e32 v148, v148, v148
	v_mul_f32_e32 v148, 0xbfb8aa3b, v148
	v_exp_f32_e32 v148, v148
	s_nop 0
	v_add_f32_e32 v148, 1.0, v148
	v_rcp_f32_e32 v148, v148
	s_nop 0
	v_mul_f32_e32 v142, v142, v148
	v_mul_f32_e32 v128, v128, v142
	v_fma_f32 v142, v138, v143, v141
	v_fmac_f32_e32 v142, v139, v144
	v_fmac_f32_e32 v142, v140, v145
	v_mul_f32_e32 v143, 0x3d372713, v142
	v_mul_f32_e32 v143, v142, v143
	v_fma_f32 v143, v142, v143, v142
	v_mul_f32_e32 v143, 0x3f4c422a, v143
	v_add_f32_e32 v143, v143, v143
	v_mul_f32_e32 v143, 0xbfb8aa3b, v143
	v_exp_f32_e32 v143, v143
	s_nop 0
	v_add_f32_e32 v143, 1.0, v143
	v_rcp_f32_e32 v143, v143
	s_nop 0
	v_mul_f32_e32 v142, v142, v143
	v_mul_f32_e32 v129, v129, v142
	v_fma_f32 v142, v138, v144, v141
	v_fmac_f32_e32 v142, v139, v145
	v_fmac_f32_e32 v142, v140, v146
	v_mul_f32_e32 v143, 0x3d372713, v142
	v_mul_f32_e32 v143, v142, v143
	v_fma_f32 v143, v142, v143, v142
	v_mul_f32_e32 v143, 0x3f4c422a, v143
	v_add_f32_e32 v143, v143, v143
	v_mul_f32_e32 v143, 0xbfb8aa3b, v143
	v_exp_f32_e32 v143, v143
	ds_read_u16 v144, v2 offset:9504
	v_add_f32_e32 v143, 1.0, v143
	v_rcp_f32_e32 v143, v143
	s_nop 0
	v_mul_f32_e32 v142, v142, v143
	v_mul_f32_e32 v130, v130, v142
	v_fma_f32 v142, v138, v145, v141
	v_fmac_f32_e32 v142, v139, v146
	v_fmac_f32_e32 v142, v140, v147
	v_mul_f32_e32 v143, 0x3d372713, v142
	v_mul_f32_e32 v143, v142, v143
	v_fma_f32 v143, v142, v143, v142
	v_mul_f32_e32 v143, 0x3f4c422a, v143
	v_add_f32_e32 v143, v143, v143
	v_mul_f32_e32 v143, 0xbfb8aa3b, v143
	v_exp_f32_e32 v143, v143
	ds_read_u16 v145, v2 offset:10032
	ds_read_u16 v146, v2 offset:10560
	ds_read_u16 v147, v2 offset:11088
	v_add_f32_e32 v143, 1.0, v143
	v_rcp_f32_e32 v143, v143
	s_waitcnt lgkmcnt(3)
	v_lshlrev_b32_e32 v144, 16, v144
	s_waitcnt lgkmcnt(2)
	v_lshlrev_b32_e32 v145, 16, v145
	s_waitcnt lgkmcnt(1)
	v_lshlrev_b32_e32 v146, 16, v146
	v_mul_f32_e32 v142, v142, v143
	v_mul_f32_e32 v131, v131, v142
	ds_read_u16 v142, v2 offset:8448
	ds_read_u16 v143, v2 offset:8976
	s_waitcnt lgkmcnt(2)
	v_lshlrev_b32_e32 v147, 16, v147
	s_waitcnt lgkmcnt(1)
	v_lshlrev_b32_e32 v142, 16, v142
	s_waitcnt lgkmcnt(0)
; DI float bf2f(u16 h) { return __uint_as_float(((unsigned)h) << 16); }
; DI float gelu_tanh(float x) { float u = 0.7978845608028654f * (x + 0.044715f * x * x * x); return x * sigmoidf_(2.f * u); }
; DI void ffup_tile(const Params& p, int l, int mt, int nt, char* smem) {
;     ...
;       for (int m = 0; m < 8; ++m) {
;         if ((m & 1) == 0) asm volatile("" ::: "memory");
;         const int t = (row0 + wr * 128 + m * 16 + fq * 4) & 8191;
;         float g[6];
; #pragma unroll
;         for (int d = 0; d < 6; ++d) { const float gv = bf2f(img[(m * 16 + d) * IMG_LD + n * 16]); g[d] = (d >= 2 || t - 2 + d >= 0) ? gv : 0.f; }
; #pragma unroll
;         for (int j = 0; j < 4; ++j) acc[m][n][j] *= gelu_tanh(cb + w0 * g[j] + w1 * g[j + 1] + w2 * g[j + 2]);
;       }
	v_lshlrev_b32_e32 v143, 16, v143
	v_fma_f32 v142, v138, v142, v141
	v_fmac_f32_e32 v142, v139, v143
	v_fmac_f32_e32 v142, v140, v144
	v_mul_f32_e32 v148, 0x3d372713, v142
	v_mul_f32_e32 v148, v142, v148
	v_fma_f32 v148, v142, v148, v142
	v_mul_f32_e32 v148, 0x3f4c422a, v148
	v_add_f32_e32 v148, v148, v148
	v_mul_f32_e32 v148, 0xbfb8aa3b, v148
	v_exp_f32_e32 v148, v148
	s_nop 0
	v_add_f32_e32 v148, 1.0, v148
	v_rcp_f32_e32 v148, v148
	s_nop 0
	v_mul_f32_e32 v142, v142, v148
	v_mul_f32_e32 v124, v124, v142
	v_fma_f32 v142, v138, v143, v141
	v_fmac_f32_e32 v142, v139, v144
	v_fmac_f32_e32 v142, v140, v145
	v_mul_f32_e32 v143, 0x3d372713, v142
	v_mul_f32_e32 v143, v142, v143
	v_fma_f32 v143, v142, v143, v142
	v_mul_f32_e32 v143, 0x3f4c422a, v143
	v_add_f32_e32 v143, v143, v143
	v_mul_f32_e32 v143, 0xbfb8aa3b, v143
	v_exp_f32_e32 v143, v143
	s_nop 0
	v_add_f32_e32 v143, 1.0, v143
	v_rcp_f32_e32 v143, v143
	s_nop 0
	v_mul_f32_e32 v142, v142, v143
	v_mul_f32_e32 v125, v125, v142
	v_fma_f32 v142, v138, v144, v141
	v_fmac_f32_e32 v142, v139, v145
	v_fmac_f32_e32 v142, v140, v146
	v_mul_f32_e32 v143, 0x3d372713, v142
	v_mul_f32_e32 v143, v142, v143
	v_fma_f32 v143, v142, v143, v142
	v_mul_f32_e32 v143, 0x3f4c422a, v143
	v_add_f32_e32 v143, v143, v143
	v_mul_f32_e32 v143, 0xbfb8aa3b, v143
	v_exp_f32_e32 v143, v143
	ds_read_u16 v144, v2 offset:17952
	v_add_f32_e32 v143, 1.0, v143
	v_rcp_f32_e32 v143, v143
	s_nop 0
	v_mul_f32_e32 v142, v142, v143
	v_mul_f32_e32 v126, v126, v142
	v_fma_f32 v142, v138, v145, v141
	v_fmac_f32_e32 v142, v139, v146
	v_fmac_f32_e32 v142, v140, v147
	v_mul_f32_e32 v143, 0x3d372713, v142
	v_mul_f32_e32 v143, v142, v143
	v_fma_f32 v143, v142, v143, v142
	v_mul_f32_e32 v143, 0x3f4c422a, v143
	v_add_f32_e32 v143, v143, v143
	v_mul_f32_e32 v143, 0xbfb8aa3b, v143
	v_exp_f32_e32 v143, v143
	ds_read_u16 v145, v2 offset:18480
	ds_read_u16 v146, v2 offset:19008
	ds_read_u16 v147, v2 offset:19536
	v_add_f32_e32 v143, 1.0, v143
	v_rcp_f32_e32 v143, v143
	s_waitcnt lgkmcnt(3)
	v_lshlrev_b32_e32 v144, 16, v144
	s_waitcnt lgkmcnt(2)
	v_lshlrev_b32_e32 v145, 16, v145
	s_waitcnt lgkmcnt(1)
	v_lshlrev_b32_e32 v146, 16, v146
	v_mul_f32_e32 v142, v142, v143
	v_mul_f32_e32 v127, v127, v142
	ds_read_u16 v142, v2 offset:16896
	ds_read_u16 v143, v2 offset:17424
	s_waitcnt lgkmcnt(2)
	v_lshlrev_b32_e32 v147, 16, v147
	s_waitcnt lgkmcnt(1)
	v_lshlrev_b32_e32 v142, 16, v142
	s_waitcnt lgkmcnt(0)
	v_lshlrev_b32_e32 v143, 16, v143
	v_fma_f32 v142, v138, v142, v141
	v_fmac_f32_e32 v142, v139, v143
	v_fmac_f32_e32 v142, v140, v144
	v_mul_f32_e32 v148, 0x3d372713, v142
	v_mul_f32_e32 v148, v142, v148
	v_fma_f32 v148, v142, v148, v142
	v_mul_f32_e32 v148, 0x3f4c422a, v148
	v_add_f32_e32 v148, v148, v148
	v_mul_f32_e32 v148, 0xbfb8aa3b, v148
	v_exp_f32_e32 v148, v148
	s_nop 0
	v_add_f32_e32 v148, 1.0, v148
	v_rcp_f32_e32 v148, v148
	s_nop 0
	v_mul_f32_e32 v142, v142, v148
	v_mul_f32_e32 v120, v120, v142
	v_fma_f32 v142, v138, v143, v141
	v_fmac_f32_e32 v142, v139, v144
	v_fmac_f32_e32 v142, v140, v145
	v_mul_f32_e32 v143, 0x3d372713, v142
	v_mul_f32_e32 v143, v142, v143
	v_fma_f32 v143, v142, v143, v142
	v_mul_f32_e32 v143, 0x3f4c422a, v143
	v_add_f32_e32 v143, v143, v143
	v_mul_f32_e32 v143, 0xbfb8aa3b, v143
	v_exp_f32_e32 v143, v143
	s_nop 0
	v_add_f32_e32 v143, 1.0, v143
	v_rcp_f32_e32 v143, v143
	s_nop 0
	v_mul_f32_e32 v142, v142, v143
	v_mul_f32_e32 v121, v121, v142
	v_fma_f32 v142, v138, v144, v141
	v_fmac_f32_e32 v142, v139, v145
	v_fmac_f32_e32 v142, v140, v146
	v_mul_f32_e32 v143, 0x3d372713, v142
	v_mul_f32_e32 v143, v142, v143
	v_fma_f32 v143, v142, v143, v142
	v_mul_f32_e32 v143, 0x3f4c422a, v143
	v_add_f32_e32 v143, v143, v143
	v_mul_f32_e32 v143, 0xbfb8aa3b, v143
	v_exp_f32_e32 v143, v143
	ds_read_u16 v144, v2 offset:26400
	v_add_f32_e32 v143, 1.0, v143
	v_rcp_f32_e32 v143, v143
	s_nop 0
	v_mul_f32_e32 v142, v142, v143
	v_mul_f32_e32 v122, v122, v142
	v_fma_f32 v142, v138, v145, v141
	v_fmac_f32_e32 v142, v139, v146
	v_fmac_f32_e32 v142, v140, v147
	v_mul_f32_e32 v143, 0x3d372713, v142
	v_mul_f32_e32 v143, v142, v143
	v_fma_f32 v143, v142, v143, v142
	v_mul_f32_e32 v143, 0x3f4c422a, v143
	v_add_f32_e32 v143, v143, v143
	v_mul_f32_e32 v143, 0xbfb8aa3b, v143
	v_exp_f32_e32 v143, v143
	ds_read_u16 v145, v2 offset:26928
	ds_read_u16 v146, v2 offset:27456
	ds_read_u16 v147, v2 offset:27984
	v_add_f32_e32 v143, 1.0, v143
	v_rcp_f32_e32 v143, v143
	s_waitcnt lgkmcnt(3)
	v_lshlrev_b32_e32 v144, 16, v144
	s_waitcnt lgkmcnt(2)
	v_lshlrev_b32_e32 v145, 16, v145
	s_waitcnt lgkmcnt(1)
	v_lshlrev_b32_e32 v146, 16, v146
	v_mul_f32_e32 v142, v142, v143
	v_mul_f32_e32 v123, v123, v142
	ds_read_u16 v142, v2 offset:25344
	ds_read_u16 v143, v2 offset:25872
	s_waitcnt lgkmcnt(2)
	v_lshlrev_b32_e32 v147, 16, v147
	s_waitcnt lgkmcnt(1)
	v_lshlrev_b32_e32 v142, 16, v142
	s_waitcnt lgkmcnt(0)
; DI float bf2f(u16 h) { return __uint_as_float(((unsigned)h) << 16); }
; DI float gelu_tanh(float x) { float u = 0.7978845608028654f * (x + 0.044715f * x * x * x); return x * sigmoidf_(2.f * u); }
; DI void ffup_tile(const Params& p, int l, int mt, int nt, char* smem) {
;     ...
;       for (int m = 0; m < 8; ++m) {
;         if ((m & 1) == 0) asm volatile("" ::: "memory");
;         const int t = (row0 + wr * 128 + m * 16 + fq * 4) & 8191;
;         float g[6];
; #pragma unroll
;         for (int d = 0; d < 6; ++d) { const float gv = bf2f(img[(m * 16 + d) * IMG_LD + n * 16]); g[d] = (d >= 2 || t - 2 + d >= 0) ? gv : 0.f; }
; #pragma unroll
;         for (int j = 0; j < 4; ++j) acc[m][n][j] *= gelu_tanh(cb + w0 * g[j] + w1 * g[j + 1] + w2 * g[j + 2]);
;       }
	v_lshlrev_b32_e32 v143, 16, v143
	v_fma_f32 v142, v138, v142, v141
	v_fmac_f32_e32 v142, v139, v143
	v_fmac_f32_e32 v142, v140, v144
	v_mul_f32_e32 v148, 0x3d372713, v142
	v_mul_f32_e32 v148, v142, v148
	v_fma_f32 v148, v142, v148, v142
	v_mul_f32_e32 v148, 0x3f4c422a, v148
	v_add_f32_e32 v148, v148, v148
	v_mul_f32_e32 v148, 0xbfb8aa3b, v148
	v_exp_f32_e32 v148, v148
	s_nop 0
	v_add_f32_e32 v148, 1.0, v148
	v_rcp_f32_e32 v148, v148
	s_nop 0
	v_mul_f32_e32 v142, v142, v148
	v_mul_f32_e32 v116, v116, v142
	v_fma_f32 v142, v138, v143, v141
	v_fmac_f32_e32 v142, v139, v144
	v_fmac_f32_e32 v142, v140, v145
	v_mul_f32_e32 v143, 0x3d372713, v142
	v_mul_f32_e32 v143, v142, v143
	v_fma_f32 v143, v142, v143, v142
	v_mul_f32_e32 v143, 0x3f4c422a, v143
	v_add_f32_e32 v143, v143, v143
	v_mul_f32_e32 v143, 0xbfb8aa3b, v143
	v_exp_f32_e32 v143, v143
	s_nop 0
	v_add_f32_e32 v143, 1.0, v143
	v_rcp_f32_e32 v143, v143
	s_nop 0
	v_mul_f32_e32 v142, v142, v143
	v_mul_f32_e32 v117, v117, v142
	v_fma_f32 v142, v138, v144, v141
	v_fmac_f32_e32 v142, v139, v145
	v_fmac_f32_e32 v142, v140, v146
	v_mul_f32_e32 v143, 0x3d372713, v142
	v_mul_f32_e32 v143, v142, v143
	v_fma_f32 v143, v142, v143, v142
	v_mul_f32_e32 v143, 0x3f4c422a, v143
	v_add_f32_e32 v143, v143, v143
	v_mul_f32_e32 v143, 0xbfb8aa3b, v143
	v_exp_f32_e32 v143, v143
	ds_read_u16 v144, v2 offset:34848
	v_add_f32_e32 v143, 1.0, v143
	v_rcp_f32_e32 v143, v143
	s_nop 0
	v_mul_f32_e32 v142, v142, v143
	v_mul_f32_e32 v118, v118, v142
	v_fma_f32 v142, v138, v145, v141
	v_fmac_f32_e32 v142, v139, v146
	v_fmac_f32_e32 v142, v140, v147
	v_mul_f32_e32 v143, 0x3d372713, v142
	v_mul_f32_e32 v143, v142, v143
	v_fma_f32 v143, v142, v143, v142
	v_mul_f32_e32 v143, 0x3f4c422a, v143
	v_add_f32_e32 v143, v143, v143
	v_mul_f32_e32 v143, 0xbfb8aa3b, v143
	v_exp_f32_e32 v143, v143
	ds_read_u16 v145, v2 offset:35376
	ds_read_u16 v146, v2 offset:35904
	ds_read_u16 v147, v2 offset:36432
	v_add_f32_e32 v143, 1.0, v143
	v_rcp_f32_e32 v143, v143
	s_waitcnt lgkmcnt(3)
	v_lshlrev_b32_e32 v144, 16, v144
	s_waitcnt lgkmcnt(2)
	v_lshlrev_b32_e32 v145, 16, v145
	s_waitcnt lgkmcnt(1)
	v_lshlrev_b32_e32 v146, 16, v146
	v_mul_f32_e32 v142, v142, v143
	v_mul_f32_e32 v119, v119, v142
	ds_read_u16 v142, v2 offset:33792
	ds_read_u16 v143, v2 offset:34320
	s_waitcnt lgkmcnt(2)
	v_lshlrev_b32_e32 v147, 16, v147
	s_waitcnt lgkmcnt(1)
	v_lshlrev_b32_e32 v142, 16, v142
	s_waitcnt lgkmcnt(0)
	v_lshlrev_b32_e32 v143, 16, v143
	v_fma_f32 v142, v138, v142, v141
	v_fmac_f32_e32 v142, v139, v143
	v_fmac_f32_e32 v142, v140, v144
	v_mul_f32_e32 v148, 0x3d372713, v142
	v_mul_f32_e32 v148, v142, v148
	v_fma_f32 v148, v142, v148, v142
	v_mul_f32_e32 v148, 0x3f4c422a, v148
	v_add_f32_e32 v148, v148, v148
	v_mul_f32_e32 v148, 0xbfb8aa3b, v148
	v_exp_f32_e32 v148, v148
	s_nop 0
	v_add_f32_e32 v148, 1.0, v148
	v_rcp_f32_e32 v148, v148
	s_nop 0
	v_mul_f32_e32 v142, v142, v148
	v_mul_f32_e32 v112, v112, v142
	v_fma_f32 v142, v138, v143, v141
	v_fmac_f32_e32 v142, v139, v144
	v_fmac_f32_e32 v142, v140, v145
	v_mul_f32_e32 v143, 0x3d372713, v142
	v_mul_f32_e32 v143, v142, v143
	v_fma_f32 v143, v142, v143, v142
	v_mul_f32_e32 v143, 0x3f4c422a, v143
	v_add_f32_e32 v143, v143, v143
	v_mul_f32_e32 v143, 0xbfb8aa3b, v143
	v_exp_f32_e32 v143, v143
	s_nop 0
	v_add_f32_e32 v143, 1.0, v143
	v_rcp_f32_e32 v143, v143
	s_nop 0
	v_mul_f32_e32 v142, v142, v143
	v_mul_f32_e32 v113, v113, v142
	v_fma_f32 v142, v138, v144, v141
	v_fmac_f32_e32 v142, v139, v145
	v_fmac_f32_e32 v142, v140, v146
	v_mul_f32_e32 v143, 0x3d372713, v142
	v_mul_f32_e32 v143, v142, v143
	v_fma_f32 v143, v142, v143, v142
	v_mul_f32_e32 v143, 0x3f4c422a, v143
	v_add_f32_e32 v143, v143, v143
	v_mul_f32_e32 v143, 0xbfb8aa3b, v143
	v_exp_f32_e32 v143, v143
	ds_read_u16 v144, v2 offset:43296
	v_add_f32_e32 v143, 1.0, v143
	v_rcp_f32_e32 v143, v143
	s_nop 0
	v_mul_f32_e32 v142, v142, v143
	v_mul_f32_e32 v114, v114, v142
	v_fma_f32 v142, v138, v145, v141
	v_fmac_f32_e32 v142, v139, v146
	v_fmac_f32_e32 v142, v140, v147
	v_mul_f32_e32 v143, 0x3d372713, v142
	v_mul_f32_e32 v143, v142, v143
	v_fma_f32 v143, v142, v143, v142
	v_mul_f32_e32 v143, 0x3f4c422a, v143
	v_add_f32_e32 v143, v143, v143
	v_mul_f32_e32 v143, 0xbfb8aa3b, v143
	v_exp_f32_e32 v143, v143
	ds_read_u16 v145, v2 offset:43824
	ds_read_u16 v146, v2 offset:44352
	ds_read_u16 v147, v2 offset:44880
	v_add_f32_e32 v143, 1.0, v143
	v_rcp_f32_e32 v143, v143
	s_waitcnt lgkmcnt(3)
	v_lshlrev_b32_e32 v144, 16, v144
	s_waitcnt lgkmcnt(2)
	v_lshlrev_b32_e32 v145, 16, v145
	s_waitcnt lgkmcnt(1)
	v_lshlrev_b32_e32 v146, 16, v146
	v_mul_f32_e32 v142, v142, v143
	v_mul_f32_e32 v115, v115, v142
	ds_read_u16 v142, v2 offset:42240
	ds_read_u16 v143, v2 offset:42768
	s_waitcnt lgkmcnt(2)
	v_lshlrev_b32_e32 v147, 16, v147
	s_waitcnt lgkmcnt(1)
	v_lshlrev_b32_e32 v142, 16, v142
	s_waitcnt lgkmcnt(0)
; DI float bf2f(u16 h) { return __uint_as_float(((unsigned)h) << 16); }
; DI float gelu_tanh(float x) { float u = 0.7978845608028654f * (x + 0.044715f * x * x * x); return x * sigmoidf_(2.f * u); }
; DI void ffup_tile(const Params& p, int l, int mt, int nt, char* smem) {
;     ...
;       for (int m = 0; m < 8; ++m) {
;         if ((m & 1) == 0) asm volatile("" ::: "memory");
;         const int t = (row0 + wr * 128 + m * 16 + fq * 4) & 8191;
;         float g[6];
; #pragma unroll
;         for (int d = 0; d < 6; ++d) { const float gv = bf2f(img[(m * 16 + d) * IMG_LD + n * 16]); g[d] = (d >= 2 || t - 2 + d >= 0) ? gv : 0.f; }
; #pragma unroll
;         for (int j = 0; j < 4; ++j) acc[m][n][j] *= gelu_tanh(cb + w0 * g[j] + w1 * g[j + 1] + w2 * g[j + 2]);
;       }
	v_lshlrev_b32_e32 v143, 16, v143
	v_fma_f32 v142, v138, v142, v141
	v_fmac_f32_e32 v142, v139, v143
	v_fmac_f32_e32 v142, v140, v144
	v_mul_f32_e32 v148, 0x3d372713, v142
	v_mul_f32_e32 v148, v142, v148
	v_fma_f32 v148, v142, v148, v142
	v_mul_f32_e32 v148, 0x3f4c422a, v148
	v_add_f32_e32 v148, v148, v148
	v_mul_f32_e32 v148, 0xbfb8aa3b, v148
	v_exp_f32_e32 v148, v148
	s_nop 0
	v_add_f32_e32 v148, 1.0, v148
	v_rcp_f32_e32 v148, v148
	s_nop 0
	v_mul_f32_e32 v142, v142, v148
	v_mul_f32_e32 v108, v108, v142
	v_fma_f32 v142, v138, v143, v141
	v_fmac_f32_e32 v142, v139, v144
	v_fmac_f32_e32 v142, v140, v145
	v_mul_f32_e32 v143, 0x3d372713, v142
	v_mul_f32_e32 v143, v142, v143
	v_fma_f32 v143, v142, v143, v142
	v_mul_f32_e32 v143, 0x3f4c422a, v143
	v_add_f32_e32 v143, v143, v143
	v_mul_f32_e32 v143, 0xbfb8aa3b, v143
	v_exp_f32_e32 v143, v143
	s_nop 0
	v_add_f32_e32 v143, 1.0, v143
	v_rcp_f32_e32 v143, v143
	s_nop 0
	v_mul_f32_e32 v142, v142, v143
	v_mul_f32_e32 v109, v109, v142
	v_fma_f32 v142, v138, v144, v141
	v_fmac_f32_e32 v142, v139, v145
	v_fmac_f32_e32 v142, v140, v146
	v_mul_f32_e32 v143, 0x3d372713, v142
	v_mul_f32_e32 v143, v142, v143
	v_fma_f32 v143, v142, v143, v142
	v_mul_f32_e32 v143, 0x3f4c422a, v143
	v_add_f32_e32 v143, v143, v143
	v_mul_f32_e32 v143, 0xbfb8aa3b, v143
	v_exp_f32_e32 v143, v143
	ds_read_u16 v144, v2 offset:51744
	v_add_f32_e32 v143, 1.0, v143
	v_rcp_f32_e32 v143, v143
	s_nop 0
	v_mul_f32_e32 v142, v142, v143
	v_mul_f32_e32 v110, v110, v142
	v_fma_f32 v142, v138, v145, v141
	v_fmac_f32_e32 v142, v139, v146
	v_fmac_f32_e32 v142, v140, v147
	v_mul_f32_e32 v143, 0x3d372713, v142
	v_mul_f32_e32 v143, v142, v143
	v_fma_f32 v143, v142, v143, v142
	v_mul_f32_e32 v143, 0x3f4c422a, v143
	v_add_f32_e32 v143, v143, v143
	v_mul_f32_e32 v143, 0xbfb8aa3b, v143
	v_exp_f32_e32 v143, v143
	ds_read_u16 v145, v2 offset:52272
	ds_read_u16 v146, v2 offset:52800
	ds_read_u16 v147, v2 offset:53328
	v_add_f32_e32 v143, 1.0, v143
	v_rcp_f32_e32 v143, v143
	s_waitcnt lgkmcnt(3)
	v_lshlrev_b32_e32 v144, 16, v144
	s_waitcnt lgkmcnt(2)
	v_lshlrev_b32_e32 v145, 16, v145
	s_waitcnt lgkmcnt(1)
	v_lshlrev_b32_e32 v146, 16, v146
	v_mul_f32_e32 v142, v142, v143
	v_mul_f32_e32 v111, v111, v142
	ds_read_u16 v142, v2 offset:50688
	ds_read_u16 v143, v2 offset:51216
	s_waitcnt lgkmcnt(2)
	v_lshlrev_b32_e32 v147, 16, v147
	s_waitcnt lgkmcnt(1)
	v_lshlrev_b32_e32 v142, 16, v142
	s_waitcnt lgkmcnt(0)
	v_lshlrev_b32_e32 v143, 16, v143
	v_fma_f32 v142, v138, v142, v141
	v_fmac_f32_e32 v142, v139, v143
	v_fmac_f32_e32 v142, v140, v144
	v_mul_f32_e32 v148, 0x3d372713, v142
	v_mul_f32_e32 v148, v142, v148
	v_fma_f32 v148, v142, v148, v142
	v_mul_f32_e32 v148, 0x3f4c422a, v148
	v_add_f32_e32 v148, v148, v148
	v_mul_f32_e32 v148, 0xbfb8aa3b, v148
	v_exp_f32_e32 v148, v148
	s_nop 0
	v_add_f32_e32 v148, 1.0, v148
	v_rcp_f32_e32 v148, v148
	s_nop 0
	v_mul_f32_e32 v142, v142, v148
	v_mul_f32_e32 v104, v104, v142
	v_fma_f32 v142, v138, v143, v141
	v_fmac_f32_e32 v142, v139, v144
	v_fmac_f32_e32 v142, v140, v145
	v_mul_f32_e32 v143, 0x3d372713, v142
	v_mul_f32_e32 v143, v142, v143
	v_fma_f32 v143, v142, v143, v142
	v_mul_f32_e32 v143, 0x3f4c422a, v143
	v_add_f32_e32 v143, v143, v143
	v_mul_f32_e32 v143, 0xbfb8aa3b, v143
	v_exp_f32_e32 v143, v143
	s_nop 0
	v_add_f32_e32 v143, 1.0, v143
	v_rcp_f32_e32 v143, v143
	s_nop 0
	v_mul_f32_e32 v142, v142, v143
	v_mul_f32_e32 v105, v105, v142
	v_fma_f32 v142, v138, v144, v141
	v_fmac_f32_e32 v142, v139, v145
	v_fmac_f32_e32 v142, v140, v146
	v_mul_f32_e32 v143, 0x3d372713, v142
	v_mul_f32_e32 v143, v142, v143
	v_fma_f32 v143, v142, v143, v142
	v_mul_f32_e32 v143, 0x3f4c422a, v143
	v_add_f32_e32 v143, v143, v143
	v_mul_f32_e32 v143, 0xbfb8aa3b, v143
	v_exp_f32_e32 v143, v143
	ds_read_u16 v144, v2 offset:60192
	v_add_f32_e32 v143, 1.0, v143
	v_rcp_f32_e32 v143, v143
	s_nop 0
	v_mul_f32_e32 v142, v142, v143
	v_mul_f32_e32 v106, v106, v142
	v_fma_f32 v142, v138, v145, v141
	v_fmac_f32_e32 v142, v139, v146
	v_fmac_f32_e32 v142, v140, v147
	v_mul_f32_e32 v143, 0x3d372713, v142
	v_mul_f32_e32 v143, v142, v143
	v_fma_f32 v143, v142, v143, v142
	v_mul_f32_e32 v143, 0x3f4c422a, v143
	v_add_f32_e32 v143, v143, v143
	v_mul_f32_e32 v143, 0xbfb8aa3b, v143
	v_exp_f32_e32 v143, v143
	ds_read_u16 v145, v2 offset:60720
	ds_read_u16 v146, v2 offset:61248
	ds_read_u16 v147, v2 offset:61776
	v_add_f32_e32 v143, 1.0, v143
	v_rcp_f32_e32 v143, v143
	s_waitcnt lgkmcnt(3)
	v_lshlrev_b32_e32 v144, 16, v144
	s_waitcnt lgkmcnt(2)
	v_lshlrev_b32_e32 v145, 16, v145
	s_waitcnt lgkmcnt(1)
	v_lshlrev_b32_e32 v146, 16, v146
	v_mul_f32_e32 v142, v142, v143
	v_mul_f32_e32 v107, v107, v142
	ds_read_u16 v142, v2 offset:59136
	ds_read_u16 v143, v2 offset:59664
	s_waitcnt lgkmcnt(2)
	v_lshlrev_b32_e32 v147, 16, v147
	s_waitcnt lgkmcnt(1)
	v_lshlrev_b32_e32 v142, 16, v142
	s_waitcnt lgkmcnt(0)
; DI float bf2f(u16 h) { return __uint_as_float(((unsigned)h) << 16); }
; DI float gelu_tanh(float x) { float u = 0.7978845608028654f * (x + 0.044715f * x * x * x); return x * sigmoidf_(2.f * u); }
; DI float sigmoidf_(float x) { return __builtin_amdgcn_rcpf(1.f + __expf(-x)); }
; DI void ffup_tile(const Params& p, int l, int mt, int nt, char* smem) {
;     ...
;     const u16* img = (const u16*)smem + (wr * 128 + fq * 4) * IMG_LD + wc * 64 + fr;
; #pragma unroll
;     for (int n = 0; n < 4; ++n) {
;       const int col = col0 + wc * 64 + n * 16 + fr;
;       const float* cw = p.in[30] + (size_t)l * 3 * DFF + col;
;       const float w0 = cw[0], w1 = cw[DFF], w2 = cw[2 * DFF], cb = p.in[31][(size_t)l * DFF + col];
; #pragma unroll
;       for (int m = 0; m < 8; ++m) {
;         if ((m & 1) == 0) asm volatile("" ::: "memory");
;         const int t = (row0 + wr * 128 + m * 16 + fq * 4) & 8191;
;         float g[6];
; #pragma unroll
;         for (int d = 0; d < 6; ++d) { const float gv = bf2f(img[(m * 16 + d) * IMG_LD + n * 16]); g[d] = (d >= 2 || t - 2 + d >= 0) ? gv : 0.f; }
; #pragma unroll
;         for (int j = 0; j < 4; ++j) acc[m][n][j] *= gelu_tanh(cb + w0 * g[j] + w1 * g[j + 1] + w2 * g[j + 2]);
;       }
	v_lshlrev_b32_e32 v143, 16, v143
	v_fma_f32 v142, v138, v142, v141
	v_fmac_f32_e32 v142, v139, v143
	v_fmac_f32_e32 v142, v140, v144
	v_mul_f32_e32 v148, 0x3d372713, v142
	v_mul_f32_e32 v148, v142, v148
	v_fma_f32 v148, v142, v148, v142
	v_mul_f32_e32 v148, 0x3f4c422a, v148
	v_add_f32_e32 v148, v148, v148
	v_mul_f32_e32 v148, 0xbfb8aa3b, v148
	v_exp_f32_e32 v148, v148
	s_nop 0
	v_add_f32_e32 v148, 1.0, v148
	v_rcp_f32_e32 v148, v148
	s_nop 0
	v_mul_f32_e32 v142, v142, v148
	v_mul_f32_e32 v100, v100, v142
	v_fma_f32 v142, v138, v143, v141
	v_fmac_f32_e32 v142, v139, v144
	v_fmac_f32_e32 v142, v140, v145
	v_mul_f32_e32 v143, 0x3d372713, v142
	v_mul_f32_e32 v143, v142, v143
	v_fma_f32 v143, v142, v143, v142
	v_mul_f32_e32 v143, 0x3f4c422a, v143
	v_add_f32_e32 v143, v143, v143
	v_mul_f32_e32 v143, 0xbfb8aa3b, v143
	v_exp_f32_e32 v143, v143
	s_nop 0
	v_add_f32_e32 v143, 1.0, v143
	v_rcp_f32_e32 v143, v143
	s_nop 0
	v_mul_f32_e32 v142, v142, v143
	v_mul_f32_e32 v101, v101, v142
	v_fma_f32 v142, v138, v144, v141
	v_fmac_f32_e32 v141, v138, v145
	v_fmac_f32_e32 v141, v139, v146
	v_fmac_f32_e32 v141, v140, v147
	v_mul_f32_e32 v138, 0x3d372713, v141
	v_mul_f32_e32 v138, v141, v138
	v_fma_f32 v138, v141, v138, v141
	v_mul_f32_e32 v138, 0x3f4c422a, v138
	v_add_f32_e32 v138, v138, v138
	v_mul_f32_e32 v138, 0xbfb8aa3b, v138
	v_exp_f32_e32 v138, v138
	v_fmac_f32_e32 v142, v139, v145
	v_fmac_f32_e32 v142, v140, v146
	v_mul_f32_e32 v143, 0x3d372713, v142
	v_add_f32_e32 v138, 1.0, v138
	v_rcp_f32_e32 v138, v138
	v_mul_f32_e32 v143, v142, v143
	v_fma_f32 v143, v142, v143, v142
	v_mul_f32_e32 v143, 0x3f4c422a, v143
	v_mul_f32_e32 v138, v141, v138
	v_mul_f32_e32 v103, v103, v138
	v_add_f32_e32 v143, v143, v143
	v_mul_f32_e32 v143, 0xbfb8aa3b, v143
	v_exp_f32_e32 v143, v143
	ds_read_u16 v144, v2 offset:1088
	ds_read_u16 v145, v2 offset:1616
	ds_read_u16 v146, v2 offset:2144
	ds_read_u16 v147, v2 offset:2672
	v_add_f32_e32 v143, 1.0, v143
	v_rcp_f32_e32 v143, v143
	s_waitcnt lgkmcnt(3)
	v_lshlrev_b32_e32 v144, 16, v144
	s_waitcnt lgkmcnt(2)
	v_lshlrev_b32_e32 v145, 16, v145
	s_waitcnt lgkmcnt(1)
	v_lshlrev_b32_e32 v146, 16, v146
	v_mul_f32_e32 v142, v142, v143
	v_mul_f32_e32 v102, v102, v142
	ds_read_u16 v142, v2 offset:32
	ds_read_u16 v143, v2 offset:560
	s_waitcnt lgkmcnt(2)
	v_lshlrev_b32_e32 v147, 16, v147
	s_waitcnt lgkmcnt(1)
	v_lshlrev_b32_e32 v142, 16, v142
	v_cndmask_b32_e64 v142, v142, 0, vcc
	s_waitcnt lgkmcnt(0)
	v_lshlrev_b32_e32 v143, 16, v143
	v_cndmask_b32_e64 v143, v143, 0, vcc
	s_waitcnt vmcnt(8)
	v_fma_f32 v142, v150, v142, v153
	v_fmac_f32_e32 v142, v151, v143
	v_fmac_f32_e32 v142, v152, v144
	v_mul_f32_e32 v148, 0x3d372713, v142
	v_mul_f32_e32 v148, v142, v148
	v_fma_f32 v148, v142, v148, v142
	v_mul_f32_e32 v148, 0x3f4c422a, v148
	v_add_f32_e32 v148, v148, v148
	v_mul_f32_e32 v148, 0xbfb8aa3b, v148
	v_exp_f32_e32 v148, v148
	s_nop 0
	v_add_f32_e32 v148, 1.0, v148
	v_rcp_f32_e32 v148, v148
	s_nop 0
	v_mul_f32_e32 v142, v142, v148
	v_mul_f32_e32 v96, v96, v142
	v_fma_f32 v142, v150, v143, v153
	v_fmac_f32_e32 v142, v151, v144
	v_fmac_f32_e32 v142, v152, v145
	v_mul_f32_e32 v143, 0x3d372713, v142
	v_mul_f32_e32 v143, v142, v143
	v_fma_f32 v143, v142, v143, v142
	v_mul_f32_e32 v143, 0x3f4c422a, v143
	v_add_f32_e32 v143, v143, v143
	v_mul_f32_e32 v143, 0xbfb8aa3b, v143
	v_exp_f32_e32 v143, v143
	s_nop 0
	v_add_f32_e32 v143, 1.0, v143
	v_rcp_f32_e32 v143, v143
	s_nop 0
	v_mul_f32_e32 v142, v142, v143
	v_mul_f32_e32 v97, v97, v142
	v_fma_f32 v142, v150, v144, v153
	v_fmac_f32_e32 v142, v151, v145
	v_fmac_f32_e32 v142, v152, v146
	v_mul_f32_e32 v143, 0x3d372713, v142
	v_mul_f32_e32 v143, v142, v143
	v_fma_f32 v143, v142, v143, v142
	v_mul_f32_e32 v143, 0x3f4c422a, v143
	v_add_f32_e32 v143, v143, v143
	v_mul_f32_e32 v143, 0xbfb8aa3b, v143
	v_exp_f32_e32 v143, v143
	ds_read_u16 v144, v2 offset:9536
	v_add_f32_e32 v143, 1.0, v143
	v_rcp_f32_e32 v143, v143
	s_nop 0
	v_mul_f32_e32 v142, v142, v143
	v_mul_f32_e32 v98, v98, v142
	v_fma_f32 v142, v150, v145, v153
	v_fmac_f32_e32 v142, v151, v146
	v_fmac_f32_e32 v142, v152, v147
	v_mul_f32_e32 v143, 0x3d372713, v142
	v_mul_f32_e32 v143, v142, v143
	v_fma_f32 v143, v142, v143, v142
	v_mul_f32_e32 v143, 0x3f4c422a, v143
	v_add_f32_e32 v143, v143, v143
	v_mul_f32_e32 v143, 0xbfb8aa3b, v143
	v_exp_f32_e32 v143, v143
	ds_read_u16 v145, v2 offset:10064
	ds_read_u16 v146, v2 offset:10592
	ds_read_u16 v147, v2 offset:11120
	v_add_f32_e32 v143, 1.0, v143
	v_rcp_f32_e32 v143, v143
	s_waitcnt lgkmcnt(3)
	v_lshlrev_b32_e32 v144, 16, v144
	s_waitcnt lgkmcnt(2)
	v_lshlrev_b32_e32 v145, 16, v145
	s_waitcnt lgkmcnt(1)
	v_lshlrev_b32_e32 v146, 16, v146
	v_mul_f32_e32 v142, v142, v143
	v_mul_f32_e32 v99, v99, v142
	ds_read_u16 v142, v2 offset:8480
	ds_read_u16 v143, v2 offset:9008
	s_waitcnt lgkmcnt(2)
	v_lshlrev_b32_e32 v147, 16, v147
	s_waitcnt lgkmcnt(1)
	v_lshlrev_b32_e32 v142, 16, v142
	s_waitcnt lgkmcnt(0)
; DI float bf2f(u16 h) { return __uint_as_float(((unsigned)h) << 16); }
; DI float gelu_tanh(float x) { float u = 0.7978845608028654f * (x + 0.044715f * x * x * x); return x * sigmoidf_(2.f * u); }
; DI float sigmoidf_(float x) { return __builtin_amdgcn_rcpf(1.f + __expf(-x)); }
; DI void ffup_tile(const Params& p, int l, int mt, int nt, char* smem) {
;     ...
;       for (int m = 0; m < 8; ++m) {
;         if ((m & 1) == 0) asm volatile("" ::: "memory");
;         const int t = (row0 + wr * 128 + m * 16 + fq * 4) & 8191;
;         float g[6];
; #pragma unroll
;         for (int d = 0; d < 6; ++d) { const float gv = bf2f(img[(m * 16 + d) * IMG_LD + n * 16]); g[d] = (d >= 2 || t - 2 + d >= 0) ? gv : 0.f; }
; #pragma unroll
;         for (int j = 0; j < 4; ++j) acc[m][n][j] *= gelu_tanh(cb + w0 * g[j] + w1 * g[j + 1] + w2 * g[j + 2]);
;       }
	v_lshlrev_b32_e32 v143, 16, v143
	v_fma_f32 v142, v150, v142, v153
	v_fmac_f32_e32 v142, v151, v143
	v_fmac_f32_e32 v142, v152, v144
	v_mul_f32_e32 v148, 0x3d372713, v142
	v_mul_f32_e32 v148, v142, v148
	v_fma_f32 v148, v142, v148, v142
	v_mul_f32_e32 v148, 0x3f4c422a, v148
	v_add_f32_e32 v148, v148, v148
	v_mul_f32_e32 v148, 0xbfb8aa3b, v148
	v_exp_f32_e32 v148, v148
	s_nop 0
	v_add_f32_e32 v148, 1.0, v148
	v_rcp_f32_e32 v148, v148
	s_nop 0
	v_mul_f32_e32 v142, v142, v148
	v_mul_f32_e32 v92, v92, v142
	v_fma_f32 v142, v150, v143, v153
	v_fmac_f32_e32 v142, v151, v144
	v_fmac_f32_e32 v142, v152, v145
	v_mul_f32_e32 v143, 0x3d372713, v142
	v_mul_f32_e32 v143, v142, v143
	v_fma_f32 v143, v142, v143, v142
	v_mul_f32_e32 v143, 0x3f4c422a, v143
	v_add_f32_e32 v143, v143, v143
	v_mul_f32_e32 v143, 0xbfb8aa3b, v143
	v_exp_f32_e32 v143, v143
	s_nop 0
	v_add_f32_e32 v143, 1.0, v143
	v_rcp_f32_e32 v143, v143
	s_nop 0
	v_mul_f32_e32 v142, v142, v143
	v_mul_f32_e32 v93, v93, v142
	v_fma_f32 v142, v150, v144, v153
	v_fmac_f32_e32 v142, v151, v145
	v_fmac_f32_e32 v142, v152, v146
	v_mul_f32_e32 v143, 0x3d372713, v142
	v_mul_f32_e32 v143, v142, v143
	v_fma_f32 v143, v142, v143, v142
	v_mul_f32_e32 v143, 0x3f4c422a, v143
	v_add_f32_e32 v143, v143, v143
	v_mul_f32_e32 v143, 0xbfb8aa3b, v143
	v_exp_f32_e32 v143, v143
	ds_read_u16 v144, v2 offset:17984
	v_add_f32_e32 v143, 1.0, v143
	v_rcp_f32_e32 v143, v143
	s_nop 0
	v_mul_f32_e32 v142, v142, v143
	v_mul_f32_e32 v94, v94, v142
	v_fma_f32 v142, v150, v145, v153
	v_fmac_f32_e32 v142, v151, v146
	v_fmac_f32_e32 v142, v152, v147
	v_mul_f32_e32 v143, 0x3d372713, v142
	v_mul_f32_e32 v143, v142, v143
	v_fma_f32 v143, v142, v143, v142
	v_mul_f32_e32 v143, 0x3f4c422a, v143
	v_add_f32_e32 v143, v143, v143
	v_mul_f32_e32 v143, 0xbfb8aa3b, v143
	v_exp_f32_e32 v143, v143
	ds_read_u16 v145, v2 offset:18512
	ds_read_u16 v146, v2 offset:19040
	ds_read_u16 v147, v2 offset:19568
	v_add_f32_e32 v143, 1.0, v143
	v_rcp_f32_e32 v143, v143
	s_waitcnt lgkmcnt(3)
	v_lshlrev_b32_e32 v144, 16, v144
	s_waitcnt lgkmcnt(2)
	v_lshlrev_b32_e32 v145, 16, v145
	s_waitcnt lgkmcnt(1)
	v_lshlrev_b32_e32 v146, 16, v146
	v_mul_f32_e32 v142, v142, v143
	v_mul_f32_e32 v95, v95, v142
	ds_read_u16 v142, v2 offset:16928
	ds_read_u16 v143, v2 offset:17456
	s_waitcnt lgkmcnt(2)
	v_lshlrev_b32_e32 v147, 16, v147
	s_waitcnt lgkmcnt(1)
	v_lshlrev_b32_e32 v142, 16, v142
	s_waitcnt lgkmcnt(0)
	v_lshlrev_b32_e32 v143, 16, v143
	v_fma_f32 v142, v150, v142, v153
	v_fmac_f32_e32 v142, v151, v143
	v_fmac_f32_e32 v142, v152, v144
	v_mul_f32_e32 v148, 0x3d372713, v142
	v_mul_f32_e32 v148, v142, v148
	v_fma_f32 v148, v142, v148, v142
	v_mul_f32_e32 v148, 0x3f4c422a, v148
	v_add_f32_e32 v148, v148, v148
	v_mul_f32_e32 v148, 0xbfb8aa3b, v148
	v_exp_f32_e32 v148, v148
	s_nop 0
	v_add_f32_e32 v148, 1.0, v148
	v_rcp_f32_e32 v148, v148
	s_nop 0
	v_mul_f32_e32 v142, v142, v148
	v_mul_f32_e32 v88, v88, v142
	v_fma_f32 v142, v150, v143, v153
	v_fmac_f32_e32 v142, v151, v144
	v_fmac_f32_e32 v142, v152, v145
	v_mul_f32_e32 v143, 0x3d372713, v142
	v_mul_f32_e32 v143, v142, v143
	v_fma_f32 v143, v142, v143, v142
	v_mul_f32_e32 v143, 0x3f4c422a, v143
	v_add_f32_e32 v143, v143, v143
	v_mul_f32_e32 v143, 0xbfb8aa3b, v143
	v_exp_f32_e32 v143, v143
	s_nop 0
	v_add_f32_e32 v143, 1.0, v143
	v_rcp_f32_e32 v143, v143
	s_nop 0
	v_mul_f32_e32 v142, v142, v143
	v_mul_f32_e32 v89, v89, v142
	v_fma_f32 v142, v150, v144, v153
	v_fmac_f32_e32 v142, v151, v145
	v_fmac_f32_e32 v142, v152, v146
	v_mul_f32_e32 v143, 0x3d372713, v142
	v_mul_f32_e32 v143, v142, v143
	v_fma_f32 v143, v142, v143, v142
	v_mul_f32_e32 v143, 0x3f4c422a, v143
	v_add_f32_e32 v143, v143, v143
	v_mul_f32_e32 v143, 0xbfb8aa3b, v143
	v_exp_f32_e32 v143, v143
	ds_read_u16 v144, v2 offset:26432
	v_add_f32_e32 v143, 1.0, v143
	v_rcp_f32_e32 v143, v143
	s_nop 0
	v_mul_f32_e32 v142, v142, v143
	v_mul_f32_e32 v90, v90, v142
	v_fma_f32 v142, v150, v145, v153
	v_fmac_f32_e32 v142, v151, v146
	v_fmac_f32_e32 v142, v152, v147
	v_mul_f32_e32 v143, 0x3d372713, v142
	v_mul_f32_e32 v143, v142, v143
	v_fma_f32 v143, v142, v143, v142
	v_mul_f32_e32 v143, 0x3f4c422a, v143
	v_add_f32_e32 v143, v143, v143
	v_mul_f32_e32 v143, 0xbfb8aa3b, v143
	v_exp_f32_e32 v143, v143
	ds_read_u16 v145, v2 offset:26960
	ds_read_u16 v146, v2 offset:27488
	ds_read_u16 v147, v2 offset:28016
	v_add_f32_e32 v143, 1.0, v143
	v_rcp_f32_e32 v143, v143
	s_waitcnt lgkmcnt(3)
	v_lshlrev_b32_e32 v144, 16, v144
	s_waitcnt lgkmcnt(2)
	v_lshlrev_b32_e32 v145, 16, v145
	s_waitcnt lgkmcnt(1)
	v_lshlrev_b32_e32 v146, 16, v146
	v_mul_f32_e32 v142, v142, v143
	v_mul_f32_e32 v91, v91, v142
	ds_read_u16 v142, v2 offset:25376
	ds_read_u16 v143, v2 offset:25904
	s_waitcnt lgkmcnt(2)
	v_lshlrev_b32_e32 v147, 16, v147
	s_waitcnt lgkmcnt(1)
	v_lshlrev_b32_e32 v142, 16, v142
	s_waitcnt lgkmcnt(0)
; DI float bf2f(u16 h) { return __uint_as_float(((unsigned)h) << 16); }
; DI float gelu_tanh(float x) { float u = 0.7978845608028654f * (x + 0.044715f * x * x * x); return x * sigmoidf_(2.f * u); }
; DI float sigmoidf_(float x) { return __builtin_amdgcn_rcpf(1.f + __expf(-x)); }
; DI void ffup_tile(const Params& p, int l, int mt, int nt, char* smem) {
;     ...
;       for (int m = 0; m < 8; ++m) {
;         if ((m & 1) == 0) asm volatile("" ::: "memory");
;         const int t = (row0 + wr * 128 + m * 16 + fq * 4) & 8191;
;         float g[6];
; #pragma unroll
;         for (int d = 0; d < 6; ++d) { const float gv = bf2f(img[(m * 16 + d) * IMG_LD + n * 16]); g[d] = (d >= 2 || t - 2 + d >= 0) ? gv : 0.f; }
; #pragma unroll
;         for (int j = 0; j < 4; ++j) acc[m][n][j] *= gelu_tanh(cb + w0 * g[j] + w1 * g[j + 1] + w2 * g[j + 2]);
;       }
	v_lshlrev_b32_e32 v143, 16, v143
	v_fma_f32 v142, v150, v142, v153
	v_fmac_f32_e32 v142, v151, v143
	v_fmac_f32_e32 v142, v152, v144
	v_mul_f32_e32 v148, 0x3d372713, v142
	v_mul_f32_e32 v148, v142, v148
	v_fma_f32 v148, v142, v148, v142
	v_mul_f32_e32 v148, 0x3f4c422a, v148
	v_add_f32_e32 v148, v148, v148
	v_mul_f32_e32 v148, 0xbfb8aa3b, v148
	v_exp_f32_e32 v148, v148
	s_nop 0
	v_add_f32_e32 v148, 1.0, v148
	v_rcp_f32_e32 v148, v148
	s_nop 0
	v_mul_f32_e32 v142, v142, v148
	v_mul_f32_e32 v84, v84, v142
	v_fma_f32 v142, v150, v143, v153
	v_fmac_f32_e32 v142, v151, v144
	v_fmac_f32_e32 v142, v152, v145
	v_mul_f32_e32 v143, 0x3d372713, v142
	v_mul_f32_e32 v143, v142, v143
	v_fma_f32 v143, v142, v143, v142
	v_mul_f32_e32 v143, 0x3f4c422a, v143
	v_add_f32_e32 v143, v143, v143
	v_mul_f32_e32 v143, 0xbfb8aa3b, v143
	v_exp_f32_e32 v143, v143
	s_nop 0
	v_add_f32_e32 v143, 1.0, v143
	v_rcp_f32_e32 v143, v143
	s_nop 0
	v_mul_f32_e32 v142, v142, v143
	v_mul_f32_e32 v85, v85, v142
	v_fma_f32 v142, v150, v144, v153
	v_fmac_f32_e32 v142, v151, v145
	v_fmac_f32_e32 v142, v152, v146
	v_mul_f32_e32 v143, 0x3d372713, v142
	v_mul_f32_e32 v143, v142, v143
	v_fma_f32 v143, v142, v143, v142
	v_mul_f32_e32 v143, 0x3f4c422a, v143
	v_add_f32_e32 v143, v143, v143
	v_mul_f32_e32 v143, 0xbfb8aa3b, v143
	v_exp_f32_e32 v143, v143
	ds_read_u16 v144, v2 offset:34880
	v_add_f32_e32 v143, 1.0, v143
	v_rcp_f32_e32 v143, v143
	s_nop 0
	v_mul_f32_e32 v142, v142, v143
	v_mul_f32_e32 v86, v86, v142
	v_fma_f32 v142, v150, v145, v153
	v_fmac_f32_e32 v142, v151, v146
	v_fmac_f32_e32 v142, v152, v147
	v_mul_f32_e32 v143, 0x3d372713, v142
	v_mul_f32_e32 v143, v142, v143
	v_fma_f32 v143, v142, v143, v142
	v_mul_f32_e32 v143, 0x3f4c422a, v143
	v_add_f32_e32 v143, v143, v143
	v_mul_f32_e32 v143, 0xbfb8aa3b, v143
	v_exp_f32_e32 v143, v143
	ds_read_u16 v145, v2 offset:35408
	ds_read_u16 v146, v2 offset:35936
	ds_read_u16 v147, v2 offset:36464
	v_add_f32_e32 v143, 1.0, v143
	v_rcp_f32_e32 v143, v143
	s_waitcnt lgkmcnt(3)
	v_lshlrev_b32_e32 v144, 16, v144
	s_waitcnt lgkmcnt(2)
	v_lshlrev_b32_e32 v145, 16, v145
	s_waitcnt lgkmcnt(1)
	v_lshlrev_b32_e32 v146, 16, v146
	v_mul_f32_e32 v142, v142, v143
	v_mul_f32_e32 v87, v87, v142
	ds_read_u16 v142, v2 offset:33824
	ds_read_u16 v143, v2 offset:34352
	s_waitcnt lgkmcnt(2)
	v_lshlrev_b32_e32 v147, 16, v147
	s_waitcnt lgkmcnt(1)
	v_lshlrev_b32_e32 v142, 16, v142
	s_waitcnt lgkmcnt(0)
	v_lshlrev_b32_e32 v143, 16, v143
	v_fma_f32 v142, v150, v142, v153
	v_fmac_f32_e32 v142, v151, v143
	v_fmac_f32_e32 v142, v152, v144
	v_mul_f32_e32 v148, 0x3d372713, v142
	v_mul_f32_e32 v148, v142, v148
	v_fma_f32 v148, v142, v148, v142
	v_mul_f32_e32 v148, 0x3f4c422a, v148
	v_add_f32_e32 v148, v148, v148
	v_mul_f32_e32 v148, 0xbfb8aa3b, v148
	v_exp_f32_e32 v148, v148
	s_nop 0
	v_add_f32_e32 v148, 1.0, v148
	v_rcp_f32_e32 v148, v148
	s_nop 0
	v_mul_f32_e32 v142, v142, v148
	v_mul_f32_e32 v80, v80, v142
	v_fma_f32 v142, v150, v143, v153
	v_fmac_f32_e32 v142, v151, v144
	v_fmac_f32_e32 v142, v152, v145
	v_mul_f32_e32 v143, 0x3d372713, v142
	v_mul_f32_e32 v143, v142, v143
	v_fma_f32 v143, v142, v143, v142
	v_mul_f32_e32 v143, 0x3f4c422a, v143
	v_add_f32_e32 v143, v143, v143
	v_mul_f32_e32 v143, 0xbfb8aa3b, v143
	v_exp_f32_e32 v143, v143
	s_nop 0
	v_add_f32_e32 v143, 1.0, v143
	v_rcp_f32_e32 v143, v143
	s_nop 0
	v_mul_f32_e32 v142, v142, v143
	v_mul_f32_e32 v81, v81, v142
	v_fma_f32 v142, v150, v144, v153
	v_fmac_f32_e32 v142, v151, v145
	v_fmac_f32_e32 v142, v152, v146
	v_mul_f32_e32 v143, 0x3d372713, v142
	v_mul_f32_e32 v143, v142, v143
	v_fma_f32 v143, v142, v143, v142
	v_mul_f32_e32 v143, 0x3f4c422a, v143
	v_add_f32_e32 v143, v143, v143
	v_mul_f32_e32 v143, 0xbfb8aa3b, v143
	v_exp_f32_e32 v143, v143
	ds_read_u16 v144, v2 offset:43328
	v_add_f32_e32 v143, 1.0, v143
	v_rcp_f32_e32 v143, v143
	s_nop 0
	v_mul_f32_e32 v142, v142, v143
	v_mul_f32_e32 v82, v82, v142
	v_fma_f32 v142, v150, v145, v153
	v_fmac_f32_e32 v142, v151, v146
	v_fmac_f32_e32 v142, v152, v147
	v_mul_f32_e32 v143, 0x3d372713, v142
	v_mul_f32_e32 v143, v142, v143
	v_fma_f32 v143, v142, v143, v142
	v_mul_f32_e32 v143, 0x3f4c422a, v143
	v_add_f32_e32 v143, v143, v143
	v_mul_f32_e32 v143, 0xbfb8aa3b, v143
	v_exp_f32_e32 v143, v143
	ds_read_u16 v145, v2 offset:43856
	ds_read_u16 v146, v2 offset:44384
	ds_read_u16 v147, v2 offset:44912
	v_add_f32_e32 v143, 1.0, v143
	v_rcp_f32_e32 v143, v143
	s_waitcnt lgkmcnt(3)
	v_lshlrev_b32_e32 v144, 16, v144
	s_waitcnt lgkmcnt(2)
	v_lshlrev_b32_e32 v145, 16, v145
	s_waitcnt lgkmcnt(1)
	v_lshlrev_b32_e32 v146, 16, v146
	v_mul_f32_e32 v142, v142, v143
	v_mul_f32_e32 v83, v83, v142
	ds_read_u16 v142, v2 offset:42272
	ds_read_u16 v143, v2 offset:42800
	s_waitcnt lgkmcnt(2)
	v_lshlrev_b32_e32 v147, 16, v147
	s_waitcnt lgkmcnt(1)
	v_lshlrev_b32_e32 v142, 16, v142
	s_waitcnt lgkmcnt(0)
; DI float bf2f(u16 h) { return __uint_as_float(((unsigned)h) << 16); }
; DI float gelu_tanh(float x) { float u = 0.7978845608028654f * (x + 0.044715f * x * x * x); return x * sigmoidf_(2.f * u); }
; DI float sigmoidf_(float x) { return __builtin_amdgcn_rcpf(1.f + __expf(-x)); }
; DI void ffup_tile(const Params& p, int l, int mt, int nt, char* smem) {
;     ...
;       for (int m = 0; m < 8; ++m) {
;         if ((m & 1) == 0) asm volatile("" ::: "memory");
;         const int t = (row0 + wr * 128 + m * 16 + fq * 4) & 8191;
;         float g[6];
; #pragma unroll
;         for (int d = 0; d < 6; ++d) { const float gv = bf2f(img[(m * 16 + d) * IMG_LD + n * 16]); g[d] = (d >= 2 || t - 2 + d >= 0) ? gv : 0.f; }
; #pragma unroll
;         for (int j = 0; j < 4; ++j) acc[m][n][j] *= gelu_tanh(cb + w0 * g[j] + w1 * g[j + 1] + w2 * g[j + 2]);
;       }
	v_lshlrev_b32_e32 v143, 16, v143
	v_fma_f32 v142, v150, v142, v153
	v_fmac_f32_e32 v142, v151, v143
	v_fmac_f32_e32 v142, v152, v144
	v_mul_f32_e32 v148, 0x3d372713, v142
	v_mul_f32_e32 v148, v142, v148
	v_fma_f32 v148, v142, v148, v142
	v_mul_f32_e32 v148, 0x3f4c422a, v148
	v_add_f32_e32 v148, v148, v148
	v_mul_f32_e32 v148, 0xbfb8aa3b, v148
	v_exp_f32_e32 v148, v148
	s_nop 0
	v_add_f32_e32 v148, 1.0, v148
	v_rcp_f32_e32 v148, v148
	s_nop 0
	v_mul_f32_e32 v142, v142, v148
	v_mul_f32_e32 v76, v76, v142
	v_fma_f32 v142, v150, v143, v153
	v_fmac_f32_e32 v142, v151, v144
	v_fmac_f32_e32 v142, v152, v145
	v_mul_f32_e32 v143, 0x3d372713, v142
	v_mul_f32_e32 v143, v142, v143
	v_fma_f32 v143, v142, v143, v142
	v_mul_f32_e32 v143, 0x3f4c422a, v143
	v_add_f32_e32 v143, v143, v143
	v_mul_f32_e32 v143, 0xbfb8aa3b, v143
	v_exp_f32_e32 v143, v143
	s_nop 0
	v_add_f32_e32 v143, 1.0, v143
	v_rcp_f32_e32 v143, v143
	s_nop 0
	v_mul_f32_e32 v142, v142, v143
	v_mul_f32_e32 v77, v77, v142
	v_fma_f32 v142, v150, v144, v153
	v_fmac_f32_e32 v142, v151, v145
	v_fmac_f32_e32 v142, v152, v146
	v_mul_f32_e32 v143, 0x3d372713, v142
	v_mul_f32_e32 v143, v142, v143
	v_fma_f32 v143, v142, v143, v142
	v_mul_f32_e32 v143, 0x3f4c422a, v143
	v_add_f32_e32 v143, v143, v143
	v_mul_f32_e32 v143, 0xbfb8aa3b, v143
	v_exp_f32_e32 v143, v143
	ds_read_u16 v144, v2 offset:51776
	v_add_f32_e32 v143, 1.0, v143
	v_rcp_f32_e32 v143, v143
	s_nop 0
	v_mul_f32_e32 v142, v142, v143
	v_mul_f32_e32 v78, v78, v142
	v_fma_f32 v142, v150, v145, v153
	v_fmac_f32_e32 v142, v151, v146
	v_fmac_f32_e32 v142, v152, v147
	v_mul_f32_e32 v143, 0x3d372713, v142
	v_mul_f32_e32 v143, v142, v143
	v_fma_f32 v143, v142, v143, v142
	v_mul_f32_e32 v143, 0x3f4c422a, v143
	v_add_f32_e32 v143, v143, v143
	v_mul_f32_e32 v143, 0xbfb8aa3b, v143
	v_exp_f32_e32 v143, v143
	ds_read_u16 v145, v2 offset:52304
	ds_read_u16 v146, v2 offset:52832
	ds_read_u16 v147, v2 offset:53360
	v_add_f32_e32 v143, 1.0, v143
	v_rcp_f32_e32 v143, v143
	s_waitcnt lgkmcnt(3)
	v_lshlrev_b32_e32 v144, 16, v144
	s_waitcnt lgkmcnt(2)
	v_lshlrev_b32_e32 v145, 16, v145
	s_waitcnt lgkmcnt(1)
	v_lshlrev_b32_e32 v146, 16, v146
	v_mul_f32_e32 v142, v142, v143
	v_mul_f32_e32 v79, v79, v142
	ds_read_u16 v142, v2 offset:50720
	ds_read_u16 v143, v2 offset:51248
	s_waitcnt lgkmcnt(2)
	v_lshlrev_b32_e32 v147, 16, v147
	s_waitcnt lgkmcnt(1)
	v_lshlrev_b32_e32 v142, 16, v142
	s_waitcnt lgkmcnt(0)
	v_lshlrev_b32_e32 v143, 16, v143
	v_fma_f32 v142, v150, v142, v153
	v_fmac_f32_e32 v142, v151, v143
	v_fmac_f32_e32 v142, v152, v144
	v_mul_f32_e32 v148, 0x3d372713, v142
	v_mul_f32_e32 v148, v142, v148
	v_fma_f32 v148, v142, v148, v142
	v_mul_f32_e32 v148, 0x3f4c422a, v148
	v_add_f32_e32 v148, v148, v148
	v_mul_f32_e32 v148, 0xbfb8aa3b, v148
	v_exp_f32_e32 v148, v148
	s_nop 0
	v_add_f32_e32 v148, 1.0, v148
	v_rcp_f32_e32 v148, v148
	s_nop 0
	v_mul_f32_e32 v142, v142, v148
	v_mul_f32_e32 v72, v72, v142
	v_fma_f32 v142, v150, v143, v153
	v_fmac_f32_e32 v142, v151, v144
	v_fmac_f32_e32 v142, v152, v145
	v_mul_f32_e32 v143, 0x3d372713, v142
	v_mul_f32_e32 v143, v142, v143
	v_fma_f32 v143, v142, v143, v142
	v_mul_f32_e32 v143, 0x3f4c422a, v143
	v_add_f32_e32 v143, v143, v143
	v_mul_f32_e32 v143, 0xbfb8aa3b, v143
	v_exp_f32_e32 v143, v143
	s_nop 0
	v_add_f32_e32 v143, 1.0, v143
	v_rcp_f32_e32 v143, v143
	s_nop 0
	v_mul_f32_e32 v142, v142, v143
	v_mul_f32_e32 v73, v73, v142
	v_fma_f32 v142, v150, v144, v153
	v_fmac_f32_e32 v142, v151, v145
	v_fmac_f32_e32 v142, v152, v146
	v_mul_f32_e32 v143, 0x3d372713, v142
	v_mul_f32_e32 v143, v142, v143
	v_fma_f32 v143, v142, v143, v142
	v_mul_f32_e32 v143, 0x3f4c422a, v143
	v_add_f32_e32 v143, v143, v143
	v_mul_f32_e32 v143, 0xbfb8aa3b, v143
	v_exp_f32_e32 v143, v143
	ds_read_u16 v144, v2 offset:60224
	v_add_f32_e32 v143, 1.0, v143
	v_rcp_f32_e32 v143, v143
	s_nop 0
	v_mul_f32_e32 v142, v142, v143
	v_mul_f32_e32 v74, v74, v142
	v_fma_f32 v142, v150, v145, v153
	v_fmac_f32_e32 v142, v151, v146
	v_fmac_f32_e32 v142, v152, v147
	v_mul_f32_e32 v143, 0x3d372713, v142
	v_mul_f32_e32 v143, v142, v143
	v_fma_f32 v143, v142, v143, v142
	v_mul_f32_e32 v143, 0x3f4c422a, v143
	v_add_f32_e32 v143, v143, v143
	v_mul_f32_e32 v143, 0xbfb8aa3b, v143
	v_exp_f32_e32 v143, v143
	ds_read_u16 v145, v2 offset:60752
	ds_read_u16 v146, v2 offset:61280
	ds_read_u16 v147, v2 offset:61808
	v_add_f32_e32 v143, 1.0, v143
	v_rcp_f32_e32 v143, v143
	s_waitcnt lgkmcnt(3)
	v_lshlrev_b32_e32 v144, 16, v144
	s_waitcnt lgkmcnt(2)
	v_lshlrev_b32_e32 v145, 16, v145
	s_waitcnt lgkmcnt(1)
	v_lshlrev_b32_e32 v146, 16, v146
	v_mul_f32_e32 v142, v142, v143
	v_mul_f32_e32 v75, v75, v142
	ds_read_u16 v142, v2 offset:59168
	ds_read_u16 v143, v2 offset:59696
	s_waitcnt lgkmcnt(2)
	v_lshlrev_b32_e32 v147, 16, v147
	s_waitcnt lgkmcnt(1)
	v_lshlrev_b32_e32 v142, 16, v142
	s_waitcnt lgkmcnt(0)
; DI float bf2f(u16 h) { return __uint_as_float(((unsigned)h) << 16); }
; DI float gelu_tanh(float x) { float u = 0.7978845608028654f * (x + 0.044715f * x * x * x); return x * sigmoidf_(2.f * u); }
; DI float sigmoidf_(float x) { return __builtin_amdgcn_rcpf(1.f + __expf(-x)); }
; DI void ffup_tile(const Params& p, int l, int mt, int nt, char* smem) {
;     ...
;       for (int m = 0; m < 8; ++m) {
;         if ((m & 1) == 0) asm volatile("" ::: "memory");
;         const int t = (row0 + wr * 128 + m * 16 + fq * 4) & 8191;
;         float g[6];
; #pragma unroll
;         for (int d = 0; d < 6; ++d) { const float gv = bf2f(img[(m * 16 + d) * IMG_LD + n * 16]); g[d] = (d >= 2 || t - 2 + d >= 0) ? gv : 0.f; }
; #pragma unroll
;         for (int j = 0; j < 4; ++j) acc[m][n][j] *= gelu_tanh(cb + w0 * g[j] + w1 * g[j + 1] + w2 * g[j + 2]);
;       }
	v_lshlrev_b32_e32 v143, 16, v143
	v_fma_f32 v142, v150, v142, v153
	v_fmac_f32_e32 v142, v151, v143
	v_fmac_f32_e32 v142, v152, v144
	v_mul_f32_e32 v148, 0x3d372713, v142
	v_mul_f32_e32 v148, v142, v148
	v_fma_f32 v148, v142, v148, v142
	v_mul_f32_e32 v148, 0x3f4c422a, v148
	v_add_f32_e32 v148, v148, v148
	v_mul_f32_e32 v148, 0xbfb8aa3b, v148
	v_exp_f32_e32 v148, v148
	s_nop 0
	v_add_f32_e32 v148, 1.0, v148
	v_rcp_f32_e32 v148, v148
	s_nop 0
	v_mul_f32_e32 v142, v142, v148
	v_mul_f32_e32 v68, v68, v142
	v_fma_f32 v142, v150, v143, v153
	v_fmac_f32_e32 v142, v151, v144
	v_fmac_f32_e32 v142, v152, v145
	v_mul_f32_e32 v143, 0x3d372713, v142
	v_mul_f32_e32 v143, v142, v143
	v_fma_f32 v143, v142, v143, v142
	v_mul_f32_e32 v143, 0x3f4c422a, v143
	v_add_f32_e32 v143, v143, v143
	v_mul_f32_e32 v143, 0xbfb8aa3b, v143
	v_exp_f32_e32 v143, v143
	s_nop 0
	v_add_f32_e32 v143, 1.0, v143
	v_rcp_f32_e32 v143, v143
	s_nop 0
	v_mul_f32_e32 v142, v142, v143
	v_mul_f32_e32 v69, v69, v142
	v_fma_f32 v142, v150, v144, v153
	v_fmac_f32_e32 v153, v150, v145
	v_fmac_f32_e32 v153, v151, v146
	v_fmac_f32_e32 v153, v152, v147
	v_mul_f32_e32 v138, 0x3d372713, v153
	v_mul_f32_e32 v138, v153, v138
	v_fma_f32 v138, v153, v138, v153
	v_mul_f32_e32 v138, 0x3f4c422a, v138
	v_add_f32_e32 v138, v138, v138
	v_mul_f32_e32 v138, 0xbfb8aa3b, v138
	v_exp_f32_e32 v138, v138
	v_fmac_f32_e32 v142, v151, v145
	v_fmac_f32_e32 v142, v152, v146
	v_mul_f32_e32 v143, 0x3d372713, v142
	v_add_f32_e32 v138, 1.0, v138
	v_rcp_f32_e32 v138, v138
	v_mul_f32_e32 v143, v142, v143
	v_fma_f32 v143, v142, v143, v142
	v_mul_f32_e32 v143, 0x3f4c422a, v143
	v_mul_f32_e32 v138, v153, v138
	v_mul_f32_e32 v71, v71, v138
	v_add_f32_e32 v143, v143, v143
	v_mul_f32_e32 v143, 0xbfb8aa3b, v143
	v_exp_f32_e32 v143, v143
	ds_read_u16 v144, v2 offset:1120
	ds_read_u16 v145, v2 offset:1648
	ds_read_u16 v146, v2 offset:2176
	ds_read_u16 v147, v2 offset:2704
	v_add_f32_e32 v143, 1.0, v143
	v_rcp_f32_e32 v143, v143
	s_waitcnt lgkmcnt(3)
	v_lshlrev_b32_e32 v144, 16, v144
	s_waitcnt lgkmcnt(2)
	v_lshlrev_b32_e32 v145, 16, v145
	s_waitcnt lgkmcnt(1)
	v_lshlrev_b32_e32 v146, 16, v146
	v_mul_f32_e32 v142, v142, v143
	v_mul_f32_e32 v70, v70, v142
	ds_read_u16 v142, v2 offset:64
	ds_read_u16 v143, v2 offset:592
	s_waitcnt lgkmcnt(2)
	v_lshlrev_b32_e32 v147, 16, v147
	s_waitcnt lgkmcnt(1)
	v_lshlrev_b32_e32 v142, 16, v142
	v_cndmask_b32_e64 v142, v142, 0, vcc
	s_waitcnt lgkmcnt(0)
	v_lshlrev_b32_e32 v143, 16, v143
	v_cndmask_b32_e64 v143, v143, 0, vcc
	s_waitcnt vmcnt(4)
	v_fma_f32 v142, v154, v142, v157
	v_fmac_f32_e32 v142, v155, v143
	v_fmac_f32_e32 v142, v156, v144
	v_mul_f32_e32 v148, 0x3d372713, v142
	v_mul_f32_e32 v148, v142, v148
	v_fma_f32 v148, v142, v148, v142
	v_mul_f32_e32 v148, 0x3f4c422a, v148
	v_add_f32_e32 v148, v148, v148
	v_mul_f32_e32 v148, 0xbfb8aa3b, v148
	v_exp_f32_e32 v148, v148
	s_nop 0
	v_add_f32_e32 v148, 1.0, v148
	v_rcp_f32_e32 v148, v148
	s_nop 0
	v_mul_f32_e32 v142, v142, v148
	v_mul_f32_e32 v64, v64, v142
	v_fma_f32 v142, v154, v143, v157
	v_fmac_f32_e32 v142, v155, v144
	v_fmac_f32_e32 v142, v156, v145
	v_mul_f32_e32 v143, 0x3d372713, v142
	v_mul_f32_e32 v143, v142, v143
	v_fma_f32 v143, v142, v143, v142
	v_mul_f32_e32 v143, 0x3f4c422a, v143
	v_add_f32_e32 v143, v143, v143
	v_mul_f32_e32 v143, 0xbfb8aa3b, v143
	v_exp_f32_e32 v143, v143
	s_nop 0
	v_add_f32_e32 v143, 1.0, v143
	v_rcp_f32_e32 v143, v143
	s_nop 0
	v_mul_f32_e32 v142, v142, v143
	v_mul_f32_e32 v65, v65, v142
	v_fma_f32 v142, v154, v144, v157
	v_fmac_f32_e32 v142, v155, v145
	v_fmac_f32_e32 v142, v156, v146
	v_mul_f32_e32 v143, 0x3d372713, v142
	v_mul_f32_e32 v143, v142, v143
	v_fma_f32 v143, v142, v143, v142
	v_mul_f32_e32 v143, 0x3f4c422a, v143
	v_add_f32_e32 v143, v143, v143
	v_mul_f32_e32 v143, 0xbfb8aa3b, v143
	v_exp_f32_e32 v143, v143
	ds_read_u16 v144, v2 offset:9568
	v_add_f32_e32 v143, 1.0, v143
	v_rcp_f32_e32 v143, v143
	s_nop 0
	v_mul_f32_e32 v142, v142, v143
	v_mul_f32_e32 v66, v66, v142
	v_fma_f32 v142, v154, v145, v157
	v_fmac_f32_e32 v142, v155, v146
	v_fmac_f32_e32 v142, v156, v147
	v_mul_f32_e32 v143, 0x3d372713, v142
	v_mul_f32_e32 v143, v142, v143
	v_fma_f32 v143, v142, v143, v142
	v_mul_f32_e32 v143, 0x3f4c422a, v143
	v_add_f32_e32 v143, v143, v143
	v_mul_f32_e32 v143, 0xbfb8aa3b, v143
	v_exp_f32_e32 v143, v143
	ds_read_u16 v145, v2 offset:10096
	ds_read_u16 v146, v2 offset:10624
	ds_read_u16 v147, v2 offset:11152
	v_add_f32_e32 v143, 1.0, v143
	v_rcp_f32_e32 v143, v143
	s_waitcnt lgkmcnt(3)
	v_lshlrev_b32_e32 v144, 16, v144
	s_waitcnt lgkmcnt(2)
	v_lshlrev_b32_e32 v145, 16, v145
	s_waitcnt lgkmcnt(1)
	v_lshlrev_b32_e32 v146, 16, v146
	v_mul_f32_e32 v142, v142, v143
	v_mul_f32_e32 v67, v67, v142
	ds_read_u16 v142, v2 offset:8512
	ds_read_u16 v143, v2 offset:9040
	s_waitcnt lgkmcnt(2)
	v_lshlrev_b32_e32 v147, 16, v147
	s_waitcnt lgkmcnt(1)
	v_lshlrev_b32_e32 v142, 16, v142
	s_waitcnt lgkmcnt(0)
; DI float bf2f(u16 h) { return __uint_as_float(((unsigned)h) << 16); }
; DI float gelu_tanh(float x) { float u = 0.7978845608028654f * (x + 0.044715f * x * x * x); return x * sigmoidf_(2.f * u); }
; DI float sigmoidf_(float x) { return __builtin_amdgcn_rcpf(1.f + __expf(-x)); }
; DI void ffup_tile(const Params& p, int l, int mt, int nt, char* smem) {
;     ...
;       for (int m = 0; m < 8; ++m) {
;         if ((m & 1) == 0) asm volatile("" ::: "memory");
;         const int t = (row0 + wr * 128 + m * 16 + fq * 4) & 8191;
;         float g[6];
; #pragma unroll
;         for (int d = 0; d < 6; ++d) { const float gv = bf2f(img[(m * 16 + d) * IMG_LD + n * 16]); g[d] = (d >= 2 || t - 2 + d >= 0) ? gv : 0.f; }
; #pragma unroll
;         for (int j = 0; j < 4; ++j) acc[m][n][j] *= gelu_tanh(cb + w0 * g[j] + w1 * g[j + 1] + w2 * g[j + 2]);
;       }
	v_lshlrev_b32_e32 v143, 16, v143
	v_fma_f32 v142, v154, v142, v157
	v_fmac_f32_e32 v142, v155, v143
	v_fmac_f32_e32 v142, v156, v144
	v_mul_f32_e32 v148, 0x3d372713, v142
	v_mul_f32_e32 v148, v142, v148
	v_fma_f32 v148, v142, v148, v142
	v_mul_f32_e32 v148, 0x3f4c422a, v148
	v_add_f32_e32 v148, v148, v148
	v_mul_f32_e32 v148, 0xbfb8aa3b, v148
	v_exp_f32_e32 v148, v148
	s_nop 0
	v_add_f32_e32 v148, 1.0, v148
	v_rcp_f32_e32 v148, v148
	s_nop 0
	v_mul_f32_e32 v142, v142, v148
	v_mul_f32_e32 v60, v60, v142
	v_fma_f32 v142, v154, v143, v157
	v_fmac_f32_e32 v142, v155, v144
	v_fmac_f32_e32 v142, v156, v145
	v_mul_f32_e32 v143, 0x3d372713, v142
	v_mul_f32_e32 v143, v142, v143
	v_fma_f32 v143, v142, v143, v142
	v_mul_f32_e32 v143, 0x3f4c422a, v143
	v_add_f32_e32 v143, v143, v143
	v_mul_f32_e32 v143, 0xbfb8aa3b, v143
	v_exp_f32_e32 v143, v143
	s_nop 0
	v_add_f32_e32 v143, 1.0, v143
	v_rcp_f32_e32 v143, v143
	s_nop 0
	v_mul_f32_e32 v142, v142, v143
	v_mul_f32_e32 v61, v61, v142
	v_fma_f32 v142, v154, v144, v157
	v_fmac_f32_e32 v142, v155, v145
	v_fmac_f32_e32 v142, v156, v146
	v_mul_f32_e32 v143, 0x3d372713, v142
	v_mul_f32_e32 v143, v142, v143
	v_fma_f32 v143, v142, v143, v142
	v_mul_f32_e32 v143, 0x3f4c422a, v143
	v_add_f32_e32 v143, v143, v143
	v_mul_f32_e32 v143, 0xbfb8aa3b, v143
	v_exp_f32_e32 v143, v143
	ds_read_u16 v144, v2 offset:18016
	v_add_f32_e32 v143, 1.0, v143
	v_rcp_f32_e32 v143, v143
	s_nop 0
	v_mul_f32_e32 v142, v142, v143
	v_mul_f32_e32 v62, v62, v142
	v_fma_f32 v142, v154, v145, v157
	v_fmac_f32_e32 v142, v155, v146
	v_fmac_f32_e32 v142, v156, v147
	v_mul_f32_e32 v143, 0x3d372713, v142
	v_mul_f32_e32 v143, v142, v143
	v_fma_f32 v143, v142, v143, v142
	v_mul_f32_e32 v143, 0x3f4c422a, v143
	v_add_f32_e32 v143, v143, v143
	v_mul_f32_e32 v143, 0xbfb8aa3b, v143
	v_exp_f32_e32 v143, v143
	ds_read_u16 v145, v2 offset:18544
	ds_read_u16 v146, v2 offset:19072
	ds_read_u16 v147, v2 offset:19600
	v_add_f32_e32 v143, 1.0, v143
	v_rcp_f32_e32 v143, v143
	s_waitcnt lgkmcnt(3)
	v_lshlrev_b32_e32 v144, 16, v144
	s_waitcnt lgkmcnt(2)
	v_lshlrev_b32_e32 v145, 16, v145
	s_waitcnt lgkmcnt(1)
	v_lshlrev_b32_e32 v146, 16, v146
	v_mul_f32_e32 v142, v142, v143
	v_mul_f32_e32 v63, v63, v142
	ds_read_u16 v142, v2 offset:16960
	ds_read_u16 v143, v2 offset:17488
	s_waitcnt lgkmcnt(2)
	v_lshlrev_b32_e32 v147, 16, v147
	s_waitcnt lgkmcnt(1)
	v_lshlrev_b32_e32 v142, 16, v142
	s_waitcnt lgkmcnt(0)
	v_lshlrev_b32_e32 v143, 16, v143
	v_fma_f32 v142, v154, v142, v157
	v_fmac_f32_e32 v142, v155, v143
	v_fmac_f32_e32 v142, v156, v144
	v_mul_f32_e32 v148, 0x3d372713, v142
	v_mul_f32_e32 v148, v142, v148
	v_fma_f32 v148, v142, v148, v142
	v_mul_f32_e32 v148, 0x3f4c422a, v148
	v_add_f32_e32 v148, v148, v148
	v_mul_f32_e32 v148, 0xbfb8aa3b, v148
	v_exp_f32_e32 v148, v148
	s_nop 0
	v_add_f32_e32 v148, 1.0, v148
	v_rcp_f32_e32 v148, v148
	s_nop 0
	v_mul_f32_e32 v142, v142, v148
	v_mul_f32_e32 v56, v56, v142
	v_fma_f32 v142, v154, v143, v157
	v_fmac_f32_e32 v142, v155, v144
	v_fmac_f32_e32 v142, v156, v145
	v_mul_f32_e32 v143, 0x3d372713, v142
	v_mul_f32_e32 v143, v142, v143
	v_fma_f32 v143, v142, v143, v142
	v_mul_f32_e32 v143, 0x3f4c422a, v143
	v_add_f32_e32 v143, v143, v143
	v_mul_f32_e32 v143, 0xbfb8aa3b, v143
	v_exp_f32_e32 v143, v143
	s_nop 0
	v_add_f32_e32 v143, 1.0, v143
	v_rcp_f32_e32 v143, v143
	s_nop 0
	v_mul_f32_e32 v142, v142, v143
	v_mul_f32_e32 v57, v57, v142
	v_fma_f32 v142, v154, v144, v157
	v_fmac_f32_e32 v142, v155, v145
	v_fmac_f32_e32 v142, v156, v146
	v_mul_f32_e32 v143, 0x3d372713, v142
	v_mul_f32_e32 v143, v142, v143
	v_fma_f32 v143, v142, v143, v142
	v_mul_f32_e32 v143, 0x3f4c422a, v143
	v_add_f32_e32 v143, v143, v143
	v_mul_f32_e32 v143, 0xbfb8aa3b, v143
	v_exp_f32_e32 v143, v143
	ds_read_u16 v144, v2 offset:26464
	v_add_f32_e32 v143, 1.0, v143
	v_rcp_f32_e32 v143, v143
	s_nop 0
	v_mul_f32_e32 v142, v142, v143
	v_mul_f32_e32 v58, v58, v142
	v_fma_f32 v142, v154, v145, v157
	v_fmac_f32_e32 v142, v155, v146
	v_fmac_f32_e32 v142, v156, v147
	v_mul_f32_e32 v143, 0x3d372713, v142
	v_mul_f32_e32 v143, v142, v143
	v_fma_f32 v143, v142, v143, v142
	v_mul_f32_e32 v143, 0x3f4c422a, v143
	v_add_f32_e32 v143, v143, v143
	v_mul_f32_e32 v143, 0xbfb8aa3b, v143
	v_exp_f32_e32 v143, v143
	ds_read_u16 v145, v2 offset:26992
	ds_read_u16 v146, v2 offset:27520
	ds_read_u16 v147, v2 offset:28048
	v_add_f32_e32 v143, 1.0, v143
	v_rcp_f32_e32 v143, v143
	s_waitcnt lgkmcnt(3)
	v_lshlrev_b32_e32 v144, 16, v144
	s_waitcnt lgkmcnt(2)
	v_lshlrev_b32_e32 v145, 16, v145
	s_waitcnt lgkmcnt(1)
	v_lshlrev_b32_e32 v146, 16, v146
	v_mul_f32_e32 v142, v142, v143
	v_mul_f32_e32 v59, v59, v142
	ds_read_u16 v142, v2 offset:25408
	ds_read_u16 v143, v2 offset:25936
	s_waitcnt lgkmcnt(2)
	v_lshlrev_b32_e32 v147, 16, v147
	s_waitcnt lgkmcnt(1)
	v_lshlrev_b32_e32 v142, 16, v142
	s_waitcnt lgkmcnt(0)
; DI float bf2f(u16 h) { return __uint_as_float(((unsigned)h) << 16); }
; DI float gelu_tanh(float x) { float u = 0.7978845608028654f * (x + 0.044715f * x * x * x); return x * sigmoidf_(2.f * u); }
; DI float sigmoidf_(float x) { return __builtin_amdgcn_rcpf(1.f + __expf(-x)); }
; DI void ffup_tile(const Params& p, int l, int mt, int nt, char* smem) {
;     ...
;       for (int m = 0; m < 8; ++m) {
;         if ((m & 1) == 0) asm volatile("" ::: "memory");
;         const int t = (row0 + wr * 128 + m * 16 + fq * 4) & 8191;
;         float g[6];
; #pragma unroll
;         for (int d = 0; d < 6; ++d) { const float gv = bf2f(img[(m * 16 + d) * IMG_LD + n * 16]); g[d] = (d >= 2 || t - 2 + d >= 0) ? gv : 0.f; }
; #pragma unroll
;         for (int j = 0; j < 4; ++j) acc[m][n][j] *= gelu_tanh(cb + w0 * g[j] + w1 * g[j + 1] + w2 * g[j + 2]);
;       }
	v_lshlrev_b32_e32 v143, 16, v143
	v_fma_f32 v142, v154, v142, v157
	v_fmac_f32_e32 v142, v155, v143
	v_fmac_f32_e32 v142, v156, v144
	v_mul_f32_e32 v148, 0x3d372713, v142
	v_mul_f32_e32 v148, v142, v148
	v_fma_f32 v148, v142, v148, v142
	v_mul_f32_e32 v148, 0x3f4c422a, v148
	v_add_f32_e32 v148, v148, v148
	v_mul_f32_e32 v148, 0xbfb8aa3b, v148
	v_exp_f32_e32 v148, v148
	s_nop 0
	v_add_f32_e32 v148, 1.0, v148
	v_rcp_f32_e32 v148, v148
	s_nop 0
	v_mul_f32_e32 v142, v142, v148
	v_mul_f32_e32 v52, v52, v142
	v_fma_f32 v142, v154, v143, v157
	v_fmac_f32_e32 v142, v155, v144
	v_fmac_f32_e32 v142, v156, v145
	v_mul_f32_e32 v143, 0x3d372713, v142
	v_mul_f32_e32 v143, v142, v143
	v_fma_f32 v143, v142, v143, v142
	v_mul_f32_e32 v143, 0x3f4c422a, v143
	v_add_f32_e32 v143, v143, v143
	v_mul_f32_e32 v143, 0xbfb8aa3b, v143
	v_exp_f32_e32 v143, v143
	s_nop 0
	v_add_f32_e32 v143, 1.0, v143
	v_rcp_f32_e32 v143, v143
	s_nop 0
	v_mul_f32_e32 v142, v142, v143
	v_mul_f32_e32 v53, v53, v142
	v_fma_f32 v142, v154, v144, v157
	v_fmac_f32_e32 v142, v155, v145
	v_fmac_f32_e32 v142, v156, v146
	v_mul_f32_e32 v143, 0x3d372713, v142
	v_mul_f32_e32 v143, v142, v143
	v_fma_f32 v143, v142, v143, v142
	v_mul_f32_e32 v143, 0x3f4c422a, v143
	v_add_f32_e32 v143, v143, v143
	v_mul_f32_e32 v143, 0xbfb8aa3b, v143
	v_exp_f32_e32 v143, v143
	ds_read_u16 v144, v2 offset:34912
	v_add_f32_e32 v143, 1.0, v143
	v_rcp_f32_e32 v143, v143
	s_nop 0
	v_mul_f32_e32 v142, v142, v143
	v_mul_f32_e32 v54, v54, v142
	v_fma_f32 v142, v154, v145, v157
	v_fmac_f32_e32 v142, v155, v146
	v_fmac_f32_e32 v142, v156, v147
	v_mul_f32_e32 v143, 0x3d372713, v142
	v_mul_f32_e32 v143, v142, v143
	v_fma_f32 v143, v142, v143, v142
	v_mul_f32_e32 v143, 0x3f4c422a, v143
	v_add_f32_e32 v143, v143, v143
	v_mul_f32_e32 v143, 0xbfb8aa3b, v143
	v_exp_f32_e32 v143, v143
	ds_read_u16 v145, v2 offset:35440
	ds_read_u16 v146, v2 offset:35968
	ds_read_u16 v147, v2 offset:36496
	v_add_f32_e32 v143, 1.0, v143
	v_rcp_f32_e32 v143, v143
	s_waitcnt lgkmcnt(3)
	v_lshlrev_b32_e32 v144, 16, v144
	s_waitcnt lgkmcnt(2)
	v_lshlrev_b32_e32 v145, 16, v145
	s_waitcnt lgkmcnt(1)
	v_lshlrev_b32_e32 v146, 16, v146
	v_mul_f32_e32 v142, v142, v143
	v_mul_f32_e32 v55, v55, v142
	ds_read_u16 v142, v2 offset:33856
	ds_read_u16 v143, v2 offset:34384
	s_waitcnt lgkmcnt(2)
	v_lshlrev_b32_e32 v147, 16, v147
	s_waitcnt lgkmcnt(1)
	v_lshlrev_b32_e32 v142, 16, v142
	s_waitcnt lgkmcnt(0)
	v_lshlrev_b32_e32 v143, 16, v143
	v_fma_f32 v142, v154, v142, v157
	v_fmac_f32_e32 v142, v155, v143
	v_fmac_f32_e32 v142, v156, v144
	v_mul_f32_e32 v148, 0x3d372713, v142
	v_mul_f32_e32 v148, v142, v148
	v_fma_f32 v148, v142, v148, v142
	v_mul_f32_e32 v148, 0x3f4c422a, v148
	v_add_f32_e32 v148, v148, v148
	v_mul_f32_e32 v148, 0xbfb8aa3b, v148
	v_exp_f32_e32 v148, v148
	s_nop 0
	v_add_f32_e32 v148, 1.0, v148
	v_rcp_f32_e32 v148, v148
	s_nop 0
	v_mul_f32_e32 v142, v142, v148
	v_mul_f32_e32 v48, v48, v142
	v_fma_f32 v142, v154, v143, v157
	v_fmac_f32_e32 v142, v155, v144
	v_fmac_f32_e32 v142, v156, v145
	v_mul_f32_e32 v143, 0x3d372713, v142
	v_mul_f32_e32 v143, v142, v143
	v_fma_f32 v143, v142, v143, v142
	v_mul_f32_e32 v143, 0x3f4c422a, v143
	v_add_f32_e32 v143, v143, v143
	v_mul_f32_e32 v143, 0xbfb8aa3b, v143
	v_exp_f32_e32 v143, v143
	s_nop 0
	v_add_f32_e32 v143, 1.0, v143
	v_rcp_f32_e32 v143, v143
	s_nop 0
	v_mul_f32_e32 v142, v142, v143
	v_mul_f32_e32 v49, v49, v142
	v_fma_f32 v142, v154, v144, v157
	v_fmac_f32_e32 v142, v155, v145
	v_fmac_f32_e32 v142, v156, v146
	v_mul_f32_e32 v143, 0x3d372713, v142
	v_mul_f32_e32 v143, v142, v143
	v_fma_f32 v143, v142, v143, v142
	v_mul_f32_e32 v143, 0x3f4c422a, v143
	v_add_f32_e32 v143, v143, v143
	v_mul_f32_e32 v143, 0xbfb8aa3b, v143
	v_exp_f32_e32 v143, v143
	ds_read_u16 v144, v2 offset:43360
	v_add_f32_e32 v143, 1.0, v143
	v_rcp_f32_e32 v143, v143
	s_nop 0
	v_mul_f32_e32 v142, v142, v143
	v_mul_f32_e32 v50, v50, v142
	v_fma_f32 v142, v154, v145, v157
	v_fmac_f32_e32 v142, v155, v146
	v_fmac_f32_e32 v142, v156, v147
	v_mul_f32_e32 v143, 0x3d372713, v142
	v_mul_f32_e32 v143, v142, v143
	v_fma_f32 v143, v142, v143, v142
	v_mul_f32_e32 v143, 0x3f4c422a, v143
	v_add_f32_e32 v143, v143, v143
	v_mul_f32_e32 v143, 0xbfb8aa3b, v143
	v_exp_f32_e32 v143, v143
	ds_read_u16 v145, v2 offset:43888
	ds_read_u16 v146, v2 offset:44416
	ds_read_u16 v147, v2 offset:44944
	v_add_f32_e32 v143, 1.0, v143
	v_rcp_f32_e32 v143, v143
	s_waitcnt lgkmcnt(3)
	v_lshlrev_b32_e32 v144, 16, v144
	s_waitcnt lgkmcnt(2)
	v_lshlrev_b32_e32 v145, 16, v145
	s_waitcnt lgkmcnt(1)
	v_lshlrev_b32_e32 v146, 16, v146
	v_mul_f32_e32 v142, v142, v143
	v_mul_f32_e32 v51, v51, v142
	ds_read_u16 v142, v2 offset:42304
	ds_read_u16 v143, v2 offset:42832
	s_waitcnt lgkmcnt(2)
	v_lshlrev_b32_e32 v147, 16, v147
	s_waitcnt lgkmcnt(1)
	v_lshlrev_b32_e32 v142, 16, v142
	s_waitcnt lgkmcnt(0)
; DI float bf2f(u16 h) { return __uint_as_float(((unsigned)h) << 16); }
; DI float gelu_tanh(float x) { float u = 0.7978845608028654f * (x + 0.044715f * x * x * x); return x * sigmoidf_(2.f * u); }
; DI float sigmoidf_(float x) { return __builtin_amdgcn_rcpf(1.f + __expf(-x)); }
; DI void ffup_tile(const Params& p, int l, int mt, int nt, char* smem) {
;     ...
;       for (int m = 0; m < 8; ++m) {
;         if ((m & 1) == 0) asm volatile("" ::: "memory");
;         const int t = (row0 + wr * 128 + m * 16 + fq * 4) & 8191;
;         float g[6];
; #pragma unroll
;         for (int d = 0; d < 6; ++d) { const float gv = bf2f(img[(m * 16 + d) * IMG_LD + n * 16]); g[d] = (d >= 2 || t - 2 + d >= 0) ? gv : 0.f; }
; #pragma unroll
;         for (int j = 0; j < 4; ++j) acc[m][n][j] *= gelu_tanh(cb + w0 * g[j] + w1 * g[j + 1] + w2 * g[j + 2]);
;       }
	v_lshlrev_b32_e32 v143, 16, v143
	v_fma_f32 v142, v154, v142, v157
	v_fmac_f32_e32 v142, v155, v143
	v_fmac_f32_e32 v142, v156, v144
	v_mul_f32_e32 v148, 0x3d372713, v142
	v_mul_f32_e32 v148, v142, v148
	v_fma_f32 v148, v142, v148, v142
	v_mul_f32_e32 v148, 0x3f4c422a, v148
	v_add_f32_e32 v148, v148, v148
	v_mul_f32_e32 v148, 0xbfb8aa3b, v148
	v_exp_f32_e32 v148, v148
	s_nop 0
	v_add_f32_e32 v148, 1.0, v148
	v_rcp_f32_e32 v148, v148
	s_nop 0
	v_mul_f32_e32 v142, v142, v148
	v_mul_f32_e32 v44, v44, v142
	v_fma_f32 v142, v154, v143, v157
	v_fmac_f32_e32 v142, v155, v144
	v_fmac_f32_e32 v142, v156, v145
	v_mul_f32_e32 v143, 0x3d372713, v142
	v_mul_f32_e32 v143, v142, v143
	v_fma_f32 v143, v142, v143, v142
	v_mul_f32_e32 v143, 0x3f4c422a, v143
	v_add_f32_e32 v143, v143, v143
	v_mul_f32_e32 v143, 0xbfb8aa3b, v143
	v_exp_f32_e32 v143, v143
	s_nop 0
	v_add_f32_e32 v143, 1.0, v143
	v_rcp_f32_e32 v143, v143
	s_nop 0
	v_mul_f32_e32 v142, v142, v143
	v_mul_f32_e32 v45, v45, v142
	v_fma_f32 v142, v154, v144, v157
	v_fmac_f32_e32 v142, v155, v145
	v_fmac_f32_e32 v142, v156, v146
	v_mul_f32_e32 v143, 0x3d372713, v142
	v_mul_f32_e32 v143, v142, v143
	v_fma_f32 v143, v142, v143, v142
	v_mul_f32_e32 v143, 0x3f4c422a, v143
	v_add_f32_e32 v143, v143, v143
	v_mul_f32_e32 v143, 0xbfb8aa3b, v143
	v_exp_f32_e32 v143, v143
	ds_read_u16 v144, v2 offset:51808
	v_add_f32_e32 v143, 1.0, v143
	v_rcp_f32_e32 v143, v143
	s_nop 0
	v_mul_f32_e32 v142, v142, v143
	v_mul_f32_e32 v46, v46, v142
	v_fma_f32 v142, v154, v145, v157
	v_fmac_f32_e32 v142, v155, v146
	v_fmac_f32_e32 v142, v156, v147
	v_mul_f32_e32 v143, 0x3d372713, v142
	v_mul_f32_e32 v143, v142, v143
	v_fma_f32 v143, v142, v143, v142
	v_mul_f32_e32 v143, 0x3f4c422a, v143
	v_add_f32_e32 v143, v143, v143
	v_mul_f32_e32 v143, 0xbfb8aa3b, v143
	v_exp_f32_e32 v143, v143
	ds_read_u16 v145, v2 offset:52336
	ds_read_u16 v146, v2 offset:52864
	ds_read_u16 v147, v2 offset:53392
	v_add_f32_e32 v143, 1.0, v143
	v_rcp_f32_e32 v143, v143
	s_waitcnt lgkmcnt(3)
	v_lshlrev_b32_e32 v144, 16, v144
	s_waitcnt lgkmcnt(2)
	v_lshlrev_b32_e32 v145, 16, v145
	s_waitcnt lgkmcnt(1)
	v_lshlrev_b32_e32 v146, 16, v146
	v_mul_f32_e32 v142, v142, v143
	v_mul_f32_e32 v47, v47, v142
	ds_read_u16 v142, v2 offset:50752
	ds_read_u16 v143, v2 offset:51280
	s_waitcnt lgkmcnt(2)
	v_lshlrev_b32_e32 v147, 16, v147
	s_waitcnt lgkmcnt(1)
	v_lshlrev_b32_e32 v142, 16, v142
	s_waitcnt lgkmcnt(0)
	v_lshlrev_b32_e32 v143, 16, v143
	v_fma_f32 v142, v154, v142, v157
	v_fmac_f32_e32 v142, v155, v143
	v_fmac_f32_e32 v142, v156, v144
	v_mul_f32_e32 v148, 0x3d372713, v142
	v_mul_f32_e32 v148, v142, v148
	v_fma_f32 v148, v142, v148, v142
	v_mul_f32_e32 v148, 0x3f4c422a, v148
	v_add_f32_e32 v148, v148, v148
	v_mul_f32_e32 v148, 0xbfb8aa3b, v148
	v_exp_f32_e32 v148, v148
	s_nop 0
	v_add_f32_e32 v148, 1.0, v148
	v_rcp_f32_e32 v148, v148
	s_nop 0
	v_mul_f32_e32 v142, v142, v148
	v_mul_f32_e32 v40, v40, v142
	v_fma_f32 v142, v154, v143, v157
	v_fmac_f32_e32 v142, v155, v144
	v_fmac_f32_e32 v142, v156, v145
	v_mul_f32_e32 v143, 0x3d372713, v142
	v_mul_f32_e32 v143, v142, v143
	v_fma_f32 v143, v142, v143, v142
	v_mul_f32_e32 v143, 0x3f4c422a, v143
	v_add_f32_e32 v143, v143, v143
	v_mul_f32_e32 v143, 0xbfb8aa3b, v143
	v_exp_f32_e32 v143, v143
	s_nop 0
	v_add_f32_e32 v143, 1.0, v143
	v_rcp_f32_e32 v143, v143
	s_nop 0
	v_mul_f32_e32 v142, v142, v143
	v_mul_f32_e32 v41, v41, v142
	v_fma_f32 v142, v154, v144, v157
	v_fmac_f32_e32 v142, v155, v145
	v_fmac_f32_e32 v142, v156, v146
	v_mul_f32_e32 v143, 0x3d372713, v142
	v_mul_f32_e32 v143, v142, v143
	v_fma_f32 v143, v142, v143, v142
	v_mul_f32_e32 v143, 0x3f4c422a, v143
	v_add_f32_e32 v143, v143, v143
	v_mul_f32_e32 v143, 0xbfb8aa3b, v143
	v_exp_f32_e32 v143, v143
	ds_read_u16 v144, v2 offset:60256
	v_add_f32_e32 v143, 1.0, v143
	v_rcp_f32_e32 v143, v143
	s_nop 0
	v_mul_f32_e32 v142, v142, v143
	v_mul_f32_e32 v42, v42, v142
	v_fma_f32 v142, v154, v145, v157
	v_fmac_f32_e32 v142, v155, v146
	v_fmac_f32_e32 v142, v156, v147
	v_mul_f32_e32 v143, 0x3d372713, v142
	v_mul_f32_e32 v143, v142, v143
	v_fma_f32 v143, v142, v143, v142
	v_mul_f32_e32 v143, 0x3f4c422a, v143
	v_add_f32_e32 v143, v143, v143
	v_mul_f32_e32 v143, 0xbfb8aa3b, v143
	v_exp_f32_e32 v143, v143
	ds_read_u16 v145, v2 offset:60784
	ds_read_u16 v146, v2 offset:61312
	ds_read_u16 v147, v2 offset:61840
	v_add_f32_e32 v143, 1.0, v143
	v_rcp_f32_e32 v143, v143
	s_waitcnt lgkmcnt(3)
	v_lshlrev_b32_e32 v144, 16, v144
	s_waitcnt lgkmcnt(2)
	v_lshlrev_b32_e32 v145, 16, v145
	s_waitcnt lgkmcnt(1)
	v_lshlrev_b32_e32 v146, 16, v146
	v_mul_f32_e32 v142, v142, v143
	v_mul_f32_e32 v43, v43, v142
	ds_read_u16 v142, v2 offset:59200
	ds_read_u16 v143, v2 offset:59728
	s_waitcnt lgkmcnt(2)
	v_lshlrev_b32_e32 v147, 16, v147
	s_waitcnt lgkmcnt(1)
	v_lshlrev_b32_e32 v142, 16, v142
	s_waitcnt lgkmcnt(0)
; DI float bf2f(u16 h) { return __uint_as_float(((unsigned)h) << 16); }
; DI float gelu_tanh(float x) { float u = 0.7978845608028654f * (x + 0.044715f * x * x * x); return x * sigmoidf_(2.f * u); }
; DI float sigmoidf_(float x) { return __builtin_amdgcn_rcpf(1.f + __expf(-x)); }
; DI void ffup_tile(const Params& p, int l, int mt, int nt, char* smem) {
;     ...
;       for (int m = 0; m < 8; ++m) {
;         if ((m & 1) == 0) asm volatile("" ::: "memory");
;         const int t = (row0 + wr * 128 + m * 16 + fq * 4) & 8191;
;         float g[6];
; #pragma unroll
;         for (int d = 0; d < 6; ++d) { const float gv = bf2f(img[(m * 16 + d) * IMG_LD + n * 16]); g[d] = (d >= 2 || t - 2 + d >= 0) ? gv : 0.f; }
; #pragma unroll
;         for (int j = 0; j < 4; ++j) acc[m][n][j] *= gelu_tanh(cb + w0 * g[j] + w1 * g[j + 1] + w2 * g[j + 2]);
;       }
	v_lshlrev_b32_e32 v143, 16, v143
	v_fma_f32 v142, v154, v142, v157
	v_fmac_f32_e32 v142, v155, v143
	v_fmac_f32_e32 v142, v156, v144
	v_mul_f32_e32 v148, 0x3d372713, v142
	v_mul_f32_e32 v148, v142, v148
	v_fma_f32 v148, v142, v148, v142
	v_mul_f32_e32 v148, 0x3f4c422a, v148
	v_add_f32_e32 v148, v148, v148
	v_mul_f32_e32 v148, 0xbfb8aa3b, v148
	v_exp_f32_e32 v148, v148
	s_nop 0
	v_add_f32_e32 v148, 1.0, v148
	v_rcp_f32_e32 v148, v148
	s_nop 0
	v_mul_f32_e32 v142, v142, v148
	v_mul_f32_e32 v36, v36, v142
	v_fma_f32 v142, v154, v143, v157
	v_fmac_f32_e32 v142, v155, v144
	v_fmac_f32_e32 v142, v156, v145
	v_mul_f32_e32 v143, 0x3d372713, v142
	v_mul_f32_e32 v143, v142, v143
	v_fma_f32 v143, v142, v143, v142
	v_mul_f32_e32 v143, 0x3f4c422a, v143
	v_add_f32_e32 v143, v143, v143
	v_mul_f32_e32 v143, 0xbfb8aa3b, v143
	v_exp_f32_e32 v143, v143
	s_nop 0
	v_add_f32_e32 v143, 1.0, v143
	v_rcp_f32_e32 v143, v143
	s_nop 0
	v_mul_f32_e32 v142, v142, v143
	v_mul_f32_e32 v37, v37, v142
	v_fma_f32 v142, v154, v144, v157
	v_fmac_f32_e32 v157, v154, v145
	v_fmac_f32_e32 v157, v155, v146
	v_fmac_f32_e32 v157, v156, v147
	v_mul_f32_e32 v138, 0x3d372713, v157
	v_mul_f32_e32 v138, v157, v138
	v_fma_f32 v138, v157, v138, v157
	v_mul_f32_e32 v138, 0x3f4c422a, v138
	v_add_f32_e32 v138, v138, v138
	v_mul_f32_e32 v138, 0xbfb8aa3b, v138
	v_exp_f32_e32 v138, v138
	v_fmac_f32_e32 v142, v155, v145
	v_fmac_f32_e32 v142, v156, v146
	v_mul_f32_e32 v143, 0x3d372713, v142
	v_add_f32_e32 v138, 1.0, v138
	v_rcp_f32_e32 v138, v138
	v_mul_f32_e32 v143, v142, v143
	v_fma_f32 v143, v142, v143, v142
	v_mul_f32_e32 v143, 0x3f4c422a, v143
	v_mul_f32_e32 v138, v157, v138
	v_mul_f32_e32 v39, v39, v138
	s_nop 0
	s_nop 0
	ds_read_u16 v1, v2 offset:96
	ds_read_u16 v134, v2 offset:624
	ds_read_u16 v135, v2 offset:1152
	ds_read_u16 v136, v2 offset:1680
	ds_read_u16 v137, v2 offset:2208
	ds_read_u16 v139, v2 offset:2736
	s_waitcnt lgkmcnt(5)
	v_lshlrev_b32_e32 v1, 16, v1
	v_cndmask_b32_e64 v1, v1, 0, vcc
	s_waitcnt lgkmcnt(4)
	v_lshlrev_b32_e32 v134, 16, v134
	v_cndmask_b32_e64 v134, v134, 0, vcc
	s_waitcnt lgkmcnt(3)
	v_lshlrev_b32_e32 v135, 16, v135
	s_waitcnt lgkmcnt(2)
	v_lshlrev_b32_e32 v136, 16, v136
	s_waitcnt lgkmcnt(1)
	v_lshlrev_b32_e32 v137, 16, v137
	s_waitcnt lgkmcnt(0)
	v_lshlrev_b32_e32 v139, 16, v139
	v_add_f32_e32 v143, v143, v143
	v_mul_f32_e32 v143, 0xbfb8aa3b, v143
	v_exp_f32_e32 v143, v143
	s_waitcnt vmcnt(0)
	v_fma_f32 v1, v158, v1, v161
	v_fmac_f32_e32 v1, v159, v134
	v_fmac_f32_e32 v1, v160, v135
	v_mul_f32_e32 v140, 0x3d372713, v1
	v_mul_f32_e32 v140, v1, v140
	v_fma_f32 v140, v1, v140, v1
	v_mul_f32_e32 v140, 0x3f4c422a, v140
	v_add_f32_e32 v140, v140, v140
	v_mul_f32_e32 v140, 0xbfb8aa3b, v140
	v_exp_f32_e32 v140, v140
	v_add_f32_e32 v143, 1.0, v143
	v_rcp_f32_e32 v143, v143
	v_add_f32_e32 v140, 1.0, v140
	v_rcp_f32_e32 v140, v140
	v_mul_f32_e32 v142, v142, v143
	v_mul_f32_e32 v38, v38, v142
	v_mul_f32_e32 v1, v1, v140
	v_mul_f32_e32 v1, v32, v1
	v_fma_f32 v32, v158, v134, v161
	v_fmac_f32_e32 v32, v159, v135
	v_fmac_f32_e32 v32, v160, v136
	v_mul_f32_e32 v134, 0x3d372713, v32
	v_mul_f32_e32 v134, v32, v134
	v_fma_f32 v134, v32, v134, v32
	v_mul_f32_e32 v134, 0x3f4c422a, v134
	v_add_f32_e32 v134, v134, v134
	v_mul_f32_e32 v134, 0xbfb8aa3b, v134
	v_exp_f32_e32 v134, v134
	v_cvt_pk_bf16_f32 v1, v1, s0
	v_add_f32_e32 v134, 1.0, v134
	v_rcp_f32_e32 v134, v134
	s_nop 0
	v_mul_f32_e32 v32, v32, v134
	v_mul_f32_e32 v32, v33, v32
	v_fma_f32 v33, v158, v135, v161
	v_fmac_f32_e32 v33, v159, v136
	v_fmac_f32_e32 v33, v160, v137
	v_mul_f32_e32 v134, 0x3d372713, v33
	v_mul_f32_e32 v134, v33, v134
	v_fma_f32 v134, v33, v134, v33
	v_mul_f32_e32 v134, 0x3f4c422a, v134
	v_add_f32_e32 v134, v134, v134
	v_mul_f32_e32 v134, 0xbfb8aa3b, v134
	v_exp_f32_e32 v134, v134
	ds_read_u16 v135, v2 offset:9600
	v_add_f32_e32 v134, 1.0, v134
	v_rcp_f32_e32 v134, v134
	s_nop 0
	v_mul_f32_e32 v33, v33, v134
	v_mul_f32_e32 v33, v34, v33
	v_fma_f32 v34, v158, v136, v161
	v_fmac_f32_e32 v34, v159, v137
	v_fmac_f32_e32 v34, v160, v139
	v_mul_f32_e32 v134, 0x3d372713, v34
	v_mul_f32_e32 v134, v34, v134
	v_fma_f32 v134, v34, v134, v34
	v_mul_f32_e32 v134, 0x3f4c422a, v134
	v_add_f32_e32 v134, v134, v134
	v_mul_f32_e32 v134, 0xbfb8aa3b, v134
	v_exp_f32_e32 v134, v134
	ds_read_u16 v136, v2 offset:10128
	ds_read_u16 v137, v2 offset:10656
	ds_read_u16 v139, v2 offset:11184
	v_add_f32_e32 v134, 1.0, v134
	v_rcp_f32_e32 v134, v134
	s_waitcnt lgkmcnt(3)
	v_lshlrev_b32_e32 v135, 16, v135
	s_waitcnt lgkmcnt(2)
	v_lshlrev_b32_e32 v136, 16, v136
	s_waitcnt lgkmcnt(1)
	v_lshlrev_b32_e32 v137, 16, v137
	v_mul_f32_e32 v34, v34, v134
	v_mul_f32_e32 v34, v35, v34
	ds_read_u16 v35, v2 offset:8544
	ds_read_u16 v134, v2 offset:9072
	s_waitcnt lgkmcnt(2)
	v_lshlrev_b32_e32 v139, 16, v139
	s_waitcnt lgkmcnt(1)
	v_lshlrev_b32_e32 v35, 16, v35
	s_waitcnt lgkmcnt(0)
; DI float bf2f(u16 h) { return __uint_as_float(((unsigned)h) << 16); }
; DI float gelu_tanh(float x) { float u = 0.7978845608028654f * (x + 0.044715f * x * x * x); return x * sigmoidf_(2.f * u); }
; DI float sigmoidf_(float x) { return __builtin_amdgcn_rcpf(1.f + __expf(-x)); }
; DI void ffup_tile(const Params& p, int l, int mt, int nt, char* smem) {
;     ...
;       for (int m = 0; m < 8; ++m) {
;         if ((m & 1) == 0) asm volatile("" ::: "memory");
;         const int t = (row0 + wr * 128 + m * 16 + fq * 4) & 8191;
;         float g[6];
; #pragma unroll
;         for (int d = 0; d < 6; ++d) { const float gv = bf2f(img[(m * 16 + d) * IMG_LD + n * 16]); g[d] = (d >= 2 || t - 2 + d >= 0) ? gv : 0.f; }
; #pragma unroll
;         for (int j = 0; j < 4; ++j) acc[m][n][j] *= gelu_tanh(cb + w0 * g[j] + w1 * g[j + 1] + w2 * g[j + 2]);
;       }
	v_lshlrev_b32_e32 v134, 16, v134
	v_fma_f32 v35, v158, v35, v161
	v_fmac_f32_e32 v35, v159, v134
	v_fmac_f32_e32 v35, v160, v135
	v_mul_f32_e32 v140, 0x3d372713, v35
	v_mul_f32_e32 v140, v35, v140
	v_fma_f32 v140, v35, v140, v35
	v_mul_f32_e32 v140, 0x3f4c422a, v140
	v_add_f32_e32 v140, v140, v140
	v_mul_f32_e32 v140, 0xbfb8aa3b, v140
	v_exp_f32_e32 v140, v140
	s_nop 0
	v_add_f32_e32 v140, 1.0, v140
	v_rcp_f32_e32 v140, v140
	s_nop 0
	v_mul_f32_e32 v35, v35, v140
	v_mul_f32_e32 v28, v28, v35
	v_fma_f32 v35, v158, v134, v161
	v_fmac_f32_e32 v35, v159, v135
	v_fmac_f32_e32 v35, v160, v136
	v_mul_f32_e32 v134, 0x3d372713, v35
	v_mul_f32_e32 v134, v35, v134
	v_fma_f32 v134, v35, v134, v35
	v_mul_f32_e32 v134, 0x3f4c422a, v134
	v_add_f32_e32 v134, v134, v134
	v_mul_f32_e32 v134, 0xbfb8aa3b, v134
	v_exp_f32_e32 v134, v134
	s_nop 0
	v_add_f32_e32 v134, 1.0, v134
	v_rcp_f32_e32 v134, v134
	s_nop 0
	v_mul_f32_e32 v35, v35, v134
	v_mul_f32_e32 v29, v29, v35
	v_fma_f32 v35, v158, v135, v161
	v_fmac_f32_e32 v35, v159, v136
	v_fmac_f32_e32 v35, v160, v137
	v_mul_f32_e32 v134, 0x3d372713, v35
	v_mul_f32_e32 v134, v35, v134
	v_fma_f32 v134, v35, v134, v35
	v_mul_f32_e32 v134, 0x3f4c422a, v134
	v_add_f32_e32 v134, v134, v134
	v_mul_f32_e32 v134, 0xbfb8aa3b, v134
	v_exp_f32_e32 v134, v134
	ds_read_u16 v135, v2 offset:18048
	v_add_f32_e32 v134, 1.0, v134
	v_rcp_f32_e32 v134, v134
	s_nop 0
	v_mul_f32_e32 v35, v35, v134
	v_mul_f32_e32 v30, v30, v35
	v_fma_f32 v35, v158, v136, v161
	v_fmac_f32_e32 v35, v159, v137
	v_fmac_f32_e32 v35, v160, v139
	v_mul_f32_e32 v134, 0x3d372713, v35
	v_mul_f32_e32 v134, v35, v134
	v_fma_f32 v134, v35, v134, v35
	v_mul_f32_e32 v134, 0x3f4c422a, v134
	v_add_f32_e32 v134, v134, v134
	v_mul_f32_e32 v134, 0xbfb8aa3b, v134
	v_exp_f32_e32 v134, v134
	ds_read_u16 v136, v2 offset:18576
	ds_read_u16 v137, v2 offset:19104
	ds_read_u16 v139, v2 offset:19632
	v_add_f32_e32 v134, 1.0, v134
	v_rcp_f32_e32 v134, v134
	s_waitcnt lgkmcnt(3)
	v_lshlrev_b32_e32 v135, 16, v135
	s_waitcnt lgkmcnt(2)
	v_lshlrev_b32_e32 v136, 16, v136
	s_waitcnt lgkmcnt(1)
	v_lshlrev_b32_e32 v137, 16, v137
	v_mul_f32_e32 v35, v35, v134
	v_mul_f32_e32 v31, v31, v35
	ds_read_u16 v35, v2 offset:16992
	ds_read_u16 v134, v2 offset:17520
	s_waitcnt lgkmcnt(2)
	v_lshlrev_b32_e32 v139, 16, v139
	s_waitcnt lgkmcnt(1)
	v_lshlrev_b32_e32 v35, 16, v35
	s_waitcnt lgkmcnt(0)
	v_lshlrev_b32_e32 v134, 16, v134
	v_fma_f32 v35, v158, v35, v161
	v_fmac_f32_e32 v35, v159, v134
	v_fmac_f32_e32 v35, v160, v135
	v_mul_f32_e32 v140, 0x3d372713, v35
	v_mul_f32_e32 v140, v35, v140
	v_fma_f32 v140, v35, v140, v35
	v_mul_f32_e32 v140, 0x3f4c422a, v140
	v_add_f32_e32 v140, v140, v140
	v_mul_f32_e32 v140, 0xbfb8aa3b, v140
	v_exp_f32_e32 v140, v140
	s_nop 0
	v_add_f32_e32 v140, 1.0, v140
	v_rcp_f32_e32 v140, v140
	s_nop 0
	v_mul_f32_e32 v35, v35, v140
	v_mul_f32_e32 v24, v24, v35
	v_fma_f32 v35, v158, v134, v161
	v_fmac_f32_e32 v35, v159, v135
	v_fmac_f32_e32 v35, v160, v136
	v_mul_f32_e32 v134, 0x3d372713, v35
	v_mul_f32_e32 v134, v35, v134
	v_fma_f32 v134, v35, v134, v35
	v_mul_f32_e32 v134, 0x3f4c422a, v134
	v_add_f32_e32 v134, v134, v134
	v_mul_f32_e32 v134, 0xbfb8aa3b, v134
	v_exp_f32_e32 v134, v134
	s_nop 0
	v_add_f32_e32 v134, 1.0, v134
	v_rcp_f32_e32 v134, v134
	s_nop 0
	v_mul_f32_e32 v35, v35, v134
	v_mul_f32_e32 v25, v25, v35
	v_fma_f32 v35, v158, v135, v161
	v_fmac_f32_e32 v35, v159, v136
	v_fmac_f32_e32 v35, v160, v137
	v_mul_f32_e32 v134, 0x3d372713, v35
	v_mul_f32_e32 v134, v35, v134
	v_fma_f32 v134, v35, v134, v35
	v_mul_f32_e32 v134, 0x3f4c422a, v134
	v_add_f32_e32 v134, v134, v134
	v_mul_f32_e32 v134, 0xbfb8aa3b, v134
	v_exp_f32_e32 v134, v134
	ds_read_u16 v135, v2 offset:26496
	v_add_f32_e32 v134, 1.0, v134
	v_rcp_f32_e32 v134, v134
	s_nop 0
	v_mul_f32_e32 v35, v35, v134
	v_mul_f32_e32 v26, v26, v35
	v_fma_f32 v35, v158, v136, v161
	v_fmac_f32_e32 v35, v159, v137
	v_fmac_f32_e32 v35, v160, v139
	v_mul_f32_e32 v134, 0x3d372713, v35
	v_mul_f32_e32 v134, v35, v134
	v_fma_f32 v134, v35, v134, v35
	v_mul_f32_e32 v134, 0x3f4c422a, v134
	v_add_f32_e32 v134, v134, v134
	v_mul_f32_e32 v134, 0xbfb8aa3b, v134
	v_exp_f32_e32 v134, v134
	ds_read_u16 v136, v2 offset:27024
	ds_read_u16 v137, v2 offset:27552
	ds_read_u16 v139, v2 offset:28080
	v_add_f32_e32 v134, 1.0, v134
	v_rcp_f32_e32 v134, v134
	s_waitcnt lgkmcnt(3)
	v_lshlrev_b32_e32 v135, 16, v135
	s_waitcnt lgkmcnt(2)
	v_lshlrev_b32_e32 v136, 16, v136
	s_waitcnt lgkmcnt(1)
	v_lshlrev_b32_e32 v137, 16, v137
	v_mul_f32_e32 v35, v35, v134
	v_mul_f32_e32 v27, v27, v35
	ds_read_u16 v35, v2 offset:25440
	ds_read_u16 v134, v2 offset:25968
	s_waitcnt lgkmcnt(2)
	v_lshlrev_b32_e32 v139, 16, v139
	s_waitcnt lgkmcnt(1)
	v_lshlrev_b32_e32 v35, 16, v35
	s_waitcnt lgkmcnt(0)
; DI float bf2f(u16 h) { return __uint_as_float(((unsigned)h) << 16); }
; DI float gelu_tanh(float x) { float u = 0.7978845608028654f * (x + 0.044715f * x * x * x); return x * sigmoidf_(2.f * u); }
; DI float sigmoidf_(float x) { return __builtin_amdgcn_rcpf(1.f + __expf(-x)); }
; DI void ffup_tile(const Params& p, int l, int mt, int nt, char* smem) {
;     ...
;       for (int m = 0; m < 8; ++m) {
;         if ((m & 1) == 0) asm volatile("" ::: "memory");
;         const int t = (row0 + wr * 128 + m * 16 + fq * 4) & 8191;
;         float g[6];
; #pragma unroll
;         for (int d = 0; d < 6; ++d) { const float gv = bf2f(img[(m * 16 + d) * IMG_LD + n * 16]); g[d] = (d >= 2 || t - 2 + d >= 0) ? gv : 0.f; }
; #pragma unroll
;         for (int j = 0; j < 4; ++j) acc[m][n][j] *= gelu_tanh(cb + w0 * g[j] + w1 * g[j + 1] + w2 * g[j + 2]);
;       }
	v_lshlrev_b32_e32 v134, 16, v134
	v_fma_f32 v35, v158, v35, v161
	v_fmac_f32_e32 v35, v159, v134
	v_fmac_f32_e32 v35, v160, v135
	v_mul_f32_e32 v140, 0x3d372713, v35
	v_mul_f32_e32 v140, v35, v140
	v_fma_f32 v140, v35, v140, v35
	v_mul_f32_e32 v140, 0x3f4c422a, v140
	v_add_f32_e32 v140, v140, v140
	v_mul_f32_e32 v140, 0xbfb8aa3b, v140
	v_exp_f32_e32 v140, v140
	s_nop 0
	v_add_f32_e32 v140, 1.0, v140
	v_rcp_f32_e32 v140, v140
	s_nop 0
	v_mul_f32_e32 v35, v35, v140
	v_mul_f32_e32 v20, v20, v35
	v_fma_f32 v35, v158, v134, v161
	v_fmac_f32_e32 v35, v159, v135
	v_fmac_f32_e32 v35, v160, v136
	v_mul_f32_e32 v134, 0x3d372713, v35
	v_mul_f32_e32 v134, v35, v134
	v_fma_f32 v134, v35, v134, v35
	v_mul_f32_e32 v134, 0x3f4c422a, v134
	v_add_f32_e32 v134, v134, v134
	v_mul_f32_e32 v134, 0xbfb8aa3b, v134
	v_exp_f32_e32 v134, v134
	s_nop 0
	v_add_f32_e32 v134, 1.0, v134
	v_rcp_f32_e32 v134, v134
	s_nop 0
	v_mul_f32_e32 v35, v35, v134
	v_mul_f32_e32 v21, v21, v35
	v_fma_f32 v35, v158, v135, v161
	v_fmac_f32_e32 v35, v159, v136
	v_fmac_f32_e32 v35, v160, v137
	v_mul_f32_e32 v134, 0x3d372713, v35
	v_mul_f32_e32 v134, v35, v134
	v_fma_f32 v134, v35, v134, v35
	v_mul_f32_e32 v134, 0x3f4c422a, v134
	v_add_f32_e32 v134, v134, v134
	v_mul_f32_e32 v134, 0xbfb8aa3b, v134
	v_exp_f32_e32 v134, v134
	ds_read_u16 v135, v2 offset:34944
	v_add_f32_e32 v134, 1.0, v134
	v_rcp_f32_e32 v134, v134
	s_nop 0
	v_mul_f32_e32 v35, v35, v134
	v_mul_f32_e32 v22, v22, v35
	v_fma_f32 v35, v158, v136, v161
	v_fmac_f32_e32 v35, v159, v137
	v_fmac_f32_e32 v35, v160, v139
	v_mul_f32_e32 v134, 0x3d372713, v35
	v_mul_f32_e32 v134, v35, v134
	v_fma_f32 v134, v35, v134, v35
	v_mul_f32_e32 v134, 0x3f4c422a, v134
	v_add_f32_e32 v134, v134, v134
	v_mul_f32_e32 v134, 0xbfb8aa3b, v134
	v_exp_f32_e32 v134, v134
	ds_read_u16 v136, v2 offset:35472
	ds_read_u16 v137, v2 offset:36000
	ds_read_u16 v139, v2 offset:36528
	v_add_f32_e32 v134, 1.0, v134
	v_rcp_f32_e32 v134, v134
	s_waitcnt lgkmcnt(3)
	v_lshlrev_b32_e32 v135, 16, v135
	s_waitcnt lgkmcnt(2)
	v_lshlrev_b32_e32 v136, 16, v136
	s_waitcnt lgkmcnt(1)
	v_lshlrev_b32_e32 v137, 16, v137
	v_mul_f32_e32 v35, v35, v134
	v_mul_f32_e32 v23, v23, v35
	ds_read_u16 v35, v2 offset:33888
	ds_read_u16 v134, v2 offset:34416
	s_waitcnt lgkmcnt(2)
	v_lshlrev_b32_e32 v139, 16, v139
	s_waitcnt lgkmcnt(1)
	v_lshlrev_b32_e32 v35, 16, v35
	s_waitcnt lgkmcnt(0)
	v_lshlrev_b32_e32 v134, 16, v134
	v_fma_f32 v35, v158, v35, v161
	v_fmac_f32_e32 v35, v159, v134
	v_fmac_f32_e32 v35, v160, v135
	v_mul_f32_e32 v140, 0x3d372713, v35
	v_mul_f32_e32 v140, v35, v140
	v_fma_f32 v140, v35, v140, v35
	v_mul_f32_e32 v140, 0x3f4c422a, v140
	v_add_f32_e32 v140, v140, v140
	v_mul_f32_e32 v140, 0xbfb8aa3b, v140
	v_exp_f32_e32 v140, v140
	s_nop 0
	v_add_f32_e32 v140, 1.0, v140
	v_rcp_f32_e32 v140, v140
	s_nop 0
	v_mul_f32_e32 v35, v35, v140
	v_mul_f32_e32 v16, v16, v35
	v_fma_f32 v35, v158, v134, v161
	v_fmac_f32_e32 v35, v159, v135
	v_fmac_f32_e32 v35, v160, v136
	v_mul_f32_e32 v134, 0x3d372713, v35
	v_mul_f32_e32 v134, v35, v134
	v_fma_f32 v134, v35, v134, v35
	v_mul_f32_e32 v134, 0x3f4c422a, v134
	v_add_f32_e32 v134, v134, v134
	v_mul_f32_e32 v134, 0xbfb8aa3b, v134
	v_exp_f32_e32 v134, v134
	s_nop 0
	v_add_f32_e32 v134, 1.0, v134
	v_rcp_f32_e32 v134, v134
	s_nop 0
	v_mul_f32_e32 v35, v35, v134
	v_mul_f32_e32 v17, v17, v35
	v_fma_f32 v35, v158, v135, v161
	v_fmac_f32_e32 v35, v159, v136
	v_fmac_f32_e32 v35, v160, v137
	v_mul_f32_e32 v134, 0x3d372713, v35
	v_mul_f32_e32 v134, v35, v134
	v_fma_f32 v134, v35, v134, v35
	v_mul_f32_e32 v134, 0x3f4c422a, v134
	v_add_f32_e32 v134, v134, v134
	v_mul_f32_e32 v134, 0xbfb8aa3b, v134
	v_exp_f32_e32 v134, v134
	ds_read_u16 v135, v2 offset:43392
	v_add_f32_e32 v134, 1.0, v134
	v_rcp_f32_e32 v134, v134
	s_nop 0
	v_mul_f32_e32 v35, v35, v134
	v_mul_f32_e32 v18, v18, v35
	v_fma_f32 v35, v158, v136, v161
	v_fmac_f32_e32 v35, v159, v137
	v_fmac_f32_e32 v35, v160, v139
	v_mul_f32_e32 v134, 0x3d372713, v35
	v_mul_f32_e32 v134, v35, v134
	v_fma_f32 v134, v35, v134, v35
	v_mul_f32_e32 v134, 0x3f4c422a, v134
	v_add_f32_e32 v134, v134, v134
	v_mul_f32_e32 v134, 0xbfb8aa3b, v134
	v_exp_f32_e32 v134, v134
	ds_read_u16 v136, v2 offset:43920
	ds_read_u16 v137, v2 offset:44448
	ds_read_u16 v139, v2 offset:44976
	v_add_f32_e32 v134, 1.0, v134
	v_rcp_f32_e32 v134, v134
	s_waitcnt lgkmcnt(3)
	v_lshlrev_b32_e32 v135, 16, v135
	s_waitcnt lgkmcnt(2)
	v_lshlrev_b32_e32 v136, 16, v136
	s_waitcnt lgkmcnt(1)
	v_lshlrev_b32_e32 v137, 16, v137
	v_mul_f32_e32 v35, v35, v134
	v_mul_f32_e32 v19, v19, v35
	ds_read_u16 v35, v2 offset:42336
	ds_read_u16 v134, v2 offset:42864
	s_waitcnt lgkmcnt(2)
	v_lshlrev_b32_e32 v139, 16, v139
	s_waitcnt lgkmcnt(1)
	v_lshlrev_b32_e32 v35, 16, v35
	s_waitcnt lgkmcnt(0)
; DI float bf2f(u16 h) { return __uint_as_float(((unsigned)h) << 16); }
; DI float gelu_tanh(float x) { float u = 0.7978845608028654f * (x + 0.044715f * x * x * x); return x * sigmoidf_(2.f * u); }
; DI void img_barrier() { asm volatile("s_waitcnt lgkmcnt(0)" ::: "memory"); __builtin_amdgcn_s_barrier(); }
; DI float sigmoidf_(float x) { return __builtin_amdgcn_rcpf(1.f + __expf(-x)); }
; DI void ffup_tile(const Params& p, int l, int mt, int nt, char* smem) {
;     ...
;       for (int m = 0; m < 8; ++m) {
;         if ((m & 1) == 0) asm volatile("" ::: "memory");
;         const int t = (row0 + wr * 128 + m * 16 + fq * 4) & 8191;
;         float g[6];
; #pragma unroll
;         for (int d = 0; d < 6; ++d) { const float gv = bf2f(img[(m * 16 + d) * IMG_LD + n * 16]); g[d] = (d >= 2 || t - 2 + d >= 0) ? gv : 0.f; }
; #pragma unroll
;         for (int j = 0; j < 4; ++j) acc[m][n][j] *= gelu_tanh(cb + w0 * g[j] + w1 * g[j + 1] + w2 * g[j + 2]);
;       }
;     }
;     img_barrier();
	v_lshlrev_b32_e32 v134, 16, v134
	v_fma_f32 v35, v158, v35, v161
	v_fmac_f32_e32 v35, v159, v134
	v_fmac_f32_e32 v35, v160, v135
	v_mul_f32_e32 v140, 0x3d372713, v35
	v_mul_f32_e32 v140, v35, v140
	v_fma_f32 v140, v35, v140, v35
	v_mul_f32_e32 v140, 0x3f4c422a, v140
	v_add_f32_e32 v140, v140, v140
	v_mul_f32_e32 v140, 0xbfb8aa3b, v140
	v_exp_f32_e32 v140, v140
	s_nop 0
	v_add_f32_e32 v140, 1.0, v140
	v_rcp_f32_e32 v140, v140
	s_nop 0
	v_mul_f32_e32 v35, v35, v140
	v_mul_f32_e32 v12, v12, v35
	v_fma_f32 v35, v158, v134, v161
	v_fmac_f32_e32 v35, v159, v135
	v_fmac_f32_e32 v35, v160, v136
	v_mul_f32_e32 v134, 0x3d372713, v35
	v_mul_f32_e32 v134, v35, v134
	v_fma_f32 v134, v35, v134, v35
	v_mul_f32_e32 v134, 0x3f4c422a, v134
	v_add_f32_e32 v134, v134, v134
	v_mul_f32_e32 v134, 0xbfb8aa3b, v134
	v_exp_f32_e32 v134, v134
	s_nop 0
	v_add_f32_e32 v134, 1.0, v134
	v_rcp_f32_e32 v134, v134
	s_nop 0
	v_mul_f32_e32 v35, v35, v134
	v_mul_f32_e32 v13, v13, v35
	v_fma_f32 v35, v158, v135, v161
	v_fmac_f32_e32 v35, v159, v136
	v_fmac_f32_e32 v35, v160, v137
	v_mul_f32_e32 v134, 0x3d372713, v35
	v_mul_f32_e32 v134, v35, v134
	v_fma_f32 v134, v35, v134, v35
	v_mul_f32_e32 v134, 0x3f4c422a, v134
	v_add_f32_e32 v134, v134, v134
	v_mul_f32_e32 v134, 0xbfb8aa3b, v134
	v_exp_f32_e32 v134, v134
	ds_read_u16 v135, v2 offset:51840
	v_add_f32_e32 v134, 1.0, v134
	v_rcp_f32_e32 v134, v134
	s_nop 0
	v_mul_f32_e32 v35, v35, v134
	v_mul_f32_e32 v14, v14, v35
	v_fma_f32 v35, v158, v136, v161
	v_fmac_f32_e32 v35, v159, v137
	v_fmac_f32_e32 v35, v160, v139
	v_mul_f32_e32 v134, 0x3d372713, v35
	v_mul_f32_e32 v134, v35, v134
	v_fma_f32 v134, v35, v134, v35
	v_mul_f32_e32 v134, 0x3f4c422a, v134
	v_add_f32_e32 v134, v134, v134
	v_mul_f32_e32 v134, 0xbfb8aa3b, v134
	v_exp_f32_e32 v134, v134
	ds_read_u16 v136, v2 offset:52368
	ds_read_u16 v137, v2 offset:52896
	ds_read_u16 v139, v2 offset:53424
	v_add_f32_e32 v134, 1.0, v134
	v_rcp_f32_e32 v134, v134
	s_waitcnt lgkmcnt(3)
	v_lshlrev_b32_e32 v135, 16, v135
	s_waitcnt lgkmcnt(2)
	v_lshlrev_b32_e32 v136, 16, v136
	s_waitcnt lgkmcnt(1)
	v_lshlrev_b32_e32 v137, 16, v137
	v_mul_f32_e32 v35, v35, v134
	v_mul_f32_e32 v15, v15, v35
	ds_read_u16 v35, v2 offset:50784
	ds_read_u16 v134, v2 offset:51312
	s_waitcnt lgkmcnt(2)
	v_lshlrev_b32_e32 v139, 16, v139
	s_waitcnt lgkmcnt(1)
	v_lshlrev_b32_e32 v35, 16, v35
	s_waitcnt lgkmcnt(0)
	v_lshlrev_b32_e32 v134, 16, v134
	v_fma_f32 v35, v158, v35, v161
	v_fmac_f32_e32 v35, v159, v134
	v_fmac_f32_e32 v35, v160, v135
	v_mul_f32_e32 v140, 0x3d372713, v35
	v_mul_f32_e32 v140, v35, v140
	v_fma_f32 v140, v35, v140, v35
	v_mul_f32_e32 v140, 0x3f4c422a, v140
	v_add_f32_e32 v140, v140, v140
	v_mul_f32_e32 v140, 0xbfb8aa3b, v140
	v_exp_f32_e32 v140, v140
	s_nop 0
	v_add_f32_e32 v140, 1.0, v140
	v_rcp_f32_e32 v140, v140
	s_nop 0
	v_mul_f32_e32 v35, v35, v140
	v_mul_f32_e32 v8, v8, v35
	v_fma_f32 v35, v158, v134, v161
	v_fmac_f32_e32 v35, v159, v135
	v_fmac_f32_e32 v35, v160, v136
	v_mul_f32_e32 v134, 0x3d372713, v35
	v_mul_f32_e32 v134, v35, v134
	v_fma_f32 v134, v35, v134, v35
	v_mul_f32_e32 v134, 0x3f4c422a, v134
	v_add_f32_e32 v134, v134, v134
	v_mul_f32_e32 v134, 0xbfb8aa3b, v134
	v_exp_f32_e32 v134, v134
	s_nop 0
	v_add_f32_e32 v134, 1.0, v134
	v_rcp_f32_e32 v134, v134
	s_nop 0
	v_mul_f32_e32 v35, v35, v134
	v_mul_f32_e32 v9, v9, v35
	v_fma_f32 v35, v158, v135, v161
	v_fmac_f32_e32 v35, v159, v136
	v_fmac_f32_e32 v35, v160, v137
	v_mul_f32_e32 v134, 0x3d372713, v35
	v_mul_f32_e32 v134, v35, v134
	v_fma_f32 v134, v35, v134, v35
	v_mul_f32_e32 v134, 0x3f4c422a, v134
	v_add_f32_e32 v134, v134, v134
	v_mul_f32_e32 v134, 0xbfb8aa3b, v134
	v_exp_f32_e32 v134, v134
	ds_read_u16 v135, v2 offset:60288
	v_add_f32_e32 v134, 1.0, v134
	v_rcp_f32_e32 v134, v134
	s_nop 0
	v_mul_f32_e32 v35, v35, v134
	v_mul_f32_e32 v10, v10, v35
	v_fma_f32 v35, v158, v136, v161
	v_fmac_f32_e32 v35, v159, v137
	v_fmac_f32_e32 v35, v160, v139
	v_mul_f32_e32 v134, 0x3d372713, v35
	v_mul_f32_e32 v134, v35, v134
	v_fma_f32 v134, v35, v134, v35
	v_mul_f32_e32 v134, 0x3f4c422a, v134
	v_add_f32_e32 v134, v134, v134
	v_mul_f32_e32 v134, 0xbfb8aa3b, v134
	v_exp_f32_e32 v134, v134
	ds_read_u16 v136, v2 offset:60816
	ds_read_u16 v137, v2 offset:61344
	s_waitcnt lgkmcnt(2)
	v_lshlrev_b32_e32 v135, 16, v135
	v_add_f32_e32 v134, 1.0, v134
	v_rcp_f32_e32 v134, v134
	s_waitcnt lgkmcnt(1)
	v_lshlrev_b32_e32 v136, 16, v136
	s_waitcnt lgkmcnt(0)
	v_lshlrev_b32_e32 v137, 16, v137
	v_mul_f32_e32 v35, v35, v134
	v_mul_f32_e32 v11, v11, v35
	ds_read_u16 v35, v2 offset:59232
	ds_read_u16 v134, v2 offset:59760
	ds_read_u16 v2, v2 offset:61872
	s_waitcnt lgkmcnt(0)
	s_barrier
; DI float bf2f(u16 h) { return __uint_as_float(((unsigned)h) << 16); }
; DI float gelu_tanh(float x) { float u = 0.7978845608028654f * (x + 0.044715f * x * x * x); return x * sigmoidf_(2.f * u); }
; DI void img_barrier() { asm volatile("s_waitcnt lgkmcnt(0)" ::: "memory"); __builtin_amdgcn_s_barrier(); }
; template <bool ROPE>
; DI void img_put_bf16(const f32x4 (&acc)[8][4], char* smem, int rowoff, float scale, int prow0, const float* cosT) {
;   EPI_IDS;
;   u16* img = (u16*)smem + (wr * 128 + fq * 4 + rowoff) * IMG_LD + wc * 64 + fr;
; #pragma unroll
;   for (int m = 0; m < 8; ++m) {
;     float cs4[4] = {0.f, 0.f, 0.f, 0.f}, sn4[4] = {0.f, 0.f, 0.f, 0.f};
;     if (ROPE) {
; #pragma unroll
;       for (int j = 0; j < 4; ++j) { const int pos = prow0 + wr * 128 + m * 16 + fq * 4 + j; cs4[j] = cosT[pos * 8 + (fr & 7)]; sn4[j] = cosT[8192 * 8 + pos * 8 + (fr & 7)]; }
;     }
; #pragma unroll
;     for (int n = 0; n < 4; ++n)
; #pragma unroll
;       for (int j = 0; j < 4; ++j) img[(m * 16 + j) * IMG_LD + n * 16] = f2bf(epi_val<ROPE>(acc, m, n, j, cs4, sn4, fr) * scale);
; DI void ffup_tile(const Params& p, int l, int mt, int nt, char* smem) {
;     ...
;         for (int d = 0; d < 6; ++d) { const float gv = bf2f(img[(m * 16 + d) * IMG_LD + n * 16]); g[d] = (d >= 2 || t - 2 + d >= 0) ? gv : 0.f; }
; #pragma unroll
;         for (int j = 0; j < 4; ++j) acc[m][n][j] *= gelu_tanh(cb + w0 * g[j] + w1 * g[j + 1] + w2 * g[j + 2]);
;       }
;     }
;     img_barrier();
;     img_put_bf16<false>(acc, smem, 2, 1.f, 0, nullptr);
	s_waitcnt lgkmcnt(2)
	v_lshlrev_b32_e32 v35, 16, v35
	s_waitcnt lgkmcnt(1)
	v_lshlrev_b32_e32 v134, 16, v134
	v_fma_f32 v35, v158, v35, v161
	v_fmac_f32_e32 v35, v159, v134
	v_fmac_f32_e32 v35, v160, v135
	v_mul_f32_e32 v139, 0x3d372713, v35
	v_mul_f32_e32 v139, v35, v139
	v_fma_f32 v139, v35, v139, v35
	v_mul_f32_e32 v139, 0x3f4c422a, v139
	v_add_f32_e32 v139, v139, v139
	v_mul_f32_e32 v139, 0xbfb8aa3b, v139
	v_exp_f32_e32 v139, v139
	s_waitcnt lgkmcnt(0)
	v_lshlrev_b32_e32 v2, 16, v2
	v_add_f32_e32 v139, 1.0, v139
	v_rcp_f32_e32 v139, v139
	s_nop 0
	v_mul_f32_e32 v35, v35, v139
	v_mul_f32_e32 v4, v4, v35
	v_fma_f32 v35, v158, v134, v161
	v_fmac_f32_e32 v35, v159, v135
	v_fmac_f32_e32 v35, v160, v136
	v_mul_f32_e32 v134, 0x3d372713, v35
	v_mul_f32_e32 v134, v35, v134
	v_fma_f32 v134, v35, v134, v35
	v_mul_f32_e32 v134, 0x3f4c422a, v134
	v_add_f32_e32 v134, v134, v134
	v_mul_f32_e32 v134, 0xbfb8aa3b, v134
	v_exp_f32_e32 v134, v134
	s_nop 0
	v_add_f32_e32 v134, 1.0, v134
	v_rcp_f32_e32 v134, v134
	s_nop 0
	v_mul_f32_e32 v35, v35, v134
	v_mul_f32_e32 v5, v5, v35
	v_fma_f32 v35, v158, v135, v161
	v_fmac_f32_e32 v161, v158, v136
	v_fmac_f32_e32 v161, v159, v137
	v_fmac_f32_e32 v35, v159, v136
	v_fmac_f32_e32 v161, v160, v2
	v_fmac_f32_e32 v35, v160, v137
	v_mul_f32_e32 v2, 0x3d372713, v161
	v_mul_f32_e32 v134, 0x3d372713, v35
	v_mul_f32_e32 v2, v161, v2
	v_mul_f32_e32 v134, v35, v134
	v_fma_f32 v2, v161, v2, v161
	v_fma_f32 v134, v35, v134, v35
	v_mul_f32_e32 v2, 0x3f4c422a, v2
	v_mul_f32_e32 v134, 0x3f4c422a, v134
	v_add_f32_e32 v2, v2, v2
	v_add_f32_e32 v134, v134, v134
	v_mul_f32_e32 v2, 0xbfb8aa3b, v2
	v_mul_f32_e32 v134, 0xbfb8aa3b, v134
	v_exp_f32_e32 v2, v2
	v_exp_f32_e32 v134, v134
	v_add_f32_e32 v2, 1.0, v2
	v_add_f32_e32 v134, 1.0, v134
	v_rcp_f32_e32 v2, v2
	v_rcp_f32_e32 v134, v134
	v_mul_f32_e32 v0, v161, v2
	v_mov_b32_e32 v2, v184
	v_mul_f32_e32 v35, v35, v134
	v_mul_f32_e32 v6, v6, v35
	v_mul_f32_e32 v0, v7, v0
	v_and_b32_e32 v7, 0xc0, v2
	v_and_b32_e32 v35, 15, v2
	v_lshrrev_b32_e32 v132, 1, v2
	v_lshrrev_b32_e32 v2, 2, v2
	v_and_b32_e32 v2, 12, v2
	v_and_or_b32 v2, v132, s5, v2
	v_mul_lo_u32 v2, v2, s3
	v_add_u32_e32 v2, 16, v2
	v_lshlrev_b32_e32 v7, 1, v7
	v_lshlrev_b32_e32 v35, 1, v35
	v_add3_u32 v2, v2, v7, v35
	ds_write_b16 v2, v1 offset:1152
	v_cvt_pk_bf16_f32 v1, v32, s0
	ds_write_b16 v2, v1 offset:1680
	v_cvt_pk_bf16_f32 v1, v33, s0
	ds_write_b16 v2, v1 offset:2208
	v_cvt_pk_bf16_f32 v1, v34, s0
	ds_write_b16 v2, v1 offset:2736
	v_cvt_pk_bf16_f32 v1, v124, s0
	ds_write_b16 v2, v1 offset:9504
	v_cvt_pk_bf16_f32 v1, v125, s0
	ds_write_b16 v2, v1 offset:10032
	v_cvt_pk_bf16_f32 v1, v126, s0
	ds_write_b16 v2, v1 offset:10560
	v_cvt_pk_bf16_f32 v1, v127, s0
	ds_write_b16 v2, v1 offset:11088
	v_cvt_pk_bf16_f32 v1, v92, s0
	ds_write_b16 v2, v1 offset:9536
	v_cvt_pk_bf16_f32 v1, v93, s0
	ds_write_b16 v2, v1 offset:10064
	v_cvt_pk_bf16_f32 v1, v94, s0
	ds_write_b16 v2, v1 offset:10592
	v_cvt_pk_bf16_f32 v1, v95, s0
	ds_write_b16 v2, v1 offset:11120
	v_cvt_pk_bf16_f32 v1, v60, s0
	ds_write_b16 v2, v1 offset:9568
	v_cvt_pk_bf16_f32 v1, v61, s0
	ds_write_b16 v2, v1 offset:10096
	v_cvt_pk_bf16_f32 v1, v62, s0
	ds_write_b16 v2, v1 offset:10624
	v_cvt_pk_bf16_f32 v1, v63, s0
	ds_write_b16 v2, v1 offset:11152
	v_cvt_pk_bf16_f32 v1, v28, s0
	ds_write_b16 v2, v1 offset:9600
	v_cvt_pk_bf16_f32 v1, v29, s0
	ds_write_b16 v2, v1 offset:10128
	v_cvt_pk_bf16_f32 v1, v30, s0
	ds_write_b16 v2, v1 offset:10656
	v_cvt_pk_bf16_f32 v1, v31, s0
	ds_write_b16 v2, v1 offset:11184
	v_cvt_pk_bf16_f32 v1, v120, s0
	ds_write_b16 v2, v1 offset:17952
	v_cvt_pk_bf16_f32 v1, v121, s0
	ds_write_b16 v2, v1 offset:18480
	v_cvt_pk_bf16_f32 v1, v122, s0
	ds_write_b16 v2, v1 offset:19008
	v_cvt_pk_bf16_f32 v1, v123, s0
	ds_write_b16 v2, v1 offset:19536
	v_cvt_pk_bf16_f32 v1, v88, s0
	ds_write_b16 v2, v1 offset:17984
	v_cvt_pk_bf16_f32 v1, v89, s0
	ds_write_b16 v2, v1 offset:18512
	v_cvt_pk_bf16_f32 v1, v90, s0
	ds_write_b16 v2, v1 offset:19040
	v_cvt_pk_bf16_f32 v1, v91, s0
	ds_write_b16 v2, v1 offset:19568
	v_cvt_pk_bf16_f32 v1, v56, s0
	ds_write_b16 v2, v1 offset:18016
	v_cvt_pk_bf16_f32 v1, v57, s0
	ds_write_b16 v2, v1 offset:18544
	v_cvt_pk_bf16_f32 v1, v58, s0
	ds_write_b16 v2, v1 offset:19072
	v_cvt_pk_bf16_f32 v1, v59, s0
	ds_write_b16 v2, v1 offset:19600
	v_cvt_pk_bf16_f32 v1, v24, s0
	ds_write_b16 v2, v1 offset:18048
	v_cvt_pk_bf16_f32 v1, v25, s0
	ds_write_b16 v2, v1 offset:18576
	v_cvt_pk_bf16_f32 v1, v26, s0
	ds_write_b16 v2, v1 offset:19104
	v_cvt_pk_bf16_f32 v1, v27, s0
	ds_write_b16 v2, v1 offset:19632
	v_cvt_pk_bf16_f32 v1, v116, s0
	ds_write_b16 v2, v1 offset:26400
	v_cvt_pk_bf16_f32 v1, v117, s0
	ds_write_b16 v2, v1 offset:26928
	v_cvt_pk_bf16_f32 v1, v118, s0
	ds_write_b16 v2, v1 offset:27456
	v_cvt_pk_bf16_f32 v1, v119, s0
	ds_write_b16 v2, v1 offset:27984
	v_cvt_pk_bf16_f32 v1, v84, s0
	ds_write_b16 v2, v1 offset:26432
	v_cvt_pk_bf16_f32 v1, v85, s0
	ds_write_b16 v2, v1 offset:26960
	v_cvt_pk_bf16_f32 v1, v86, s0
	ds_write_b16 v2, v1 offset:27488
	v_cvt_pk_bf16_f32 v1, v87, s0
	ds_write_b16 v2, v1 offset:28016
	v_cvt_pk_bf16_f32 v1, v52, s0
	ds_write_b16 v2, v1 offset:26464
	v_cvt_pk_bf16_f32 v1, v53, s0
	ds_write_b16 v2, v1 offset:26992
	v_cvt_pk_bf16_f32 v1, v54, s0
	ds_write_b16 v2, v1 offset:27520
	v_cvt_pk_bf16_f32 v1, v55, s0
	ds_write_b16 v2, v1 offset:28048
	v_cvt_pk_bf16_f32 v1, v20, s0
	ds_write_b16 v2, v1 offset:26496
	v_cvt_pk_bf16_f32 v1, v21, s0
	ds_write_b16 v2, v1 offset:27024
	v_cvt_pk_bf16_f32 v1, v22, s0
	ds_write_b16 v2, v1 offset:27552
	v_cvt_pk_bf16_f32 v1, v23, s0
	ds_write_b16 v2, v1 offset:28080
	v_cvt_pk_bf16_f32 v1, v112, s0
; DI void img_barrier() { asm volatile("s_waitcnt lgkmcnt(0)" ::: "memory"); __builtin_amdgcn_s_barrier(); }
; template <bool ROPE>
; DI void img_put_bf16(const f32x4 (&acc)[8][4], char* smem, int rowoff, float scale, int prow0, const float* cosT) {
;     ...
;   u16* img = (u16*)smem + (wr * 128 + fq * 4 + rowoff) * IMG_LD + wc * 64 + fr;
; #pragma unroll
;   for (int m = 0; m < 8; ++m) {
;     float cs4[4] = {0.f, 0.f, 0.f, 0.f}, sn4[4] = {0.f, 0.f, 0.f, 0.f};
;     if (ROPE) {
; #pragma unroll
;       for (int j = 0; j < 4; ++j) { const int pos = prow0 + wr * 128 + m * 16 + fq * 4 + j; cs4[j] = cosT[pos * 8 + (fr & 7)]; sn4[j] = cosT[8192 * 8 + pos * 8 + (fr & 7)]; }
;     }
; #pragma unroll
;     for (int n = 0; n < 4; ++n)
; #pragma unroll
;       for (int j = 0; j < 4; ++j) img[(m * 16 + j) * IMG_LD + n * 16] = f2bf(epi_val<ROPE>(acc, m, n, j, cs4, sn4, fr) * scale);
;   }
; DI void ffup_tile(const Params& p, int l, int mt, int nt, char* smem) {
;     ...
;     img_barrier();
	ds_write_b16 v2, v1 offset:34848
	v_cvt_pk_bf16_f32 v1, v113, s0
	ds_write_b16 v2, v1 offset:35376
	v_cvt_pk_bf16_f32 v1, v114, s0
	ds_write_b16 v2, v1 offset:35904
	v_cvt_pk_bf16_f32 v1, v115, s0
	ds_write_b16 v2, v1 offset:36432
	v_cvt_pk_bf16_f32 v1, v80, s0
	ds_write_b16 v2, v1 offset:34880
	v_cvt_pk_bf16_f32 v1, v81, s0
	ds_write_b16 v2, v1 offset:35408
	v_cvt_pk_bf16_f32 v1, v82, s0
	ds_write_b16 v2, v1 offset:35936
	v_cvt_pk_bf16_f32 v1, v83, s0
	ds_write_b16 v2, v1 offset:36464
	v_cvt_pk_bf16_f32 v1, v48, s0
	ds_write_b16 v2, v1 offset:34912
	v_cvt_pk_bf16_f32 v1, v49, s0
	ds_write_b16 v2, v1 offset:35440
	v_cvt_pk_bf16_f32 v1, v50, s0
	ds_write_b16 v2, v1 offset:35968
	v_cvt_pk_bf16_f32 v1, v51, s0
	ds_write_b16 v2, v1 offset:36496
	v_cvt_pk_bf16_f32 v1, v16, s0
	ds_write_b16 v2, v1 offset:34944
	v_cvt_pk_bf16_f32 v1, v17, s0
	ds_write_b16 v2, v1 offset:35472
	v_cvt_pk_bf16_f32 v1, v18, s0
	ds_write_b16 v2, v1 offset:36000
	v_cvt_pk_bf16_f32 v1, v19, s0
	ds_write_b16 v2, v1 offset:36528
	v_cvt_pk_bf16_f32 v1, v108, s0
	ds_write_b16 v2, v1 offset:43296
	v_cvt_pk_bf16_f32 v1, v109, s0
	ds_write_b16 v2, v1 offset:43824
	v_cvt_pk_bf16_f32 v1, v110, s0
	ds_write_b16 v2, v1 offset:44352
	v_cvt_pk_bf16_f32 v1, v111, s0
	ds_write_b16 v2, v1 offset:44880
	v_cvt_pk_bf16_f32 v1, v76, s0
	ds_write_b16 v2, v1 offset:43328
	v_cvt_pk_bf16_f32 v1, v77, s0
	ds_write_b16 v2, v1 offset:43856
	v_cvt_pk_bf16_f32 v1, v78, s0
	ds_write_b16 v2, v1 offset:44384
	v_cvt_pk_bf16_f32 v1, v79, s0
	ds_write_b16 v2, v1 offset:44912
	v_cvt_pk_bf16_f32 v1, v44, s0
	ds_write_b16 v2, v1 offset:43360
	v_cvt_pk_bf16_f32 v1, v45, s0
	ds_write_b16 v2, v1 offset:43888
	v_cvt_pk_bf16_f32 v1, v46, s0
	ds_write_b16 v2, v1 offset:44416
	v_cvt_pk_bf16_f32 v1, v47, s0
	ds_write_b16 v2, v1 offset:44944
	v_cvt_pk_bf16_f32 v1, v12, s0
	ds_write_b16 v2, v1 offset:43392
	v_cvt_pk_bf16_f32 v1, v13, s0
	ds_write_b16 v2, v1 offset:43920
	v_cvt_pk_bf16_f32 v1, v14, s0
	ds_write_b16 v2, v1 offset:44448
	v_cvt_pk_bf16_f32 v1, v15, s0
	ds_write_b16 v2, v1 offset:44976
	v_cvt_pk_bf16_f32 v1, v104, s0
	ds_write_b16 v2, v1 offset:51744
	v_cvt_pk_bf16_f32 v1, v105, s0
	ds_write_b16 v2, v1 offset:52272
	v_cvt_pk_bf16_f32 v1, v106, s0
	ds_write_b16 v2, v1 offset:52800
	v_cvt_pk_bf16_f32 v1, v107, s0
	ds_write_b16 v2, v1 offset:53328
	v_cvt_pk_bf16_f32 v1, v72, s0
	ds_write_b16 v2, v1 offset:51776
	v_cvt_pk_bf16_f32 v1, v73, s0
	ds_write_b16 v2, v1 offset:52304
	v_cvt_pk_bf16_f32 v1, v74, s0
	ds_write_b16 v2, v1 offset:52832
	v_cvt_pk_bf16_f32 v1, v75, s0
	ds_write_b16 v2, v1 offset:53360
	v_cvt_pk_bf16_f32 v1, v40, s0
	ds_write_b16 v2, v1 offset:51808
	v_cvt_pk_bf16_f32 v1, v41, s0
	ds_write_b16 v2, v1 offset:52336
	v_cvt_pk_bf16_f32 v1, v42, s0
	ds_write_b16 v2, v1 offset:52864
	v_cvt_pk_bf16_f32 v1, v43, s0
	ds_write_b16 v2, v1 offset:53392
	v_cvt_pk_bf16_f32 v1, v8, s0
	ds_write_b16 v2, v1 offset:51840
	v_cvt_pk_bf16_f32 v1, v9, s0
	ds_write_b16 v2, v1 offset:52368
	v_cvt_pk_bf16_f32 v1, v10, s0
	ds_write_b16 v2, v1 offset:52896
	v_cvt_pk_bf16_f32 v1, v11, s0
	ds_write_b16 v2, v1 offset:53424
	v_cvt_pk_bf16_f32 v1, v100, s0
	ds_write_b16 v2, v1 offset:60192
	v_cvt_pk_bf16_f32 v1, v101, s0
	ds_write_b16 v2, v1 offset:60720
	v_cvt_pk_bf16_f32 v1, v102, s0
	v_cvt_pk_bf16_f32 v7, v128, s0
	ds_write_b16 v2, v1 offset:61248
	v_cvt_pk_bf16_f32 v1, v103, s0
	ds_write_b16 v2, v7 offset:1056
	v_cvt_pk_bf16_f32 v7, v129, s0
	ds_write_b16 v2, v1 offset:61776
	v_cvt_pk_bf16_f32 v1, v68, s0
	ds_write_b16 v2, v7 offset:1584
	v_cvt_pk_bf16_f32 v7, v130, s0
	ds_write_b16 v2, v1 offset:60224
	v_cvt_pk_bf16_f32 v1, v69, s0
	ds_write_b16 v2, v7 offset:2112
	v_cvt_pk_bf16_f32 v7, v131, s0
	ds_write_b16 v2, v1 offset:60752
	v_cvt_pk_bf16_f32 v1, v70, s0
	ds_write_b16 v2, v7 offset:2640
	v_cvt_pk_bf16_f32 v7, v96, s0
	ds_write_b16 v2, v1 offset:61280
	v_cvt_pk_bf16_f32 v1, v71, s0
	ds_write_b16 v2, v7 offset:1088
	v_cvt_pk_bf16_f32 v7, v97, s0
	ds_write_b16 v2, v1 offset:61808
	v_cvt_pk_bf16_f32 v1, v36, s0
	ds_write_b16 v2, v7 offset:1616
	v_cvt_pk_bf16_f32 v7, v98, s0
	ds_write_b16 v2, v1 offset:60256
	v_cvt_pk_bf16_f32 v1, v37, s0
	ds_write_b16 v2, v7 offset:2144
	v_cvt_pk_bf16_f32 v7, v99, s0
	ds_write_b16 v2, v1 offset:60784
	v_cvt_pk_bf16_f32 v1, v38, s0
	ds_write_b16 v2, v7 offset:2672
	v_cvt_pk_bf16_f32 v7, v64, s0
	ds_write_b16 v2, v1 offset:61312
	v_cvt_pk_bf16_f32 v1, v39, s0
	ds_write_b16 v2, v7 offset:1120
	v_cvt_pk_bf16_f32 v7, v65, s0
	ds_write_b16 v2, v1 offset:61840
	v_cvt_pk_bf16_f32 v1, v4, s0
	ds_write_b16 v2, v7 offset:1648
	v_cvt_pk_bf16_f32 v7, v66, s0
	ds_write_b16 v2, v1 offset:60288
	v_cvt_pk_bf16_f32 v1, v5, s0
	ds_write_b16 v2, v7 offset:2176
	v_cvt_pk_bf16_f32 v7, v67, s0
	ds_write_b16 v2, v1 offset:60816
	v_cvt_pk_bf16_f32 v1, v6, s0
	v_cvt_pk_bf16_f32 v0, v0, s0
	ds_write_b16 v2, v7 offset:2704
	ds_write_b16 v2, v1 offset:61344
	ds_write_b16 v2, v0 offset:61872
	v_mov_b32_e32 v1, v184
	s_waitcnt lgkmcnt(0)
	s_barrier
; DI int TID512() { int t = threadIdx.x; asm volatile("" : "+v"(t)); return t; }
; DI void img_store_bf16(u16* dst, int ld, const char* smem, int rowoff) {
;   const int tid = TID512();
; #pragma unroll
;   for (int q = 0; q < 16; ++q) {
;     const int slot = tid + q * 512, row = slot >> 5, c16 = slot & 31;
;     *(u32x4*)(dst + (size_t)row * ld + c16 * 8) = *(const u32x4*)(smem + (row + rowoff) * (IMG_LD * 2) + c16 * 16);
;   }
; }
; DI void ffup_tile(const Params& p, int l, int mt, int nt, char* smem) {
;     ...
;     img_store_bf16((u16*)(p.ws + O_FF) + (size_t)row0 * DFF + col0, DFF, smem, 2);
	s_addc_u32 s5, s77, s39
	s_add_u32 s4, s4, s48
	v_lshlrev_b32_e32 v0, 4, v1
	v_and_b32_e32 v172, 0x1f0, v0
	s_addc_u32 s5, s5, s49
	v_add_u32_e32 v0, 16, v172
	v_ashrrev_i32_e32 v2, 5, v1
	v_lshl_add_u64 v[8:9], s[4:5], 0, v[172:173]
	v_mad_u64_u32 v[4:5], s[4:5], v2, s3, v[0:1]
	ds_read_b128 v[4:7], v4 offset:1056
	v_mad_i64_i32 v[10:11], s[4:5], v2, s96, v[8:9]
	v_add_u32_e32 v2, 0x200, v1
	v_ashrrev_i32_e32 v2, 5, v2
	s_waitcnt lgkmcnt(0)
	global_store_dwordx4 v[10:11], v[4:7], off
	v_mad_i64_i32 v[10:11], s[4:5], v2, s96, v[8:9]
	s_nop 0
	v_mad_u64_u32 v[4:5], s[4:5], v2, s3, v[0:1]
	ds_read_b128 v[4:7], v4 offset:1056
	v_add_u32_e32 v2, 0x400, v1
	v_ashrrev_i32_e32 v2, 5, v2
	s_waitcnt lgkmcnt(0)
	global_store_dwordx4 v[10:11], v[4:7], off
	s_nop 1
	v_mad_u64_u32 v[4:5], s[4:5], v2, s3, v[0:1]
	ds_read_b128 v[4:7], v4 offset:1056
	v_mad_i64_i32 v[10:11], s[4:5], v2, s96, v[8:9]
	v_add_u32_e32 v2, 0x600, v1
	v_ashrrev_i32_e32 v2, 5, v2
	s_waitcnt lgkmcnt(0)
	global_store_dwordx4 v[10:11], v[4:7], off
	v_mad_i64_i32 v[10:11], s[4:5], v2, s96, v[8:9]
	s_nop 0
	v_mad_u64_u32 v[4:5], s[4:5], v2, s3, v[0:1]
	ds_read_b128 v[4:7], v4 offset:1056
	v_add_u32_e32 v2, 0x800, v1
	v_ashrrev_i32_e32 v2, 5, v2
	s_waitcnt lgkmcnt(0)
	global_store_dwordx4 v[10:11], v[4:7], off
	s_nop 1
	v_mad_u64_u32 v[4:5], s[4:5], v2, s3, v[0:1]
	ds_read_b128 v[4:7], v4 offset:1056
	v_mad_i64_i32 v[10:11], s[4:5], v2, s96, v[8:9]
	v_add_u32_e32 v2, 0xa00, v1
	v_ashrrev_i32_e32 v2, 5, v2
	s_waitcnt lgkmcnt(0)
	global_store_dwordx4 v[10:11], v[4:7], off
	v_mad_i64_i32 v[10:11], s[4:5], v2, s96, v[8:9]
	s_nop 0
	v_mad_u64_u32 v[4:5], s[4:5], v2, s3, v[0:1]
	ds_read_b128 v[4:7], v4 offset:1056
	v_add_u32_e32 v2, 0xc00, v1
	v_ashrrev_i32_e32 v2, 5, v2
	s_waitcnt lgkmcnt(0)
	global_store_dwordx4 v[10:11], v[4:7], off
	s_nop 1
	v_mad_u64_u32 v[4:5], s[4:5], v2, s3, v[0:1]
	ds_read_b128 v[4:7], v4 offset:1056
	v_mad_i64_i32 v[10:11], s[4:5], v2, s96, v[8:9]
	v_add_u32_e32 v2, 0xe00, v1
	v_ashrrev_i32_e32 v2, 5, v2
	s_waitcnt lgkmcnt(0)
	global_store_dwordx4 v[10:11], v[4:7], off
	v_mad_i64_i32 v[10:11], s[4:5], v2, s96, v[8:9]
	s_nop 0
	v_mad_u64_u32 v[4:5], s[4:5], v2, s3, v[0:1]
	ds_read_b128 v[4:7], v4 offset:1056
	v_add_u32_e32 v2, 0x1000, v1
	v_ashrrev_i32_e32 v2, 5, v2
	s_waitcnt lgkmcnt(0)
	global_store_dwordx4 v[10:11], v[4:7], off
	s_nop 1
	v_mad_u64_u32 v[4:5], s[4:5], v2, s3, v[0:1]
	ds_read_b128 v[4:7], v4 offset:1056
	v_mad_i64_i32 v[10:11], s[4:5], v2, s96, v[8:9]
	v_add_u32_e32 v2, 0x1200, v1
	v_ashrrev_i32_e32 v2, 5, v2
	s_waitcnt lgkmcnt(0)
	global_store_dwordx4 v[10:11], v[4:7], off
	v_mad_i64_i32 v[10:11], s[4:5], v2, s96, v[8:9]
	s_nop 0
	v_mad_u64_u32 v[4:5], s[4:5], v2, s3, v[0:1]
	ds_read_b128 v[4:7], v4 offset:1056
	v_add_u32_e32 v2, 0x1400, v1
	v_ashrrev_i32_e32 v2, 5, v2
	s_waitcnt lgkmcnt(0)
	global_store_dwordx4 v[10:11], v[4:7], off
	s_nop 1
	v_mad_u64_u32 v[4:5], s[4:5], v2, s3, v[0:1]
	ds_read_b128 v[4:7], v4 offset:1056
	v_mad_i64_i32 v[10:11], s[4:5], v2, s96, v[8:9]
	v_add_u32_e32 v2, 0x1600, v1
	v_ashrrev_i32_e32 v2, 5, v2
	s_waitcnt lgkmcnt(0)
	global_store_dwordx4 v[10:11], v[4:7], off
	v_mad_i64_i32 v[10:11], s[4:5], v2, s96, v[8:9]
	s_nop 0
	v_mad_u64_u32 v[4:5], s[4:5], v2, s3, v[0:1]
	ds_read_b128 v[4:7], v4 offset:1056
	v_add_u32_e32 v2, 0x1800, v1
	v_ashrrev_i32_e32 v2, 5, v2
	s_waitcnt lgkmcnt(0)
	global_store_dwordx4 v[10:11], v[4:7], off
	s_nop 1
	v_mad_u64_u32 v[4:5], s[4:5], v2, s3, v[0:1]
	ds_read_b128 v[4:7], v4 offset:1056
	v_mad_i64_i32 v[10:11], s[4:5], v2, s96, v[8:9]
	v_add_u32_e32 v2, 0x1a00, v1
	v_ashrrev_i32_e32 v2, 5, v2
	s_waitcnt lgkmcnt(0)
	global_store_dwordx4 v[10:11], v[4:7], off
	v_mad_i64_i32 v[10:11], s[4:5], v2, s96, v[8:9]
	s_nop 0
	v_mad_u64_u32 v[4:5], s[4:5], v2, s3, v[0:1]
	ds_read_b128 v[4:7], v4 offset:1056
	v_add_u32_e32 v2, 0x1c00, v1
	v_ashrrev_i32_e32 v2, 5, v2
	s_waitcnt lgkmcnt(0)
	global_store_dwordx4 v[10:11], v[4:7], off
	s_nop 1
	v_mad_u64_u32 v[4:5], s[4:5], v2, s3, v[0:1]
	ds_read_b128 v[4:7], v4 offset:1056
	v_add_u32_e32 v1, 0x1e00, v1
	v_mad_i64_i32 v[10:11], s[4:5], v2, s96, v[8:9]
	v_ashrrev_i32_e32 v2, 5, v1
	v_mad_u64_u32 v[0:1], s[4:5], v2, s3, v[0:1]
	s_waitcnt lgkmcnt(0)
	global_store_dwordx4 v[10:11], v[4:7], off
	ds_read_b128 v[4:7], v0 offset:1056
	v_mad_i64_i32 v[0:1], s[4:5], v2, s96, v[8:9]
	s_waitcnt lgkmcnt(0)
	global_store_dwordx4 v[0:1], v[4:7], off
